# v7 plus: GEMM K-loops: hipcc's 64 per-segment s_setprio flips removed, one static s_setprio 1 for waves 4-7 per GEMM phase (reset at phase end)
# speedup vs baseline: 1.0077x; 1.0077x over previous
; #define PG8_STAGE(bufoff, gbase, voff) do { _Pragma("unroll") for (int _i = 0; _i < 2; ++_i) \
;         __builtin_amdgcn_global_load_lds((const unsigned*)((const char*)(gbase) + (voff)[_i]), (LAS unsigned*)(lds + (bufoff) + ldsw + _i * 8192), 16, 0, 0); } while (0)
; #define PG8_WAIT_V(n) asm volatile("s_waitcnt vmcnt(" #n ")" ::: "memory")
; #define PG8_BAR __builtin_amdgcn_s_barrier()
; template <class Epi, class Sched>
; __device__ __forceinline__ void gemm_phase(LAS unsigned char* lds, const Gemm g, const Sched& S, const Epi& E) {
;     ...
;     const int wid = __builtin_amdgcn_readfirstlane(tid >> 6), lane = tid & 63, wr = wid >> 2, wc = wid & 3, fr = lane & 15, fq = lane >> 4;
;     const int K = g.K;
;     unsigned voffA[2], voffB[2];
; #pragma unroll
;     for (int i = 0; i < 2; ++i) { int R, C; stage_rc(tid * 16 + i * 8192, R, C); const int Rb = Epi::PERM ? ((R & ~31) + perm32(R & 31)) : R;
;         voffA[i] = (unsigned)(R * K + C) * 2u; voffB[i] = (unsigned)(Rb * K + C) * 2u; }
;     const size_t kstep = (size_t)(BK * 2);
;     const size_t hstep = (size_t)HALF * K * 2;
;     const size_t tstep = 2 * hstep;
;     const unsigned ldsw = (unsigned)wid * 1024u;
;     const int aoff = lds_byte(wr * 64 + fr, fq * 8), boff = lds_byte(wc * 32 + fr, fq * 8);
;     ...
;     Unit cur, nxt; int ui = 0;
;     if (!S.next(0, cur)) return;
;     f32x4 acc[2][2][4][2];
; #pragma unroll
;     for (int a = 0; a < 2; ++a)
; #pragma unroll
;         for (int b = 0; b < 2; ++b)
; #pragma unroll
;             for (int m = 0; m < 4; ++m)
; #pragma unroll
;                 for (int n = 0; n < 2; ++n) acc[a][b][m][n] = (f32x4){0.f, 0.f, 0.f, 0.f};
;     bf16x8 At[4][2], B0[2][2], B1[2][2];
;     const char* cA = (const char*)g.A + (size_t)cur.pm * tstep + (size_t)cur.kt0 * kstep; const char* cB = (const char*)g.Bt + (size_t)cur.pn * tstep + (size_t)cur.kt0 * kstep;
;     PG8_STAGE(PG8_SB(0, 0), cB, voffB); PG8_STAGE(PG8_SA(0, 0), cA, voffA); PG8_STAGE(PG8_SB(0, 1), cB + hstep, voffB); PG8_STAGE(PG8_SA(0, 1), cA + hstep, voffA);
;     if (wr == 1) PG8_BAR;
;     PG8_WAIT_V(4); PG8_BAR;
;     PG8_STAGE(PG8_SB(1, 0), cB + kstep, voffB); PG8_STAGE(PG8_SA(1, 0), cA + kstep, voffA); PG8_STAGE(PG8_SB(1, 1), cB + hstep + kstep, voffB);
;     PG8_WAIT_V(6); PG8_BAR;
.LBB0_110:
	v_readlane_b32 s2, v253, 14
	s_mulk_i32 s2, 0x2100
	s_add_i32 s26, s2, 0
	s_and_b64 vcc, exec, s[0:1]
	s_cbranch_vccz .LBB0_134
	v_readlane_b32 s0, v253, 27
	s_cmp_gt_i32 s0, 1
	s_cbranch_scc0 .LBB0_135
	s_cmp_gt_i32 s0, 2
	s_mov_b64 s[10:11], 0
	s_cbranch_scc0 .LBB0_136
	s_cmp_gt_i32 s0, 3
	s_cbranch_scc0 .LBB0_149
	v_readlane_b32 s0, v251, 11
	v_mov_b32_e32 v14, v178
	v_readlane_b32 s1, v251, 12
	s_andn2_b64 vcc, exec, s[0:1]
	v_readfirstlane_b32 s24, v14
	s_cbranch_vccnz .LBB0_130
	v_lshlrev_b32_e32 v0, 4, v14
	v_add_u32_e32 v1, 0x2000, v0
	v_ashrrev_i32_e32 v2, 31, v1
	v_lshrrev_b32_e32 v2, 22, v2
	v_add_u32_e32 v2, v1, v2
	v_ashrrev_i32_e32 v8, 10, v2
	v_mul_i32_i24_e32 v2, 0x400, v8
	v_sub_u32_e32 v1, v1, v2
	v_lshrrev_b32_e32 v2, 4, v1
	v_bitop3_b32 v1, v2, v1, 32 bitop3:0x6c
	v_ashrrev_i32_e32 v2, 31, v1
	v_lshrrev_b32_e32 v2, 26, v2
	v_add_u32_e32 v2, v1, v2
	v_lshlrev_b32_e32 v3, 3, v8
	v_ashrrev_i32_e32 v9, 6, v2
	v_and_b32_e32 v3, -16, v3
	v_add_u32_e32 v3, v9, v3
	v_and_b32_e32 v4, 3, v9
	s_mov_b32 s2, 0xfffe0
	v_lshrrev_b32_e32 v5, 2, v3
	v_lshlrev_b32_e32 v6, 1, v3
	v_and_b32_e32 v2, 0xc0, v2
	v_and_or_b32 v4, v3, s2, v4
	v_and_b32_e32 v5, 4, v5
	v_and_b32_e32 v6, 24, v6
	v_sub_u32_e32 v1, v1, v2
	v_or3_b32 v4, v4, v5, v6
	v_lshlrev_b32_e32 v5, 5, v8
	v_ashrrev_i16_sdwa v1, v183, sext(v1) dst_sel:DWORD dst_unused:UNUSED_PAD src0_sel:DWORD src1_sel:BYTE_0
	v_and_b32_e32 v5, 32, v5
	v_bfe_i32 v10, v1, 0, 16
	v_add_lshl_u32 v1, v5, v10, 1
	v_lshl_add_u32 v128, v4, 12, v1
	v_lshl_add_u32 v130, v3, 12, v1
	v_bfe_i32 v1, v14, 27, 1
	v_lshrrev_b32_e32 v1, 22, v1
	v_add_u32_e32 v1, v0, v1
	v_and_b32_e32 v1, 0xfffffc00, v1
	v_sub_u32_e32 v0, v0, v1
	v_lshrrev_b32_e32 v1, 4, v0
	v_ashrrev_i32_e32 v2, 31, v14
	v_bitop3_b32 v0, v1, v0, 32 bitop3:0x6c
	v_lshrrev_b32_e32 v2, 26, v2
	v_ashrrev_i32_e32 v1, 31, v0
	v_add_u32_e32 v2, v14, v2
	v_lshrrev_b32_e32 v1, 26, v1
	v_ashrrev_i32_e32 v12, 6, v2
	v_add_u32_e32 v1, v0, v1
	v_lshlrev_b32_e32 v2, 3, v12
	v_ashrrev_i32_e32 v11, 6, v1
	v_and_b32_e32 v2, -16, v2
	v_add_u32_e32 v2, v11, v2
	s_add_u32 s25, s62, 0x8400000
	v_and_b32_e32 v3, 3, v11
	v_lshrrev_b32_e32 v4, 2, v2
	v_lshlrev_b32_e32 v5, 1, v2
	v_and_b32_e32 v1, 0xc0, v1
	s_addc_u32 s27, s63, 0
	s_ashr_i32 s0, s24, 6
	v_and_or_b32 v3, v2, s2, v3
	v_and_b32_e32 v4, 4, v4
	v_and_b32_e32 v5, 24, v5
	v_sub_u32_e32 v0, v0, v1
	s_ashr_i32 s1, s24, 8
	s_lshl_b32 s29, s0, 10
	v_or3_b32 v3, v3, v4, v5
	v_lshlrev_b32_e32 v4, 5, v12
	v_ashrrev_i16_sdwa v0, v183, sext(v0) dst_sel:DWORD dst_unused:UNUSED_PAD src0_sel:DWORD src1_sel:BYTE_0
	v_readlane_b32 s2, v252, 36
	v_and_b32_e32 v4, 32, v4
	v_bfe_i32 v13, v0, 0, 16
	v_readlane_b32 s3, v252, 37
	s_add_u32 s20, s25, s2
	v_add_lshl_u32 v0, v4, v13, 1
	s_addc_u32 s21, s27, s3
	s_add_i32 s30, s29, 0
	v_lshl_add_u32 v148, v3, 12, v0
	s_add_i32 m0, s30, 0x10000
	v_readlane_b32 s2, v252, 40
	global_load_lds_dwordx4 v148, s[20:21]
	s_add_i32 m0, s30, 0x12000
	v_readlane_b32 s4, v253, 15
	v_readlane_b32 s3, v252, 41
	s_add_u32 s16, s4, s2
	v_readlane_b32 s2, v253, 16
	v_lshl_add_u32 v132, v2, 12, v0
	global_load_lds_dwordx4 v128, s[20:21]
	s_addc_u32 s17, s2, s3
	s_mov_b32 m0, s30
	s_add_i32 s31, s30, 0x2000
	global_load_lds_dwordx4 v132, s[16:17]
	s_mov_b32 m0, s31
	s_add_u32 s2, s20, 0x80000
	global_load_lds_dwordx4 v130, s[16:17]
	s_addc_u32 s3, s21, 0
	s_add_i32 m0, s30, 0x14000
	v_mov_b32_e32 v129, v149
	global_load_lds_dwordx4 v148, s[2:3]
	s_add_i32 m0, s30, 0x16000
	v_mov_b32_e32 v133, v149
	global_load_lds_dwordx4 v128, s[2:3]
	s_add_u32 s2, s16, 0x80000
	s_addc_u32 s3, s17, 0
	s_add_i32 s33, s30, 0x4000
	s_mov_b32 m0, s33
	s_add_i32 s34, s30, 0x6000
	global_load_lds_dwordx4 v132, s[2:3]
	s_mov_b32 m0, s34
	v_mov_b32_e32 v131, v149
	global_load_lds_dwordx4 v130, s[2:3]
	v_lshl_add_u64 v[6:7], s[20:21], 0, v[148:149]
	v_lshl_add_u64 v[4:5], s[20:21], 0, v[128:129]
	v_lshl_add_u64 v[2:3], s[16:17], 0, v[132:133]
	s_cmp_lg_u32 s1, 1
	v_lshl_add_u64 v[0:1], s[16:17], 0, v[130:131]
	s_cbranch_scc1 .LBB0_117
	s_barrier
	s_setprio 1

; #define PG8_STAGE(bufoff, gbase, voff) do { _Pragma("unroll") for (int _i = 0; _i < 2; ++_i) \
;         __builtin_amdgcn_global_load_lds((const unsigned*)((const char*)(gbase) + (voff)[_i]), (LAS unsigned*)(lds + (bufoff) + ldsw + _i * 8192), 16, 0, 0); } while (0)
; #define PG8_LDA(dst, b, h) do { _Pragma("unroll") for (int m = 0; m < 4; ++m) _Pragma("unroll") for (int k = 0; k < 2; ++k) dst[m][k] = *(const LAS bf16x8*)(lds + PG8_SA(b, h) + aoff + m * 2048 + k * 1024); } while (0)
; #define PG8_LDB(dst, b, h) do { _Pragma("unroll") for (int n = 0; n < 2; ++n) _Pragma("unroll") for (int k = 0; k < 2; ++k) dst[n][k] = *(const LAS bf16x8*)(lds + PG8_SB(b, h) + boff + n * 2048 + k * 1024); } while (0)
; #define PG8_MMA(ai, bj, At, Bt) do { __builtin_amdgcn_s_setprio(1); _Pragma("unroll") for (int m = 0; m < 4; ++m) _Pragma("unroll") for (int n = 0; n < 2; ++n) _Pragma("unroll") for (int k = 0; k < 2; ++k) \
;         acc[ai][bj][m][n] = __builtin_amdgcn_mfma_f32_16x16x32_bf16(Bt[n][k], At[m][k], acc[ai][bj][m][n], 0, 0, 0); __builtin_amdgcn_s_setprio(0); } while (0)
; #define PG8_WAIT_L(n) asm volatile("s_waitcnt lgkmcnt(" #n ")" ::: "memory")
; #define PG8_BAR __builtin_amdgcn_s_barrier()
; #define PG8_SCHED __builtin_amdgcn_sched_barrier(0)
; template <class Epi, class Sched>
; __device__ __forceinline__ void gemm_phase(LAS unsigned char* lds, const Gemm g, const Sched& S, const Epi& E) {
;     ...
;             PG8_LDB(B0, 0, 0); PG8_SCHED; PG8_LDA(At, 0, 0); PG8_STAGE(PG8_SA(1, 1), a1 + hstep, voffA);
;             PG8_WAIT_L(8); PG8_BAR; PG8_WAIT_L(0); PG8_MMA(0, 0, At, B0); PG8_BAR; PG8_SCHED;
;             PG8_LDB(B1, 0, 1); PG8_STAGE(PG8_SB(0, 0), b2, voffB);
;             PG8_BAR; PG8_WAIT_L(0); PG8_MMA(0, 1, At, B1); PG8_BAR;
;             PG8_LDA(At, 0, 1); PG8_STAGE(PG8_SA(0, 0), a2, voffA);
;             PG8_BAR; PG8_WAIT_L(0); PG8_MMA(1, 0, At, B0); PG8_BAR; PG8_SCHED;
.LBB0_125:
	s_add_u32 s20, s16, 0xfff80080
	s_addc_u32 s21, s17, -1
	s_add_i32 s45, 0, 0x10000
	v_add_u32_e32 v146, s45, v143
	ds_read_b128 v[138:141], v146
	ds_read_b128 v[160:163], v146 offset:1024
	ds_read_b128 v[164:167], v146 offset:2048
	ds_read_b128 v[168:171], v146 offset:3072
	s_cmp_eq_u32 s44, 28
	s_cselect_b32 s23, s7, s21
	s_cselect_b32 s22, s40, s20
	s_cselect_b32 s21, s5, s43
	s_cselect_b32 s20, s41, s42
	v_lshl_add_u64 v[146:147], s[16:17], 0, v[134:135]
	s_add_i32 m0, s30, 0xc000
	ds_read_b128 v[172:175], v145
	ds_read_b128 v[200:203], v145 offset:1024
	ds_read_b128 v[204:207], v145 offset:2048
	ds_read_b128 v[208:211], v145 offset:3072
	ds_read_b128 v[212:215], v145 offset:4096
	ds_read_b128 v[216:219], v145 offset:5120
	ds_read_b128 v[220:223], v145 offset:6144
	ds_read_b128 v[224:227], v145 offset:7168
	global_load_lds_dwordx4 v[146:147], off
	v_lshl_add_u64 v[146:147], s[16:17], 0, v[136:137]
	s_add_i32 m0, s30, 0xe000
	s_nop 0
	global_load_lds_dwordx4 v[146:147], off
	s_waitcnt lgkmcnt(8)
	s_barrier
	s_waitcnt lgkmcnt(0)
	s_waitcnt lgkmcnt(0)
	v_mfma_f32_16x16x32_bf16 v[124:127], v[138:141], v[172:175], v[124:127]
	v_mfma_f32_16x16x32_bf16 v[120:123], v[164:167], v[172:175], v[120:123]
	v_mfma_f32_16x16x32_bf16 v[116:119], v[138:141], v[204:207], v[116:119]
	v_mfma_f32_16x16x32_bf16 v[108:111], v[164:167], v[204:207], v[108:111]
	v_mfma_f32_16x16x32_bf16 v[100:103], v[138:141], v[212:215], v[100:103]
	v_mfma_f32_16x16x32_bf16 v[92:95], v[164:167], v[212:215], v[92:95]
	v_mfma_f32_16x16x32_bf16 v[84:87], v[138:141], v[220:223], v[84:87]
	v_mfma_f32_16x16x32_bf16 v[76:79], v[164:167], v[220:223], v[76:79]
	v_mfma_f32_16x16x32_bf16 v[124:127], v[160:163], v[200:203], v[124:127]
	v_mfma_f32_16x16x32_bf16 v[120:123], v[168:171], v[200:203], v[120:123]
	v_mfma_f32_16x16x32_bf16 v[116:119], v[160:163], v[208:211], v[116:119]
	v_mfma_f32_16x16x32_bf16 v[108:111], v[168:171], v[208:211], v[108:111]
	v_mfma_f32_16x16x32_bf16 v[100:103], v[160:163], v[216:219], v[100:103]
	v_mfma_f32_16x16x32_bf16 v[92:95], v[168:171], v[216:219], v[92:95]
	v_mfma_f32_16x16x32_bf16 v[84:87], v[160:163], v[224:227], v[84:87]
	v_mfma_f32_16x16x32_bf16 v[76:79], v[168:171], v[224:227], v[76:79]
	s_barrier
	s_add_i32 s48, 0, 0x14000
	v_add_u32_e32 v146, s48, v143
	s_add_i32 s45, s45, s29
	ds_read_b128 v[228:231], v146
	ds_read_b128 v[232:235], v146 offset:1024
	ds_read_b128 v[236:239], v146 offset:2048
	ds_read_b128 v[240:243], v146 offset:3072
	v_lshl_add_u64 v[146:147], s[20:21], 0, v[148:149]
	s_mov_b32 m0, s45
	v_lshl_add_u64 v[176:177], s[20:21], 0, v[128:129]
	global_load_lds_dwordx4 v[146:147], off
	s_add_i32 m0, s45, 0x2000
	s_nop 0
	global_load_lds_dwordx4 v[176:177], off
	s_barrier
	s_waitcnt lgkmcnt(0)
	s_waitcnt lgkmcnt(0)
	v_mfma_f32_16x16x32_bf16 v[112:115], v[228:231], v[172:175], v[112:115]
	v_mfma_f32_16x16x32_bf16 v[104:107], v[236:239], v[172:175], v[104:107]
	v_mfma_f32_16x16x32_bf16 v[96:99], v[228:231], v[204:207], v[96:99]
	v_mfma_f32_16x16x32_bf16 v[88:91], v[236:239], v[204:207], v[88:91]
	v_mfma_f32_16x16x32_bf16 v[80:83], v[228:231], v[212:215], v[80:83]
	v_mfma_f32_16x16x32_bf16 v[72:75], v[236:239], v[212:215], v[72:75]
	v_mfma_f32_16x16x32_bf16 v[68:71], v[228:231], v[220:223], v[68:71]
	v_mfma_f32_16x16x32_bf16 v[64:67], v[236:239], v[220:223], v[64:67]
	v_mfma_f32_16x16x32_bf16 v[112:115], v[232:235], v[200:203], v[112:115]
	v_mfma_f32_16x16x32_bf16 v[104:107], v[240:243], v[200:203], v[104:107]
	v_mfma_f32_16x16x32_bf16 v[96:99], v[232:235], v[208:211], v[96:99]
	v_mfma_f32_16x16x32_bf16 v[88:91], v[240:243], v[208:211], v[88:91]
	v_mfma_f32_16x16x32_bf16 v[80:83], v[232:235], v[216:219], v[80:83]
	v_mfma_f32_16x16x32_bf16 v[72:75], v[240:243], v[216:219], v[72:75]
	v_mfma_f32_16x16x32_bf16 v[68:71], v[232:235], v[224:227], v[68:71]
	v_mfma_f32_16x16x32_bf16 v[64:67], v[240:243], v[224:227], v[64:67]
	s_mov_b32 m0, s30
	v_lshl_add_u64 v[188:189], s[22:23], 0, v[132:133]
	s_barrier
	ds_read_b128 v[172:175], v145 offset:16384
	ds_read_b128 v[200:203], v145 offset:17408
	ds_read_b128 v[204:207], v145 offset:18432
	ds_read_b128 v[208:211], v145 offset:19456
	ds_read_b128 v[212:215], v145 offset:20480
	ds_read_b128 v[216:219], v145 offset:21504
	ds_read_b128 v[220:223], v145 offset:22528
	ds_read_b128 v[224:227], v145 offset:23552
	global_load_lds_dwordx4 v[188:189], off
	v_lshl_add_u64 v[190:191], s[22:23], 0, v[130:131]
	s_mov_b32 m0, s31
	s_nop 0
	global_load_lds_dwordx4 v[190:191], off
	s_barrier
	s_waitcnt lgkmcnt(0)
	s_waitcnt lgkmcnt(0)
	v_mfma_f32_16x16x32_bf16 v[60:63], v[138:141], v[172:175], v[60:63]
	v_mfma_f32_16x16x32_bf16 v[56:59], v[164:167], v[172:175], v[56:59]
	v_mfma_f32_16x16x32_bf16 v[52:55], v[138:141], v[204:207], v[52:55]
	v_mfma_f32_16x16x32_bf16 v[44:47], v[164:167], v[204:207], v[44:47]
	v_mfma_f32_16x16x32_bf16 v[36:39], v[138:141], v[212:215], v[36:39]
	v_mfma_f32_16x16x32_bf16 v[28:31], v[164:167], v[212:215], v[28:31]
	v_mfma_f32_16x16x32_bf16 v[20:23], v[138:141], v[220:223], v[20:23]
	v_mfma_f32_16x16x32_bf16 v[12:15], v[164:167], v[220:223], v[12:15]
	v_mfma_f32_16x16x32_bf16 v[60:63], v[160:163], v[200:203], v[60:63]
	v_mfma_f32_16x16x32_bf16 v[56:59], v[168:171], v[200:203], v[56:59]
	v_mfma_f32_16x16x32_bf16 v[52:55], v[160:163], v[208:211], v[52:55]
	v_mfma_f32_16x16x32_bf16 v[44:47], v[168:171], v[208:211], v[44:47]
	v_mfma_f32_16x16x32_bf16 v[36:39], v[160:163], v[216:219], v[36:39]
	v_mfma_f32_16x16x32_bf16 v[28:31], v[168:171], v[216:219], v[28:31]
	v_mfma_f32_16x16x32_bf16 v[20:23], v[160:163], v[224:227], v[20:23]
	v_mfma_f32_16x16x32_bf16 v[12:15], v[168:171], v[224:227], v[12:15]
	s_barrier
; #define PG8_STAGE(bufoff, gbase, voff) do { _Pragma("unroll") for (int _i = 0; _i < 2; ++_i) \
;         __builtin_amdgcn_global_load_lds((const unsigned*)((const char*)(gbase) + (voff)[_i]), (LAS unsigned*)(lds + (bufoff) + ldsw + _i * 8192), 16, 0, 0); } while (0)
; #define PG8_LDA(dst, b, h) do { _Pragma("unroll") for (int m = 0; m < 4; ++m) _Pragma("unroll") for (int k = 0; k < 2; ++k) dst[m][k] = *(const LAS bf16x8*)(lds + PG8_SA(b, h) + aoff + m * 2048 + k * 1024); } while (0)
; #define PG8_LDB(dst, b, h) do { _Pragma("unroll") for (int n = 0; n < 2; ++n) _Pragma("unroll") for (int k = 0; k < 2; ++k) dst[n][k] = *(const LAS bf16x8*)(lds + PG8_SB(b, h) + boff + n * 2048 + k * 1024); } while (0)
; #define PG8_MMA(ai, bj, At, Bt) do { __builtin_amdgcn_s_setprio(1); _Pragma("unroll") for (int m = 0; m < 4; ++m) _Pragma("unroll") for (int n = 0; n < 2; ++n) _Pragma("unroll") for (int k = 0; k < 2; ++k) \
;         acc[ai][bj][m][n] = __builtin_amdgcn_mfma_f32_16x16x32_bf16(Bt[n][k], At[m][k], acc[ai][bj][m][n], 0, 0, 0); __builtin_amdgcn_s_setprio(0); } while (0)
; #define PG8_WAIT_V(n) asm volatile("s_waitcnt vmcnt(" #n ")" ::: "memory")
; #define PG8_WAIT_L(n) asm volatile("s_waitcnt lgkmcnt(" #n ")" ::: "memory")
; #define PG8_BAR __builtin_amdgcn_s_barrier()
; #define PG8_SCHED __builtin_amdgcn_sched_barrier(0)
; template <class Epi, class Sched>
; __device__ __forceinline__ void gemm_phase(LAS unsigned char* lds, const Gemm g, const Sched& S, const Epi& E) {
;     ...
;             PG8_BAR; PG8_WAIT_L(0); PG8_MMA(1, 0, At, B0); PG8_BAR; PG8_SCHED;
;             PG8_STAGE(PG8_SB(0, 1), b2 + hstep, voffB);
;             PG8_WAIT_V(6); PG8_BAR; PG8_MMA(1, 1, At, B1); PG8_BAR;
;             PG8_LDB(B0, 1, 0); PG8_SCHED; PG8_LDA(At, 1, 0); PG8_STAGE(PG8_SA(0, 1), a2 + hstep, voffA);
;             PG8_WAIT_L(8); PG8_BAR; PG8_WAIT_L(0); PG8_MMA(0, 0, At, B0); PG8_BAR; PG8_SCHED;
;             PG8_LDB(B1, 1, 1); PG8_STAGE(PG8_SB(1, 0), b3, voffB);
;             PG8_BAR; PG8_WAIT_L(0); PG8_MMA(0, 1, At, B1); PG8_BAR;
;             PG8_LDA(At, 1, 1); PG8_STAGE(PG8_SA(1, 0), a3, voffA);
	s_add_u32 s46, s20, 0x80000
	s_addc_u32 s47, s21, 0
	s_add_i32 s45, s48, s29
	v_lshl_add_u64 v[138:139], s[46:47], 0, v[148:149]
	s_mov_b32 m0, s45
	s_nop 0
	global_load_lds_dwordx4 v[138:139], off
	v_lshl_add_u64 v[138:139], s[46:47], 0, v[128:129]
	s_add_i32 m0, s45, 0x2000
	s_nop 0
	global_load_lds_dwordx4 v[138:139], off
	s_waitcnt vmcnt(6)
	s_barrier
	v_mfma_f32_16x16x32_bf16 v[48:51], v[228:231], v[172:175], v[48:51]
	v_mfma_f32_16x16x32_bf16 v[40:43], v[236:239], v[172:175], v[40:43]
	v_mfma_f32_16x16x32_bf16 v[32:35], v[228:231], v[204:207], v[32:35]
	v_mfma_f32_16x16x32_bf16 v[24:27], v[236:239], v[204:207], v[24:27]
	v_mfma_f32_16x16x32_bf16 v[16:19], v[228:231], v[212:215], v[16:19]
	v_mfma_f32_16x16x32_bf16 v[8:11], v[236:239], v[212:215], v[8:11]
	v_mfma_f32_16x16x32_bf16 v[4:7], v[228:231], v[220:223], v[4:7]
	v_mfma_f32_16x16x32_bf16 v[0:3], v[236:239], v[220:223], v[0:3]
	v_mfma_f32_16x16x32_bf16 v[48:51], v[232:235], v[200:203], v[48:51]
	v_mfma_f32_16x16x32_bf16 v[40:43], v[240:243], v[200:203], v[40:43]
	v_mfma_f32_16x16x32_bf16 v[32:35], v[232:235], v[208:211], v[32:35]
	v_mfma_f32_16x16x32_bf16 v[24:27], v[240:243], v[208:211], v[24:27]
	v_mfma_f32_16x16x32_bf16 v[16:19], v[232:235], v[216:219], v[16:19]
	v_mfma_f32_16x16x32_bf16 v[8:11], v[240:243], v[216:219], v[8:11]
	v_mfma_f32_16x16x32_bf16 v[4:7], v[232:235], v[224:227], v[4:7]
	v_mfma_f32_16x16x32_bf16 v[0:3], v[240:243], v[224:227], v[0:3]
	s_add_i32 s45, 0, 0x18000
	v_add_u32_e32 v168, s45, v143
	s_barrier
	ds_read_b128 v[138:141], v168
	ds_read_b128 v[160:163], v168 offset:1024
	ds_read_b128 v[164:167], v168 offset:2048
	ds_read_b128 v[168:171], v168 offset:3072
	s_add_u32 s22, s22, 0x80000
	s_addc_u32 s23, s23, 0
	s_mov_b32 m0, s33
	v_lshl_add_u64 v[228:229], s[22:23], 0, v[132:133]
	ds_read_b128 v[172:175], v145 offset:32768
	ds_read_b128 v[200:203], v145 offset:33792
	ds_read_b128 v[204:207], v145 offset:34816
	ds_read_b128 v[208:211], v145 offset:35840
	ds_read_b128 v[212:215], v145 offset:36864
	ds_read_b128 v[216:219], v145 offset:37888
	ds_read_b128 v[220:223], v145 offset:38912
	ds_read_b128 v[224:227], v145 offset:39936
	global_load_lds_dwordx4 v[228:229], off
	v_lshl_add_u64 v[228:229], s[22:23], 0, v[130:131]
	s_mov_b32 m0, s34
	s_nop 0
	global_load_lds_dwordx4 v[228:229], off
	s_waitcnt lgkmcnt(8)
	s_barrier
	s_waitcnt lgkmcnt(0)
	s_waitcnt lgkmcnt(0)
	v_mfma_f32_16x16x32_bf16 v[124:127], v[138:141], v[172:175], v[124:127]
	v_mfma_f32_16x16x32_bf16 v[120:123], v[164:167], v[172:175], v[120:123]
	v_mfma_f32_16x16x32_bf16 v[116:119], v[138:141], v[204:207], v[116:119]
	v_mfma_f32_16x16x32_bf16 v[108:111], v[164:167], v[204:207], v[108:111]
	v_mfma_f32_16x16x32_bf16 v[100:103], v[138:141], v[212:215], v[100:103]
	v_mfma_f32_16x16x32_bf16 v[92:95], v[164:167], v[212:215], v[92:95]
	v_mfma_f32_16x16x32_bf16 v[84:87], v[138:141], v[220:223], v[84:87]
	v_mfma_f32_16x16x32_bf16 v[76:79], v[164:167], v[220:223], v[76:79]
	v_mfma_f32_16x16x32_bf16 v[124:127], v[160:163], v[200:203], v[124:127]
	v_mfma_f32_16x16x32_bf16 v[120:123], v[168:171], v[200:203], v[120:123]
	v_mfma_f32_16x16x32_bf16 v[116:119], v[160:163], v[208:211], v[116:119]
	v_mfma_f32_16x16x32_bf16 v[108:111], v[168:171], v[208:211], v[108:111]
	v_mfma_f32_16x16x32_bf16 v[100:103], v[160:163], v[216:219], v[100:103]
	v_mfma_f32_16x16x32_bf16 v[92:95], v[168:171], v[216:219], v[92:95]
	v_mfma_f32_16x16x32_bf16 v[84:87], v[160:163], v[224:227], v[84:87]
	v_mfma_f32_16x16x32_bf16 v[76:79], v[168:171], v[224:227], v[76:79]
	s_barrier
	s_add_i32 s22, 0, 0x1c000
	s_add_i32 s23, s45, s29
	v_add_u32_e32 v240, s22, v143
	v_lshl_add_u64 v[146:147], v[146:147], 0, s[18:19]
	s_mov_b32 m0, s23
	ds_read_b128 v[228:231], v240
	ds_read_b128 v[232:235], v240 offset:1024
	ds_read_b128 v[236:239], v240 offset:2048
	ds_read_b128 v[240:243], v240 offset:3072
	global_load_lds_dwordx4 v[146:147], off
	v_lshl_add_u64 v[146:147], v[176:177], 0, s[18:19]
	s_add_i32 m0, s23, 0x2000
	s_nop 0
	global_load_lds_dwordx4 v[146:147], off
	s_barrier
	s_waitcnt lgkmcnt(0)
	s_waitcnt lgkmcnt(0)
	v_mfma_f32_16x16x32_bf16 v[112:115], v[228:231], v[172:175], v[112:115]
	v_mfma_f32_16x16x32_bf16 v[104:107], v[236:239], v[172:175], v[104:107]
	v_mfma_f32_16x16x32_bf16 v[96:99], v[228:231], v[204:207], v[96:99]
	v_mfma_f32_16x16x32_bf16 v[88:91], v[236:239], v[204:207], v[88:91]
	v_mfma_f32_16x16x32_bf16 v[80:83], v[228:231], v[212:215], v[80:83]
	v_mfma_f32_16x16x32_bf16 v[72:75], v[236:239], v[212:215], v[72:75]
	v_mfma_f32_16x16x32_bf16 v[68:71], v[228:231], v[220:223], v[68:71]
	v_mfma_f32_16x16x32_bf16 v[64:67], v[236:239], v[220:223], v[64:67]
	v_mfma_f32_16x16x32_bf16 v[112:115], v[232:235], v[200:203], v[112:115]
	v_mfma_f32_16x16x32_bf16 v[104:107], v[240:243], v[200:203], v[104:107]
	v_mfma_f32_16x16x32_bf16 v[96:99], v[232:235], v[208:211], v[96:99]
	v_mfma_f32_16x16x32_bf16 v[88:91], v[240:243], v[208:211], v[88:91]
	v_mfma_f32_16x16x32_bf16 v[80:83], v[232:235], v[216:219], v[80:83]
	v_mfma_f32_16x16x32_bf16 v[72:75], v[240:243], v[216:219], v[72:75]
	v_mfma_f32_16x16x32_bf16 v[68:71], v[232:235], v[224:227], v[68:71]
	v_mfma_f32_16x16x32_bf16 v[64:67], v[240:243], v[224:227], v[64:67]
	s_mov_b32 m0, s35
	v_lshl_add_u64 v[146:147], v[188:189], 0, s[18:19]
	s_barrier
	ds_read_b128 v[172:175], v145 offset:49152
	ds_read_b128 v[200:203], v145 offset:50176
	ds_read_b128 v[204:207], v145 offset:51200
	ds_read_b128 v[208:211], v145 offset:52224
	ds_read_b128 v[212:215], v145 offset:53248
	ds_read_b128 v[216:219], v145 offset:54272
	ds_read_b128 v[220:223], v145 offset:55296
	ds_read_b128 v[224:227], v145 offset:56320
	global_load_lds_dwordx4 v[146:147], off
	v_lshl_add_u64 v[146:147], v[190:191], 0, s[18:19]
	s_mov_b32 m0, s36
	s_nop 0
	global_load_lds_dwordx4 v[146:147], off
	s_barrier
; #define PG8_STAGE(bufoff, gbase, voff) do { _Pragma("unroll") for (int _i = 0; _i < 2; ++_i) \
;         __builtin_amdgcn_global_load_lds((const unsigned*)((const char*)(gbase) + (voff)[_i]), (LAS unsigned*)(lds + (bufoff) + ldsw + _i * 8192), 16, 0, 0); } while (0)
; #define PG8_LDA(dst, b, h) do { _Pragma("unroll") for (int m = 0; m < 4; ++m) _Pragma("unroll") for (int k = 0; k < 2; ++k) dst[m][k] = *(const LAS bf16x8*)(lds + PG8_SA(b, h) + aoff + m * 2048 + k * 1024); } while (0)
; #define PG8_MMA(ai, bj, At, Bt) do { __builtin_amdgcn_s_setprio(1); _Pragma("unroll") for (int m = 0; m < 4; ++m) _Pragma("unroll") for (int n = 0; n < 2; ++n) _Pragma("unroll") for (int k = 0; k < 2; ++k) \
;         acc[ai][bj][m][n] = __builtin_amdgcn_mfma_f32_16x16x32_bf16(Bt[n][k], At[m][k], acc[ai][bj][m][n], 0, 0, 0); __builtin_amdgcn_s_setprio(0); } while (0)
; #define PG8_WAIT_V(n) asm volatile("s_waitcnt vmcnt(" #n ")" ::: "memory")
; #define PG8_WAIT_L(n) asm volatile("s_waitcnt lgkmcnt(" #n ")" ::: "memory")
; #define PG8_BAR __builtin_amdgcn_s_barrier()
; #define PG8_SCHED __builtin_amdgcn_sched_barrier(0)
; template <class Epi, class Sched>
; __device__ __forceinline__ void gemm_phase(LAS unsigned char* lds, const Gemm g, const Sched& S, const Epi& E) {
;     ...
;             PG8_LDA(At, 1, 1); PG8_STAGE(PG8_SA(1, 0), a3, voffA);
;             PG8_BAR; PG8_WAIT_L(0); PG8_MMA(1, 0, At, B0); PG8_BAR; PG8_SCHED;
;             PG8_STAGE(PG8_SB(1, 1), b3 + hstep, voffB);
;             PG8_WAIT_V(6); PG8_BAR; PG8_MMA(1, 1, At, B1); PG8_BAR;
;         }
	s_waitcnt lgkmcnt(0)
	s_waitcnt lgkmcnt(0)
	v_mfma_f32_16x16x32_bf16 v[60:63], v[138:141], v[172:175], v[60:63]
	v_mfma_f32_16x16x32_bf16 v[56:59], v[164:167], v[172:175], v[56:59]
	v_mfma_f32_16x16x32_bf16 v[52:55], v[138:141], v[204:207], v[52:55]
	v_mfma_f32_16x16x32_bf16 v[44:47], v[164:167], v[204:207], v[44:47]
	v_mfma_f32_16x16x32_bf16 v[36:39], v[138:141], v[212:215], v[36:39]
	v_mfma_f32_16x16x32_bf16 v[28:31], v[164:167], v[212:215], v[28:31]
	v_mfma_f32_16x16x32_bf16 v[20:23], v[138:141], v[220:223], v[20:23]
	v_mfma_f32_16x16x32_bf16 v[12:15], v[164:167], v[220:223], v[12:15]
	v_mfma_f32_16x16x32_bf16 v[60:63], v[160:163], v[200:203], v[60:63]
	v_mfma_f32_16x16x32_bf16 v[56:59], v[168:171], v[200:203], v[56:59]
	v_mfma_f32_16x16x32_bf16 v[52:55], v[160:163], v[208:211], v[52:55]
	v_mfma_f32_16x16x32_bf16 v[44:47], v[168:171], v[208:211], v[44:47]
	v_mfma_f32_16x16x32_bf16 v[36:39], v[160:163], v[216:219], v[36:39]
	v_mfma_f32_16x16x32_bf16 v[28:31], v[168:171], v[216:219], v[28:31]
	v_mfma_f32_16x16x32_bf16 v[20:23], v[160:163], v[224:227], v[20:23]
	v_mfma_f32_16x16x32_bf16 v[12:15], v[168:171], v[224:227], v[12:15]
	s_barrier
	s_add_u32 s20, s20, 0x80080
	s_addc_u32 s21, s21, 0
	s_add_i32 s22, s22, s29
	v_lshl_add_u64 v[138:139], s[20:21], 0, v[148:149]
	s_mov_b32 m0, s22
	s_nop 0
	global_load_lds_dwordx4 v[138:139], off
	v_lshl_add_u64 v[138:139], s[20:21], 0, v[128:129]
	s_add_i32 m0, s22, 0x2000
	s_nop 0
	global_load_lds_dwordx4 v[138:139], off
	s_waitcnt vmcnt(6)
	s_barrier
	v_mfma_f32_16x16x32_bf16 v[48:51], v[228:231], v[172:175], v[48:51]
	v_mfma_f32_16x16x32_bf16 v[40:43], v[236:239], v[172:175], v[40:43]
	v_mfma_f32_16x16x32_bf16 v[32:35], v[228:231], v[204:207], v[32:35]
	v_mfma_f32_16x16x32_bf16 v[24:27], v[236:239], v[204:207], v[24:27]
	v_mfma_f32_16x16x32_bf16 v[16:19], v[228:231], v[212:215], v[16:19]
	v_mfma_f32_16x16x32_bf16 v[8:11], v[236:239], v[212:215], v[8:11]
	v_mfma_f32_16x16x32_bf16 v[4:7], v[228:231], v[220:223], v[4:7]
	v_mfma_f32_16x16x32_bf16 v[0:3], v[236:239], v[220:223], v[0:3]
	v_mfma_f32_16x16x32_bf16 v[48:51], v[232:235], v[200:203], v[48:51]
	v_mfma_f32_16x16x32_bf16 v[40:43], v[240:243], v[200:203], v[40:43]
	v_mfma_f32_16x16x32_bf16 v[32:35], v[232:235], v[208:211], v[32:35]
	v_mfma_f32_16x16x32_bf16 v[24:27], v[240:243], v[208:211], v[24:27]
	v_mfma_f32_16x16x32_bf16 v[16:19], v[232:235], v[216:219], v[16:19]
	v_mfma_f32_16x16x32_bf16 v[8:11], v[240:243], v[216:219], v[8:11]
	v_mfma_f32_16x16x32_bf16 v[4:7], v[232:235], v[224:227], v[4:7]
	v_mfma_f32_16x16x32_bf16 v[0:3], v[240:243], v[224:227], v[0:3]
	s_add_i32 s44, s44, 2
	s_add_u32 s16, s16, 0x100
	s_addc_u32 s17, s17, 0
	s_add_u32 s42, s42, 0x100
	s_addc_u32 s43, s43, 0
	s_cmp_gt_u32 s44, 29
	s_barrier
	s_cbranch_scc0 .LBB0_125
; __device__ __forceinline__ unsigned cvt_pk_bf16(float lo, float hi) { unsigned r; asm("v_cvt_pk_bf16_f32 %0, %1, %2" : "=v"(r) : "v"(lo), "v"(hi)); return r; }
; #define PG8_WAIT_V(n) asm volatile("s_waitcnt vmcnt(" #n ")" ::: "memory")
; #define PG8_BAR __builtin_amdgcn_s_barrier()
;     __device__ __forceinline__ void operator()(const f32x4 (&acc)[2][2][4][2], const Unit& u, int wr, int wc, int fr, int fq) const {
;         const int row0 = u.pm * BM + wr * 64 + fr, col0 = u.pn * BM + wc * 32 + 8 * fq;
; #pragma unroll
;         for (int ai = 0; ai < 2; ++ai)
; #pragma unroll
;             for (int m = 0; m < 4; ++m) { bf16_t* rowp = O + (size_t)(row0 + ai * HALF + m * 16) * ldc + col0;
; #pragma unroll
;                 for (int bj = 0; bj < 2; ++bj) { const f32x4 v0 = acc[ai][bj][m][0], v1 = acc[ai][bj][m][1];
;                     u32x4 w; w.x = cvt_pk_bf16(v0[0], v0[1]); w.y = cvt_pk_bf16(v0[2], v0[3]); w.z = cvt_pk_bf16(v1[0], v1[1]); w.w = cvt_pk_bf16(v1[2], v1[3]);
;                     *(u32x4*)(rowp + bj * HALF) = w; } }
;     }
; template <class Epi, class Sched>
; __device__ __forceinline__ void gemm_phase(LAS unsigned char* lds, const Gemm g, const Sched& S, const Epi& E) {
;     ...
;         E(acc, cur, wr, wc, fr, fq);
;         if (!has_next) break;
; #pragma unroll
;         for (int a = 0; a < 2; ++a)
; #pragma unroll
;             for (int b = 0; b < 2; ++b)
; #pragma unroll
;                 for (int m = 0; m < 4; ++m)
; #pragma unroll
;                     for (int n = 0; n < 2; ++n) acc[a][b][m][n] = (f32x4){0.f, 0.f, 0.f, 0.f};
;         cur = nxt; cA = nA; cB = nB; ++ui;
;     }
;     PG8_WAIT_V(0);
;     if (wr == 0) PG8_BAR;
;     PG8_BAR;
	v_lshl_add_u32 v160, s39, 8, v142
	v_lshl_or_b32 v140, s38, 8, v144
	v_ashrrev_i32_e32 v141, 31, v140
	v_mov_b64_e32 v[138:139], s[2:3]
	v_cvt_pk_bf16_f32 v68, v68, v69
	v_cvt_pk_bf16_f32 v69, v70, v71
	v_cvt_pk_bf16_f32 v70, v64, v65
	v_add_u32_e32 v64, 0x80, v160
	v_mad_i64_i32 v[146:147], s[16:17], v160, s56, v[138:139]
	v_lshlrev_b64 v[140:141], 1, v[140:141]
	v_cvt_pk_bf16_f32 v112, v112, v113
	v_cvt_pk_bf16_f32 v113, v114, v115
	v_cvt_pk_bf16_f32 v114, v104, v105
	v_or_b32_e32 v104, 16, v160
	v_mad_i64_i32 v[64:65], s[16:17], v64, s56, v[138:139]
	v_cvt_pk_bf16_f32 v48, v48, v49
	v_cvt_pk_bf16_f32 v49, v50, v51
	v_cvt_pk_bf16_f32 v50, v40, v41
	v_add_u32_e32 v40, 0x90, v160
	v_lshl_add_u64 v[146:147], v[146:147], 0, v[140:141]
	v_mad_i64_i32 v[104:105], s[16:17], v104, s56, v[138:139]
	v_cvt_pk_bf16_f32 v96, v96, v97
	v_cvt_pk_bf16_f32 v97, v98, v99
	v_cvt_pk_bf16_f32 v98, v88, v89
	v_or_b32_e32 v88, 32, v160
	v_lshl_add_u64 v[64:65], v[64:65], 0, v[140:141]
	v_mad_i64_i32 v[40:41], s[16:17], v40, s56, v[138:139]
	v_cvt_pk_bf16_f32 v32, v32, v33
	v_cvt_pk_bf16_f32 v33, v34, v35
	v_cvt_pk_bf16_f32 v34, v24, v25
	v_add_u32_e32 v24, 0xa0, v160
	v_cvt_pk_bf16_f32 v115, v106, v107
	global_store_dwordx4 v[146:147], v[112:115], off offset:256
	v_mad_i64_i32 v[88:89], s[16:17], v88, s56, v[138:139]
	s_nop 0
	v_lshl_add_u64 v[112:113], v[104:105], 0, v[140:141]
	v_cvt_pk_bf16_f32 v80, v80, v81
	v_cvt_pk_bf16_f32 v81, v82, v83
	v_cvt_pk_bf16_f32 v82, v72, v73
	v_or_b32_e32 v72, 48, v160
	v_cvt_pk_bf16_f32 v51, v42, v43
	global_store_dwordx4 v[64:65], v[48:51], off offset:256
	v_mad_i64_i32 v[24:25], s[16:17], v24, s56, v[138:139]
	s_nop 0
	v_lshl_add_u64 v[48:49], v[40:41], 0, v[140:141]
	v_cvt_pk_bf16_f32 v16, v16, v17
	v_cvt_pk_bf16_f32 v17, v18, v19
	v_cvt_pk_bf16_f32 v18, v8, v9
	v_add_u32_e32 v8, 0xb0, v160
	v_cvt_pk_bf16_f32 v99, v90, v91
	global_store_dwordx4 v[112:113], v[96:99], off offset:256
	v_mad_i64_i32 v[72:73], s[16:17], v72, s56, v[138:139]
	s_nop 0
	v_lshl_add_u64 v[96:97], v[88:89], 0, v[140:141]
	v_cvt_pk_bf16_f32 v35, v26, v27
	global_store_dwordx4 v[48:49], v[32:35], off offset:256
	v_mad_i64_i32 v[8:9], s[16:17], v8, s56, v[138:139]
	s_nop 0
	v_lshl_add_u64 v[32:33], v[24:25], 0, v[140:141]
	v_cvt_pk_bf16_f32 v83, v74, v75
	global_store_dwordx4 v[96:97], v[80:83], off offset:256
	v_cvt_pk_bf16_f32 v19, v10, v11
	global_store_dwordx4 v[32:33], v[16:19], off offset:256
	s_and_b64 vcc, exec, s[0:1]
	v_lshl_add_u64 v[80:81], v[72:73], 0, v[140:141]
	v_lshl_add_u64 v[16:17], v[8:9], 0, v[140:141]
	s_mov_b32 s38, s4
	s_mov_b32 s39, s6
	s_mov_b64 s[20:21], s[14:15]
	s_mov_b64 s[16:17], s[12:13]
	v_cvt_pk_bf16_f32 v124, v124, v125
	v_cvt_pk_bf16_f32 v125, v126, v127
	v_cvt_pk_bf16_f32 v126, v120, v121
	v_cvt_pk_bf16_f32 v127, v122, v123
	global_store_dwordx4 v[146:147], v[124:127], off
	v_cvt_pk_bf16_f32 v104, v116, v117
	v_cvt_pk_bf16_f32 v105, v118, v119
	v_cvt_pk_bf16_f32 v106, v108, v109
	v_cvt_pk_bf16_f32 v107, v110, v111
	global_store_dwordx4 v[112:113], v[104:107], off
	v_cvt_pk_bf16_f32 v88, v100, v101
	v_cvt_pk_bf16_f32 v89, v102, v103
	v_cvt_pk_bf16_f32 v90, v92, v93
	v_cvt_pk_bf16_f32 v91, v94, v95
	global_store_dwordx4 v[96:97], v[88:91], off
	v_cvt_pk_bf16_f32 v72, v84, v85
	v_cvt_pk_bf16_f32 v73, v86, v87
	v_cvt_pk_bf16_f32 v74, v76, v77
	v_cvt_pk_bf16_f32 v75, v78, v79
	global_store_dwordx4 v[80:81], v[72:75], off
	v_cvt_pk_bf16_f32 v71, v66, v67
	global_store_dwordx4 v[80:81], v[68:71], off offset:256
	v_cvt_pk_bf16_f32 v60, v60, v61
	v_cvt_pk_bf16_f32 v61, v62, v63
	v_cvt_pk_bf16_f32 v62, v56, v57
	v_cvt_pk_bf16_f32 v63, v58, v59
	global_store_dwordx4 v[64:65], v[60:63], off
	v_cvt_pk_bf16_f32 v40, v52, v53
	v_cvt_pk_bf16_f32 v41, v54, v55
	v_cvt_pk_bf16_f32 v42, v44, v45
	v_cvt_pk_bf16_f32 v43, v46, v47
	global_store_dwordx4 v[48:49], v[40:43], off
	v_cvt_pk_bf16_f32 v24, v36, v37
	v_cvt_pk_bf16_f32 v25, v38, v39
	v_cvt_pk_bf16_f32 v26, v28, v29
	v_cvt_pk_bf16_f32 v27, v30, v31
	global_store_dwordx4 v[32:33], v[24:27], off
	v_cvt_pk_bf16_f32 v8, v20, v21
	v_cvt_pk_bf16_f32 v9, v22, v23
	v_cvt_pk_bf16_f32 v10, v12, v13
	v_cvt_pk_bf16_f32 v11, v14, v15
	global_store_dwordx4 v[16:17], v[8:11], off
	v_cvt_pk_bf16_f32 v4, v4, v5
	v_cvt_pk_bf16_f32 v5, v6, v7
	v_cvt_pk_bf16_f32 v6, v0, v1
	v_cvt_pk_bf16_f32 v7, v2, v3
	global_store_dwordx4 v[16:17], v[4:7], off offset:256
	s_cbranch_vccz .LBB0_118
	s_waitcnt vmcnt(0)
	s_cmpk_gt_u32 s24, 0xff
	s_cbranch_scc1 .LBB0_129
	s_barrier
.LBB0_129:
	s_barrier
	s_setprio 0

; #define PG8_STAGE(bufoff, gbase, voff) do { _Pragma("unroll") for (int _i = 0; _i < 2; ++_i) \
;         __builtin_amdgcn_global_load_lds((const unsigned*)((const char*)(gbase) + (voff)[_i]), (LAS unsigned*)(lds + (bufoff) + ldsw + _i * 8192), 16, 0, 0); } while (0)
; #define PG8_WAIT_V(n) asm volatile("s_waitcnt vmcnt(" #n ")" ::: "memory")
; #define PG8_BAR __builtin_amdgcn_s_barrier()
; template <class Epi, class Sched>
; __device__ __forceinline__ void gemm_phase(LAS unsigned char* lds, const Gemm g, const Sched& S, const Epi& E) {
;     ...
;     const int wid = __builtin_amdgcn_readfirstlane(tid >> 6), lane = tid & 63, wr = wid >> 2, wc = wid & 3, fr = lane & 15, fq = lane >> 4;
;     const int K = g.K;
;     unsigned voffA[2], voffB[2];
; #pragma unroll
;     for (int i = 0; i < 2; ++i) { int R, C; stage_rc(tid * 16 + i * 8192, R, C); const int Rb = Epi::PERM ? ((R & ~31) + perm32(R & 31)) : R;
;         voffA[i] = (unsigned)(R * K + C) * 2u; voffB[i] = (unsigned)(Rb * K + C) * 2u; }
;     const size_t kstep = (size_t)(BK * 2);
;     const size_t hstep = (size_t)HALF * K * 2;
;     const size_t tstep = 2 * hstep;
;     const unsigned ldsw = (unsigned)wid * 1024u;
;     const int aoff = lds_byte(wr * 64 + fr, fq * 8), boff = lds_byte(wc * 32 + fr, fq * 8);
;     ...
;     Unit cur, nxt; int ui = 0;
;     if (!S.next(0, cur)) return;
;     f32x4 acc[2][2][4][2];
; #pragma unroll
;     for (int a = 0; a < 2; ++a)
; #pragma unroll
;         for (int b = 0; b < 2; ++b)
; #pragma unroll
;             for (int m = 0; m < 4; ++m)
; #pragma unroll
;                 for (int n = 0; n < 2; ++n) acc[a][b][m][n] = (f32x4){0.f, 0.f, 0.f, 0.f};
;     bf16x8 At[4][2], B0[2][2], B1[2][2];
;     const char* cA = (const char*)g.A + (size_t)cur.pm * tstep + (size_t)cur.kt0 * kstep; const char* cB = (const char*)g.Bt + (size_t)cur.pn * tstep + (size_t)cur.kt0 * kstep;
;     PG8_STAGE(PG8_SB(0, 0), cB, voffB); PG8_STAGE(PG8_SA(0, 0), cA, voffA); PG8_STAGE(PG8_SB(0, 1), cB + hstep, voffB); PG8_STAGE(PG8_SA(0, 1), cA + hstep, voffA);
;     if (wr == 1) PG8_BAR;
;     PG8_WAIT_V(4); PG8_BAR;
;     PG8_STAGE(PG8_SB(1, 0), cB + kstep, voffB); PG8_STAGE(PG8_SA(1, 0), cA + kstep, voffA); PG8_STAGE(PG8_SB(1, 1), cB + hstep + kstep, voffB);
;     PG8_WAIT_V(6); PG8_BAR;
.LBB0_154:
	v_readlane_b32 s0, v251, 15
	v_mov_b32_e32 v16, v178
	v_readlane_b32 s1, v251, 16
	s_andn2_b64 vcc, exec, s[0:1]
	v_readfirstlane_b32 s27, v16
	s_cbranch_vccnz .LBB0_178
	v_lshlrev_b32_e32 v0, 4, v16
	v_add_u32_e32 v1, 0x2000, v0
	v_ashrrev_i32_e32 v2, 31, v1
	v_lshrrev_b32_e32 v2, 22, v2
	v_add_u32_e32 v2, v1, v2
	v_ashrrev_i32_e32 v8, 10, v2
	v_mul_i32_i24_e32 v2, 0x400, v8
	v_sub_u32_e32 v1, v1, v2
	v_lshrrev_b32_e32 v2, 4, v1
	v_bitop3_b32 v1, v2, v1, 32 bitop3:0x6c
	v_ashrrev_i32_e32 v2, 31, v1
	v_lshrrev_b32_e32 v2, 26, v2
	v_add_u32_e32 v2, v1, v2
	v_ashrrev_i32_e32 v9, 6, v2
	v_and_b32_e32 v2, 0xc0, v2
	v_sub_u32_e32 v1, v1, v2
	v_ashrrev_i16_sdwa v1, v183, sext(v1) dst_sel:DWORD dst_unused:UNUSED_PAD src0_sel:DWORD src1_sel:BYTE_0
	v_bfe_i32 v11, v1, 0, 16
	v_bfe_i32 v1, v16, 27, 1
	v_lshrrev_b32_e32 v1, 22, v1
	v_add_u32_e32 v1, v0, v1
	v_and_b32_e32 v1, 0xfffffc00, v1
	v_sub_u32_e32 v0, v0, v1
	s_ashr_i32 s0, s27, 6
	v_lshrrev_b32_e32 v1, 4, v0
	v_ashrrev_i32_e32 v2, 31, v16
	s_ashr_i32 s1, s27, 8
	s_lshl_b32 s29, s0, 10
	v_bitop3_b32 v0, v1, v0, 32 bitop3:0x6c
	v_lshrrev_b32_e32 v2, 26, v2
	s_add_u32 s30, s62, 0xb800000
	v_ashrrev_i32_e32 v1, 31, v0
	v_add_u32_e32 v2, v16, v2
	s_addc_u32 s31, s63, 0
	v_readlane_b32 s4, v253, 27
	v_lshrrev_b32_e32 v1, 26, v1
	v_ashrrev_i32_e32 v13, 6, v2
	s_cmp_eq_u32 s4, 10
	s_mov_b32 s4, 0x6e00000
	v_lshlrev_b32_e32 v3, 3, v8
	v_add_u32_e32 v1, v0, v1
	v_lshlrev_b32_e32 v2, 3, v13
	s_cselect_b32 s4, s4, 0x5800000
	v_and_b32_e32 v3, 0x7ffff0, v3
	v_ashrrev_i32_e32 v12, 6, v1
	v_and_b32_e32 v2, 0x7ffff0, v2
	s_add_u32 s33, s62, s4
	v_add_u32_e32 v3, v9, v3
	s_movk_i32 s4, 0x1600
	v_add_u32_e32 v2, v12, v2
	v_mul_lo_u32 v3, v3, s4
	v_mul_lo_u32 v2, v2, s4
	v_readlane_b32 s4, v252, 28
	s_addc_u32 s34, s63, 0
	v_readlane_b32 s5, v252, 29
	s_mov_b32 s6, s4
	s_mul_i32 s4, s4, 0x2c0000
	v_lshlrev_b32_e32 v4, 5, v8
	s_add_u32 s4, s30, s4
	s_mul_hi_i32 s5, s6, 0x2c0000
	v_and_b32_e32 v10, 32, v4
	s_addc_u32 s5, s31, s5
	v_readlane_b32 s6, v252, 26
	v_or_b32_e32 v3, v3, v10
	v_and_b32_e32 v1, 0xc0, v1
	s_add_u32 s6, s33, s6
	v_readlane_b32 s7, v252, 27
	v_add_lshl_u32 v140, v3, v11, 1
	v_lshlrev_b32_e32 v3, 5, v13
	v_sub_u32_e32 v0, v0, v1
	s_addc_u32 s7, s34, s7
	v_readlane_b32 s14, v251, 17
	v_and_b32_e32 v14, 32, v3
	v_ashrrev_i16_sdwa v0, v183, sext(v0) dst_sel:DWORD dst_unused:UNUSED_PAD src0_sel:DWORD src1_sel:BYTE_0
	v_readlane_b32 s15, v251, 18
	s_add_u32 s20, s6, s14
	v_or_b32_e32 v2, v2, v14
	v_bfe_i32 v15, v0, 0, 16
	s_addc_u32 s21, s7, s15
	s_add_i32 s35, s29, 0
	v_add_lshl_u32 v148, v2, v15, 1
	s_add_i32 m0, s35, 0x10000
	v_mov_b32_e32 v141, v149
	global_load_lds_dwordx4 v148, s[20:21]
	s_add_i32 m0, s35, 0x12000
	s_add_u32 s16, s4, s14
	global_load_lds_dwordx4 v140, s[20:21]
	s_addc_u32 s17, s5, s15
	s_mov_b32 m0, s35
	s_add_i32 s36, s35, 0x2000
	global_load_lds_dwordx4 v148, s[16:17]
	s_mov_b32 m0, s36
	s_add_u32 s4, s20, 0x160000
	global_load_lds_dwordx4 v140, s[16:17]
	s_addc_u32 s5, s21, 0
	s_add_i32 m0, s35, 0x14000
	v_lshl_add_u64 v[6:7], s[20:21], 0, v[148:149]
	global_load_lds_dwordx4 v148, s[4:5]
	s_add_i32 m0, s35, 0x16000
	v_lshl_add_u64 v[4:5], s[20:21], 0, v[140:141]
	global_load_lds_dwordx4 v140, s[4:5]
	s_add_u32 s4, s16, 0x160000
	s_addc_u32 s5, s17, 0
	s_add_i32 s37, s35, 0x4000
	s_mov_b32 m0, s37
	s_add_i32 s38, s35, 0x6000
	global_load_lds_dwordx4 v148, s[4:5]
	s_mov_b32 m0, s38
	v_lshl_add_u64 v[2:3], s[16:17], 0, v[148:149]
	global_load_lds_dwordx4 v140, s[4:5]
	s_cmp_lg_u32 s1, 1
	v_lshl_add_u64 v[0:1], s[16:17], 0, v[140:141]
	s_cbranch_scc1 .LBB0_157
	s_barrier
	s_setprio 1

; #define PG8_STAGE(bufoff, gbase, voff) do { _Pragma("unroll") for (int _i = 0; _i < 2; ++_i) \
;         __builtin_amdgcn_global_load_lds((const unsigned*)((const char*)(gbase) + (voff)[_i]), (LAS unsigned*)(lds + (bufoff) + ldsw + _i * 8192), 16, 0, 0); } while (0)
; #define PG8_LDA(dst, b, h) do { _Pragma("unroll") for (int m = 0; m < 4; ++m) _Pragma("unroll") for (int k = 0; k < 2; ++k) dst[m][k] = *(const LAS bf16x8*)(lds + PG8_SA(b, h) + aoff + m * 2048 + k * 1024); } while (0)
; #define PG8_LDB(dst, b, h) do { _Pragma("unroll") for (int n = 0; n < 2; ++n) _Pragma("unroll") for (int k = 0; k < 2; ++k) dst[n][k] = *(const LAS bf16x8*)(lds + PG8_SB(b, h) + boff + n * 2048 + k * 1024); } while (0)
; #define PG8_MMA(ai, bj, At, Bt) do { __builtin_amdgcn_s_setprio(1); _Pragma("unroll") for (int m = 0; m < 4; ++m) _Pragma("unroll") for (int n = 0; n < 2; ++n) _Pragma("unroll") for (int k = 0; k < 2; ++k) \
;         acc[ai][bj][m][n] = __builtin_amdgcn_mfma_f32_16x16x32_bf16(Bt[n][k], At[m][k], acc[ai][bj][m][n], 0, 0, 0); __builtin_amdgcn_s_setprio(0); } while (0)
; #define PG8_WAIT_L(n) asm volatile("s_waitcnt lgkmcnt(" #n ")" ::: "memory")
; #define PG8_BAR __builtin_amdgcn_s_barrier()
; #define PG8_SCHED __builtin_amdgcn_sched_barrier(0)
; template <class Epi, class Sched>
; __device__ __forceinline__ void gemm_phase(LAS unsigned char* lds, const Gemm g, const Sched& S, const Epi& E) {
;     ...
;             PG8_LDB(B0, 0, 0); PG8_SCHED; PG8_LDA(At, 0, 0); PG8_STAGE(PG8_SA(1, 1), a1 + hstep, voffA);
;             PG8_WAIT_L(8); PG8_BAR; PG8_WAIT_L(0); PG8_MMA(0, 0, At, B0); PG8_BAR; PG8_SCHED;
;             PG8_LDB(B1, 0, 1); PG8_STAGE(PG8_SB(0, 0), b2, voffB);
;             PG8_BAR; PG8_WAIT_L(0); PG8_MMA(0, 1, At, B1); PG8_BAR;
;             PG8_LDA(At, 0, 1); PG8_STAGE(PG8_SA(0, 0), a2, voffA);
;             PG8_BAR; PG8_WAIT_L(0); PG8_MMA(1, 0, At, B0); PG8_BAR; PG8_SCHED;
.LBB0_170:
	s_add_i32 s53, s22, 2
	s_add_u32 s20, s16, 0x100
	s_addc_u32 s21, s17, 0
	s_add_i32 s54, 0, 0x10000
	v_add_u32_e32 v146, s54, v171
	ds_read_b128 v[128:131], v146
	ds_read_b128 v[132:135], v146 offset:1024
	ds_read_b128 v[136:139], v146 offset:2048
	ds_read_b128 v[160:163], v146 offset:3072
	s_cmp_eq_u32 s15, s22
	s_cselect_b32 s22, s4, s51
	s_cselect_b32 s25, s7, s21
	s_cselect_b32 s24, s6, s20
	s_cselect_b32 s23, s5, s52
	v_lshl_add_u64 v[146:147], s[16:17], 0, v[142:143]
	s_add_i32 m0, s35, 0xc000
	ds_read_b128 v[164:167], v173
	ds_read_b128 v[174:177], v173 offset:1024
	ds_read_b128 v[200:203], v173 offset:2048
	ds_read_b128 v[204:207], v173 offset:3072
	ds_read_b128 v[208:211], v173 offset:4096
	ds_read_b128 v[212:215], v173 offset:5120
	ds_read_b128 v[216:219], v173 offset:6144
	ds_read_b128 v[220:223], v173 offset:7168
	global_load_lds_dwordx4 v[146:147], off
	v_lshl_add_u64 v[146:147], s[16:17], 0, v[144:145]
	s_add_i32 m0, s35, 0xe000
	s_nop 0
	global_load_lds_dwordx4 v[146:147], off
	s_waitcnt lgkmcnt(8)
	s_barrier
	s_waitcnt lgkmcnt(0)
	s_waitcnt lgkmcnt(0)
	v_mfma_f32_16x16x32_bf16 v[124:127], v[128:131], v[164:167], v[124:127]
	v_mfma_f32_16x16x32_bf16 v[120:123], v[136:139], v[164:167], v[120:123]
	v_mfma_f32_16x16x32_bf16 v[116:119], v[128:131], v[200:203], v[116:119]
	v_mfma_f32_16x16x32_bf16 v[112:115], v[136:139], v[200:203], v[112:115]
	v_mfma_f32_16x16x32_bf16 v[100:103], v[128:131], v[208:211], v[100:103]
	v_mfma_f32_16x16x32_bf16 v[96:99], v[136:139], v[208:211], v[96:99]
	v_mfma_f32_16x16x32_bf16 v[84:87], v[128:131], v[216:219], v[84:87]
	v_mfma_f32_16x16x32_bf16 v[80:83], v[136:139], v[216:219], v[80:83]
	v_mfma_f32_16x16x32_bf16 v[124:127], v[132:135], v[174:177], v[124:127]
	v_mfma_f32_16x16x32_bf16 v[120:123], v[160:163], v[174:177], v[120:123]
	v_mfma_f32_16x16x32_bf16 v[116:119], v[132:135], v[204:207], v[116:119]
	v_mfma_f32_16x16x32_bf16 v[112:115], v[160:163], v[204:207], v[112:115]
	v_mfma_f32_16x16x32_bf16 v[100:103], v[132:135], v[212:215], v[100:103]
	v_mfma_f32_16x16x32_bf16 v[96:99], v[160:163], v[212:215], v[96:99]
	v_mfma_f32_16x16x32_bf16 v[84:87], v[132:135], v[220:223], v[84:87]
	v_mfma_f32_16x16x32_bf16 v[80:83], v[160:163], v[220:223], v[80:83]
	s_barrier
	s_add_i32 s55, 0, 0x14000
	v_add_u32_e32 v146, s55, v171
	s_add_i32 s16, s54, s29
	ds_read_b128 v[224:227], v146
	ds_read_b128 v[228:231], v146 offset:1024
	ds_read_b128 v[232:235], v146 offset:2048
	ds_read_b128 v[236:239], v146 offset:3072
	v_lshl_add_u64 v[146:147], s[22:23], 0, v[148:149]
	s_mov_b32 m0, s16
	v_lshl_add_u64 v[168:169], s[22:23], 0, v[140:141]
	global_load_lds_dwordx4 v[146:147], off
	s_add_i32 m0, s16, 0x2000
	s_nop 0
	global_load_lds_dwordx4 v[168:169], off
	s_barrier
	s_waitcnt lgkmcnt(0)
	s_waitcnt lgkmcnt(0)
	v_mfma_f32_16x16x32_bf16 v[108:111], v[224:227], v[164:167], v[108:111]
	v_mfma_f32_16x16x32_bf16 v[104:107], v[232:235], v[164:167], v[104:107]
	v_mfma_f32_16x16x32_bf16 v[92:95], v[224:227], v[200:203], v[92:95]
	v_mfma_f32_16x16x32_bf16 v[88:91], v[232:235], v[200:203], v[88:91]
	v_mfma_f32_16x16x32_bf16 v[76:79], v[224:227], v[208:211], v[76:79]
	v_mfma_f32_16x16x32_bf16 v[72:75], v[232:235], v[208:211], v[72:75]
	v_mfma_f32_16x16x32_bf16 v[68:71], v[224:227], v[216:219], v[68:71]
	v_mfma_f32_16x16x32_bf16 v[64:67], v[232:235], v[216:219], v[64:67]
	v_mfma_f32_16x16x32_bf16 v[108:111], v[228:231], v[174:177], v[108:111]
	v_mfma_f32_16x16x32_bf16 v[104:107], v[236:239], v[174:177], v[104:107]
	v_mfma_f32_16x16x32_bf16 v[92:95], v[228:231], v[204:207], v[92:95]
	v_mfma_f32_16x16x32_bf16 v[88:91], v[236:239], v[204:207], v[88:91]
	v_mfma_f32_16x16x32_bf16 v[76:79], v[228:231], v[212:215], v[76:79]
	v_mfma_f32_16x16x32_bf16 v[72:75], v[236:239], v[212:215], v[72:75]
	v_mfma_f32_16x16x32_bf16 v[68:71], v[228:231], v[220:223], v[68:71]
	v_mfma_f32_16x16x32_bf16 v[64:67], v[236:239], v[220:223], v[64:67]
	s_mov_b32 m0, s35
	v_lshl_add_u64 v[188:189], s[24:25], 0, v[148:149]
	s_barrier
	ds_read_b128 v[164:167], v173 offset:16384
	ds_read_b128 v[174:177], v173 offset:17408
	ds_read_b128 v[200:203], v173 offset:18432
	ds_read_b128 v[204:207], v173 offset:19456
	ds_read_b128 v[208:211], v173 offset:20480
	ds_read_b128 v[212:215], v173 offset:21504
	ds_read_b128 v[216:219], v173 offset:22528
	ds_read_b128 v[220:223], v173 offset:23552
	global_load_lds_dwordx4 v[188:189], off
	v_lshl_add_u64 v[190:191], s[24:25], 0, v[140:141]
	s_mov_b32 m0, s36
	s_nop 0
	global_load_lds_dwordx4 v[190:191], off
	s_barrier
	s_waitcnt lgkmcnt(0)
	s_waitcnt lgkmcnt(0)
	v_mfma_f32_16x16x32_bf16 v[60:63], v[128:131], v[164:167], v[60:63]
	v_mfma_f32_16x16x32_bf16 v[56:59], v[136:139], v[164:167], v[56:59]
	v_mfma_f32_16x16x32_bf16 v[52:55], v[128:131], v[200:203], v[52:55]
	v_mfma_f32_16x16x32_bf16 v[48:51], v[136:139], v[200:203], v[48:51]
	v_mfma_f32_16x16x32_bf16 v[36:39], v[128:131], v[208:211], v[36:39]
	v_mfma_f32_16x16x32_bf16 v[32:35], v[136:139], v[208:211], v[32:35]
	v_mfma_f32_16x16x32_bf16 v[20:23], v[128:131], v[216:219], v[20:23]
	v_mfma_f32_16x16x32_bf16 v[16:19], v[136:139], v[216:219], v[16:19]
	v_mfma_f32_16x16x32_bf16 v[60:63], v[132:135], v[174:177], v[60:63]
	v_mfma_f32_16x16x32_bf16 v[56:59], v[160:163], v[174:177], v[56:59]
	v_mfma_f32_16x16x32_bf16 v[52:55], v[132:135], v[204:207], v[52:55]
	v_mfma_f32_16x16x32_bf16 v[48:51], v[160:163], v[204:207], v[48:51]
	v_mfma_f32_16x16x32_bf16 v[36:39], v[132:135], v[212:215], v[36:39]
	v_mfma_f32_16x16x32_bf16 v[32:35], v[160:163], v[212:215], v[32:35]
	v_mfma_f32_16x16x32_bf16 v[20:23], v[132:135], v[220:223], v[20:23]
	v_mfma_f32_16x16x32_bf16 v[16:19], v[160:163], v[220:223], v[16:19]
	s_barrier
; #define PG8_STAGE(bufoff, gbase, voff) do { _Pragma("unroll") for (int _i = 0; _i < 2; ++_i) \
;         __builtin_amdgcn_global_load_lds((const unsigned*)((const char*)(gbase) + (voff)[_i]), (LAS unsigned*)(lds + (bufoff) + ldsw + _i * 8192), 16, 0, 0); } while (0)
; #define PG8_LDA(dst, b, h) do { _Pragma("unroll") for (int m = 0; m < 4; ++m) _Pragma("unroll") for (int k = 0; k < 2; ++k) dst[m][k] = *(const LAS bf16x8*)(lds + PG8_SA(b, h) + aoff + m * 2048 + k * 1024); } while (0)
; #define PG8_LDB(dst, b, h) do { _Pragma("unroll") for (int n = 0; n < 2; ++n) _Pragma("unroll") for (int k = 0; k < 2; ++k) dst[n][k] = *(const LAS bf16x8*)(lds + PG8_SB(b, h) + boff + n * 2048 + k * 1024); } while (0)
; #define PG8_MMA(ai, bj, At, Bt) do { __builtin_amdgcn_s_setprio(1); _Pragma("unroll") for (int m = 0; m < 4; ++m) _Pragma("unroll") for (int n = 0; n < 2; ++n) _Pragma("unroll") for (int k = 0; k < 2; ++k) \
;         acc[ai][bj][m][n] = __builtin_amdgcn_mfma_f32_16x16x32_bf16(Bt[n][k], At[m][k], acc[ai][bj][m][n], 0, 0, 0); __builtin_amdgcn_s_setprio(0); } while (0)
; #define PG8_WAIT_V(n) asm volatile("s_waitcnt vmcnt(" #n ")" ::: "memory")
; #define PG8_WAIT_L(n) asm volatile("s_waitcnt lgkmcnt(" #n ")" ::: "memory")
; #define PG8_BAR __builtin_amdgcn_s_barrier()
; #define PG8_SCHED __builtin_amdgcn_sched_barrier(0)
; template <class Epi, class Sched>
; __device__ __forceinline__ void gemm_phase(LAS unsigned char* lds, const Gemm g, const Sched& S, const Epi& E) {
;     ...
;             PG8_BAR; PG8_WAIT_L(0); PG8_MMA(1, 0, At, B0); PG8_BAR; PG8_SCHED;
;             PG8_STAGE(PG8_SB(0, 1), b2 + hstep, voffB);
;             PG8_WAIT_V(6); PG8_BAR; PG8_MMA(1, 1, At, B1); PG8_BAR;
;             PG8_LDB(B0, 1, 0); PG8_SCHED; PG8_LDA(At, 1, 0); PG8_STAGE(PG8_SA(0, 1), a2 + hstep, voffA);
;             PG8_WAIT_L(8); PG8_BAR; PG8_WAIT_L(0); PG8_MMA(0, 0, At, B0); PG8_BAR; PG8_SCHED;
;             PG8_LDB(B1, 1, 1); PG8_STAGE(PG8_SB(1, 0), b3, voffB);
;             PG8_BAR; PG8_WAIT_L(0); PG8_MMA(0, 1, At, B1); PG8_BAR;
;             PG8_LDA(At, 1, 1); PG8_STAGE(PG8_SA(1, 0), a3, voffA);
	s_add_u32 s16, s22, 0x160000
	s_addc_u32 s17, s23, 0
	s_add_i32 s54, s55, s29
	v_lshl_add_u64 v[128:129], s[16:17], 0, v[148:149]
	s_mov_b32 m0, s54
	s_nop 0
	global_load_lds_dwordx4 v[128:129], off
	v_lshl_add_u64 v[128:129], s[16:17], 0, v[140:141]
	s_add_i32 m0, s54, 0x2000
	s_nop 0
	global_load_lds_dwordx4 v[128:129], off
	s_waitcnt vmcnt(6)
	s_barrier
	v_mfma_f32_16x16x32_bf16 v[44:47], v[224:227], v[164:167], v[44:47]
	v_mfma_f32_16x16x32_bf16 v[40:43], v[232:235], v[164:167], v[40:43]
	v_mfma_f32_16x16x32_bf16 v[28:31], v[224:227], v[200:203], v[28:31]
	v_mfma_f32_16x16x32_bf16 v[24:27], v[232:235], v[200:203], v[24:27]
	v_mfma_f32_16x16x32_bf16 v[12:15], v[224:227], v[208:211], v[12:15]
	v_mfma_f32_16x16x32_bf16 v[8:11], v[232:235], v[208:211], v[8:11]
	v_mfma_f32_16x16x32_bf16 v[4:7], v[224:227], v[216:219], v[4:7]
	v_mfma_f32_16x16x32_bf16 v[0:3], v[232:235], v[216:219], v[0:3]
	v_mfma_f32_16x16x32_bf16 v[44:47], v[228:231], v[174:177], v[44:47]
	v_mfma_f32_16x16x32_bf16 v[40:43], v[236:239], v[174:177], v[40:43]
	v_mfma_f32_16x16x32_bf16 v[28:31], v[228:231], v[204:207], v[28:31]
	v_mfma_f32_16x16x32_bf16 v[24:27], v[236:239], v[204:207], v[24:27]
	v_mfma_f32_16x16x32_bf16 v[12:15], v[228:231], v[212:215], v[12:15]
	v_mfma_f32_16x16x32_bf16 v[8:11], v[236:239], v[212:215], v[8:11]
	v_mfma_f32_16x16x32_bf16 v[4:7], v[228:231], v[220:223], v[4:7]
	v_mfma_f32_16x16x32_bf16 v[0:3], v[236:239], v[220:223], v[0:3]
	s_add_i32 s54, 0, 0x18000
	v_add_u32_e32 v160, s54, v171
	s_barrier
	ds_read_b128 v[128:131], v160
	ds_read_b128 v[132:135], v160 offset:1024
	ds_read_b128 v[136:139], v160 offset:2048
	ds_read_b128 v[160:163], v160 offset:3072
	s_add_u32 s16, s24, 0x160000
	s_addc_u32 s17, s25, 0
	s_mov_b32 m0, s37
	v_lshl_add_u64 v[224:225], s[16:17], 0, v[148:149]
	ds_read_b128 v[164:167], v173 offset:32768
	ds_read_b128 v[174:177], v173 offset:33792
	ds_read_b128 v[200:203], v173 offset:34816
	ds_read_b128 v[204:207], v173 offset:35840
	ds_read_b128 v[208:211], v173 offset:36864
	ds_read_b128 v[212:215], v173 offset:37888
	ds_read_b128 v[216:219], v173 offset:38912
	ds_read_b128 v[220:223], v173 offset:39936
	global_load_lds_dwordx4 v[224:225], off
	v_lshl_add_u64 v[224:225], s[16:17], 0, v[140:141]
	s_mov_b32 m0, s38
	s_nop 0
	global_load_lds_dwordx4 v[224:225], off
	s_waitcnt lgkmcnt(8)
	s_barrier
	s_waitcnt lgkmcnt(0)
	s_waitcnt lgkmcnt(0)
	v_mfma_f32_16x16x32_bf16 v[124:127], v[128:131], v[164:167], v[124:127]
	v_mfma_f32_16x16x32_bf16 v[120:123], v[136:139], v[164:167], v[120:123]
	v_mfma_f32_16x16x32_bf16 v[116:119], v[128:131], v[200:203], v[116:119]
	v_mfma_f32_16x16x32_bf16 v[112:115], v[136:139], v[200:203], v[112:115]
	v_mfma_f32_16x16x32_bf16 v[100:103], v[128:131], v[208:211], v[100:103]
	v_mfma_f32_16x16x32_bf16 v[96:99], v[136:139], v[208:211], v[96:99]
	v_mfma_f32_16x16x32_bf16 v[84:87], v[128:131], v[216:219], v[84:87]
	v_mfma_f32_16x16x32_bf16 v[80:83], v[136:139], v[216:219], v[80:83]
	v_mfma_f32_16x16x32_bf16 v[124:127], v[132:135], v[174:177], v[124:127]
	v_mfma_f32_16x16x32_bf16 v[120:123], v[160:163], v[174:177], v[120:123]
	v_mfma_f32_16x16x32_bf16 v[116:119], v[132:135], v[204:207], v[116:119]
	v_mfma_f32_16x16x32_bf16 v[112:115], v[160:163], v[204:207], v[112:115]
	v_mfma_f32_16x16x32_bf16 v[100:103], v[132:135], v[212:215], v[100:103]
	v_mfma_f32_16x16x32_bf16 v[96:99], v[160:163], v[212:215], v[96:99]
	v_mfma_f32_16x16x32_bf16 v[84:87], v[132:135], v[220:223], v[84:87]
	v_mfma_f32_16x16x32_bf16 v[80:83], v[160:163], v[220:223], v[80:83]
	s_barrier
	s_add_i32 s24, 0, 0x1c000
	s_add_i32 s16, s54, s29
	v_add_u32_e32 v236, s24, v171
	v_lshl_add_u64 v[146:147], v[146:147], 0, s[18:19]
	s_mov_b32 m0, s16
	ds_read_b128 v[224:227], v236
	ds_read_b128 v[228:231], v236 offset:1024
	ds_read_b128 v[232:235], v236 offset:2048
	ds_read_b128 v[236:239], v236 offset:3072
	global_load_lds_dwordx4 v[146:147], off
	v_lshl_add_u64 v[146:147], v[168:169], 0, s[18:19]
	s_add_i32 m0, s16, 0x2000
	s_nop 0
	global_load_lds_dwordx4 v[146:147], off
	s_barrier
	s_waitcnt lgkmcnt(0)
	s_waitcnt lgkmcnt(0)
	v_mfma_f32_16x16x32_bf16 v[108:111], v[224:227], v[164:167], v[108:111]
	v_mfma_f32_16x16x32_bf16 v[104:107], v[232:235], v[164:167], v[104:107]
	v_mfma_f32_16x16x32_bf16 v[92:95], v[224:227], v[200:203], v[92:95]
	v_mfma_f32_16x16x32_bf16 v[88:91], v[232:235], v[200:203], v[88:91]
	v_mfma_f32_16x16x32_bf16 v[76:79], v[224:227], v[208:211], v[76:79]
	v_mfma_f32_16x16x32_bf16 v[72:75], v[232:235], v[208:211], v[72:75]
	v_mfma_f32_16x16x32_bf16 v[68:71], v[224:227], v[216:219], v[68:71]
	v_mfma_f32_16x16x32_bf16 v[64:67], v[232:235], v[216:219], v[64:67]
	v_mfma_f32_16x16x32_bf16 v[108:111], v[228:231], v[174:177], v[108:111]
	v_mfma_f32_16x16x32_bf16 v[104:107], v[236:239], v[174:177], v[104:107]
	v_mfma_f32_16x16x32_bf16 v[92:95], v[228:231], v[204:207], v[92:95]
	v_mfma_f32_16x16x32_bf16 v[88:91], v[236:239], v[204:207], v[88:91]
	v_mfma_f32_16x16x32_bf16 v[76:79], v[228:231], v[212:215], v[76:79]
	v_mfma_f32_16x16x32_bf16 v[72:75], v[236:239], v[212:215], v[72:75]
	v_mfma_f32_16x16x32_bf16 v[68:71], v[228:231], v[220:223], v[68:71]
	v_mfma_f32_16x16x32_bf16 v[64:67], v[236:239], v[220:223], v[64:67]
	s_mov_b32 m0, s41
	v_lshl_add_u64 v[146:147], v[188:189], 0, s[18:19]
	s_barrier
	ds_read_b128 v[164:167], v173 offset:49152
	ds_read_b128 v[174:177], v173 offset:50176
	ds_read_b128 v[200:203], v173 offset:51200
	ds_read_b128 v[204:207], v173 offset:52224
	ds_read_b128 v[208:211], v173 offset:53248
	ds_read_b128 v[212:215], v173 offset:54272
	ds_read_b128 v[216:219], v173 offset:55296
	ds_read_b128 v[220:223], v173 offset:56320
	global_load_lds_dwordx4 v[146:147], off
	v_lshl_add_u64 v[146:147], v[190:191], 0, s[18:19]
	s_mov_b32 m0, s42
	s_nop 0
	global_load_lds_dwordx4 v[146:147], off
	s_barrier
; #define PG8_STAGE(bufoff, gbase, voff) do { _Pragma("unroll") for (int _i = 0; _i < 2; ++_i) \
;         __builtin_amdgcn_global_load_lds((const unsigned*)((const char*)(gbase) + (voff)[_i]), (LAS unsigned*)(lds + (bufoff) + ldsw + _i * 8192), 16, 0, 0); } while (0)
; #define PG8_LDA(dst, b, h) do { _Pragma("unroll") for (int m = 0; m < 4; ++m) _Pragma("unroll") for (int k = 0; k < 2; ++k) dst[m][k] = *(const LAS bf16x8*)(lds + PG8_SA(b, h) + aoff + m * 2048 + k * 1024); } while (0)
; #define PG8_MMA(ai, bj, At, Bt) do { __builtin_amdgcn_s_setprio(1); _Pragma("unroll") for (int m = 0; m < 4; ++m) _Pragma("unroll") for (int n = 0; n < 2; ++n) _Pragma("unroll") for (int k = 0; k < 2; ++k) \
;         acc[ai][bj][m][n] = __builtin_amdgcn_mfma_f32_16x16x32_bf16(Bt[n][k], At[m][k], acc[ai][bj][m][n], 0, 0, 0); __builtin_amdgcn_s_setprio(0); } while (0)
; #define PG8_WAIT_V(n) asm volatile("s_waitcnt vmcnt(" #n ")" ::: "memory")
; #define PG8_WAIT_L(n) asm volatile("s_waitcnt lgkmcnt(" #n ")" ::: "memory")
; #define PG8_BAR __builtin_amdgcn_s_barrier()
; #define PG8_SCHED __builtin_amdgcn_sched_barrier(0)
;     __device__ __forceinline__ void operator()(const f32x4 (&acc)[2][2][4][2], const Unit& u, int wr, int wc, int fr, int fq) const {
;     ...
;         const float* base = (u.pm < 32) ? base_lo : base_hi;
; #pragma unroll
;         for (int ai = 0; ai < 2; ++ai) {
;             f32x4 bs[4][2][2];
; #pragma unroll
;             for (int m = 0; m < 4; ++m) { const size_t off = (size_t)(row0 + ai * HALF + m * 16) * DM + col0;
; #pragma unroll
;                 for (int bj = 0; bj < 2; ++bj)
; #pragma unroll
;                     for (int n = 0; n < 2; ++n) bs[m][bj][n] = *(const f32x4*)(base + off + bj * HALF + n * 16); }
; template <class Epi, class Sched>
; __device__ __forceinline__ void gemm_phase(LAS unsigned char* lds, const Gemm g, const Sched& S, const Epi& E) {
;     ...
;             PG8_LDA(At, 1, 1); PG8_STAGE(PG8_SA(1, 0), a3, voffA);
;             PG8_BAR; PG8_WAIT_L(0); PG8_MMA(1, 0, At, B0); PG8_BAR; PG8_SCHED;
;             PG8_STAGE(PG8_SB(1, 1), b3 + hstep, voffB);
;             PG8_WAIT_V(6); PG8_BAR; PG8_MMA(1, 1, At, B1); PG8_BAR;
;         }
	s_waitcnt lgkmcnt(0)
	s_waitcnt lgkmcnt(0)
	v_mfma_f32_16x16x32_bf16 v[60:63], v[128:131], v[164:167], v[60:63]
	v_mfma_f32_16x16x32_bf16 v[56:59], v[136:139], v[164:167], v[56:59]
	v_mfma_f32_16x16x32_bf16 v[52:55], v[128:131], v[200:203], v[52:55]
	v_mfma_f32_16x16x32_bf16 v[48:51], v[136:139], v[200:203], v[48:51]
	v_mfma_f32_16x16x32_bf16 v[36:39], v[128:131], v[208:211], v[36:39]
	v_mfma_f32_16x16x32_bf16 v[32:35], v[136:139], v[208:211], v[32:35]
	v_mfma_f32_16x16x32_bf16 v[20:23], v[128:131], v[216:219], v[20:23]
	v_mfma_f32_16x16x32_bf16 v[16:19], v[136:139], v[216:219], v[16:19]
	v_mfma_f32_16x16x32_bf16 v[60:63], v[132:135], v[174:177], v[60:63]
	v_mfma_f32_16x16x32_bf16 v[56:59], v[160:163], v[174:177], v[56:59]
	v_mfma_f32_16x16x32_bf16 v[52:55], v[132:135], v[204:207], v[52:55]
	v_mfma_f32_16x16x32_bf16 v[48:51], v[160:163], v[204:207], v[48:51]
	v_mfma_f32_16x16x32_bf16 v[36:39], v[132:135], v[212:215], v[36:39]
	v_mfma_f32_16x16x32_bf16 v[32:35], v[160:163], v[212:215], v[32:35]
	v_mfma_f32_16x16x32_bf16 v[20:23], v[132:135], v[220:223], v[20:23]
	v_mfma_f32_16x16x32_bf16 v[16:19], v[160:163], v[220:223], v[16:19]
	s_barrier
	s_add_u32 s16, s22, 0x160080
	s_addc_u32 s17, s23, 0
	s_add_i32 s22, s24, s29
	v_lshl_add_u64 v[128:129], s[16:17], 0, v[148:149]
	s_mov_b32 m0, s22
	s_nop 0
	global_load_lds_dwordx4 v[128:129], off
	v_lshl_add_u64 v[128:129], s[16:17], 0, v[140:141]
	s_add_i32 m0, s22, 0x2000
	s_nop 0
	global_load_lds_dwordx4 v[128:129], off
	s_waitcnt vmcnt(6)
	s_barrier
	v_mfma_f32_16x16x32_bf16 v[44:47], v[224:227], v[164:167], v[44:47]
	v_mfma_f32_16x16x32_bf16 v[40:43], v[232:235], v[164:167], v[40:43]
	v_mfma_f32_16x16x32_bf16 v[28:31], v[224:227], v[200:203], v[28:31]
	v_mfma_f32_16x16x32_bf16 v[24:27], v[232:235], v[200:203], v[24:27]
	v_mfma_f32_16x16x32_bf16 v[12:15], v[224:227], v[208:211], v[12:15]
	v_mfma_f32_16x16x32_bf16 v[8:11], v[232:235], v[208:211], v[8:11]
	v_mfma_f32_16x16x32_bf16 v[4:7], v[224:227], v[216:219], v[4:7]
	v_mfma_f32_16x16x32_bf16 v[0:3], v[232:235], v[216:219], v[0:3]
	v_mfma_f32_16x16x32_bf16 v[44:47], v[228:231], v[174:177], v[44:47]
	v_mfma_f32_16x16x32_bf16 v[40:43], v[236:239], v[174:177], v[40:43]
	v_mfma_f32_16x16x32_bf16 v[28:31], v[228:231], v[204:207], v[28:31]
	v_mfma_f32_16x16x32_bf16 v[24:27], v[236:239], v[204:207], v[24:27]
	v_mfma_f32_16x16x32_bf16 v[12:15], v[228:231], v[212:215], v[12:15]
	v_mfma_f32_16x16x32_bf16 v[8:11], v[236:239], v[212:215], v[8:11]
	v_mfma_f32_16x16x32_bf16 v[4:7], v[228:231], v[220:223], v[4:7]
	v_mfma_f32_16x16x32_bf16 v[0:3], v[236:239], v[220:223], v[0:3]
	s_add_u32 s51, s51, 0x100
	s_addc_u32 s52, s52, 0
	s_cmp_ge_i32 s53, s50
	s_mov_b64 s[16:17], s[20:21]
	s_mov_b32 s22, s53
	s_barrier
	s_cbranch_scc0 .LBB0_170
	v_lshl_add_u32 v146, s48, 8, v170
	v_lshl_or_b32 v160, s49, 8, v172
	s_mov_b64 s[16:17], -1
	s_cmp_lt_i32 s82, 0
	v_ashrrev_i32_e32 v161, 31, v160
	v_ashrrev_i32_e32 v147, 31, v146
	s_cbranch_scc0 .LBB0_173
	s_cmp_lt_i32 s48, 32
	s_cselect_b32 s17, s13, s61
	s_cselect_b32 s16, s12, s60
	v_lshlrev_b64 v[162:163], 2, v[160:161]
	v_lshl_add_u64 v[164:165], s[16:17], 0, v[162:163]
	v_lshlrev_b64 v[166:167], 13, v[146:147]
	v_lshl_add_u64 v[128:129], v[164:165], 0, v[166:167]
	global_load_dwordx4 v[174:177], v[128:129], off
	global_load_dwordx4 v[200:203], v[128:129], off offset:64
	global_load_dwordx4 v[204:207], v[128:129], off offset:512
	global_load_dwordx4 v[208:211], v[128:129], off offset:576
	v_or_b32_e32 v128, 16, v146
	v_ashrrev_i32_e32 v129, 31, v128
	v_lshlrev_b64 v[248:249], 13, v[128:129]
	v_lshl_add_u64 v[128:129], v[164:165], 0, v[248:249]
	global_load_dwordx4 v[212:215], v[128:129], off
	global_load_dwordx4 v[216:219], v[128:129], off offset:64
	global_load_dwordx4 v[220:223], v[128:129], off offset:512
	global_load_dwordx4 v[224:227], v[128:129], off offset:576
	v_or_b32_e32 v128, 32, v146
	v_ashrrev_i32_e32 v129, 31, v128
	v_lshlrev_b64 v[188:189], 13, v[128:129]
	v_lshl_add_u64 v[128:129], v[164:165], 0, v[188:189]
	global_load_dwordx4 v[228:231], v[128:129], off
	global_load_dwordx4 v[232:235], v[128:129], off offset:64
	global_load_dwordx4 v[236:239], v[128:129], off offset:512
	global_load_dwordx4 v[240:243], v[128:129], off offset:576
	v_or_b32_e32 v128, 48, v146
	v_ashrrev_i32_e32 v129, 31, v128
	v_lshlrev_b64 v[168:169], 13, v[128:129]
	v_lshl_add_u64 v[128:129], v[164:165], 0, v[168:169]
	global_load_dwordx4 v[244:247], v[128:129], off
	global_load_dwordx4 v[136:139], v[128:129], off offset:64
	global_load_dwordx4 v[132:135], v[128:129], off offset:512
	s_nop 0
	global_load_dwordx4 v[128:131], v[128:129], off offset:576
	v_lshl_add_u64 v[190:191], s[60:61], 0, v[166:167]
	v_lshl_add_u64 v[190:191], v[190:191], 0, v[162:163]
	v_lshl_add_u64 v[188:189], s[60:61], 0, v[188:189]
	v_lshl_add_u64 v[188:189], v[188:189], 0, v[162:163]
	v_lshl_add_u64 v[168:169], s[60:61], 0, v[168:169]
	v_lshl_add_u64 v[168:169], v[168:169], 0, v[162:163]
	s_mov_b64 s[16:17], 0x100000
	s_waitcnt vmcnt(0)
;     __device__ __forceinline__ void operator()(const f32x4 (&acc)[2][2][4][2], const Unit& u, int wr, int wc, int fr, int fq) const {
;     ...
; #pragma unroll
;             for (int m = 0; m < 4; ++m) { const size_t off = (size_t)(row0 + ai * HALF + m * 16) * DM + col0;
; #pragma unroll
;                 for (int bj = 0; bj < 2; ++bj)
; #pragma unroll
;                     for (int n = 0; n < 2; ++n) *(f32x4*)(out + off + bj * HALF + n * 16) = bs[m][bj][n] + scale * acc[ai][bj][m][n]; }
;             asm volatile("" ::: "memory");
	v_pk_fma_f32 v[176:177], v[126:127], 0.5, v[176:177] op_sel_hi:[1,0,1]
	v_pk_fma_f32 v[174:175], v[124:125], 0.5, v[174:175] op_sel_hi:[1,0,1]
	global_store_dwordx4 v[190:191], v[174:177], off
	v_pk_fma_f32 v[138:139], v[82:83], 0.5, v[138:139] op_sel_hi:[1,0,1]
	s_nop 0
	v_pk_fma_f32 v[176:177], v[122:123], 0.5, v[202:203] op_sel_hi:[1,0,1]
	v_pk_fma_f32 v[174:175], v[120:121], 0.5, v[200:201] op_sel_hi:[1,0,1]
	global_store_dwordx4 v[190:191], v[174:177], off offset:64
	v_pk_fma_f32 v[136:137], v[80:81], 0.5, v[136:137] op_sel_hi:[1,0,1]
	v_pk_fma_f32 v[134:135], v[70:71], 0.5, v[134:135] op_sel_hi:[1,0,1]
	v_pk_fma_f32 v[176:177], v[110:111], 0.5, v[206:207] op_sel_hi:[1,0,1]
	v_pk_fma_f32 v[174:175], v[108:109], 0.5, v[204:205] op_sel_hi:[1,0,1]
	global_store_dwordx4 v[190:191], v[174:177], off offset:512
	v_pk_fma_f32 v[132:133], v[68:69], 0.5, v[132:133] op_sel_hi:[1,0,1]
	v_pk_fma_f32 v[130:131], v[66:67], 0.5, v[130:131] op_sel_hi:[1,0,1]
	v_pk_fma_f32 v[176:177], v[106:107], 0.5, v[210:211] op_sel_hi:[1,0,1]
	v_pk_fma_f32 v[174:175], v[104:105], 0.5, v[208:209] op_sel_hi:[1,0,1]
	global_store_dwordx4 v[190:191], v[174:177], off offset:576
	v_lshl_add_u64 v[190:191], s[60:61], 0, v[248:249]
	v_lshl_add_u64 v[190:191], v[190:191], 0, v[162:163]
	v_pk_fma_f32 v[176:177], v[118:119], 0.5, v[214:215] op_sel_hi:[1,0,1]
	v_pk_fma_f32 v[174:175], v[116:117], 0.5, v[212:213] op_sel_hi:[1,0,1]
	global_store_dwordx4 v[190:191], v[174:177], off
	v_pk_fma_f32 v[128:129], v[64:65], 0.5, v[128:129] op_sel_hi:[1,0,1]
	global_store_dwordx4 v[168:169], v[136:139], off offset:64
	v_pk_fma_f32 v[176:177], v[114:115], 0.5, v[218:219] op_sel_hi:[1,0,1]
	v_pk_fma_f32 v[174:175], v[112:113], 0.5, v[216:217] op_sel_hi:[1,0,1]
	global_store_dwordx4 v[190:191], v[174:177], off offset:64
	global_store_dwordx4 v[168:169], v[132:135], off offset:512
	global_store_dwordx4 v[168:169], v[128:131], off offset:576
	v_pk_fma_f32 v[176:177], v[94:95], 0.5, v[222:223] op_sel_hi:[1,0,1]
	v_pk_fma_f32 v[174:175], v[92:93], 0.5, v[220:221] op_sel_hi:[1,0,1]
	global_store_dwordx4 v[190:191], v[174:177], off offset:512
	s_nop 1
	v_pk_fma_f32 v[176:177], v[90:91], 0.5, v[226:227] op_sel_hi:[1,0,1]
	v_pk_fma_f32 v[174:175], v[88:89], 0.5, v[224:225] op_sel_hi:[1,0,1]
	global_store_dwordx4 v[190:191], v[174:177], off offset:576
	s_nop 1
	v_pk_fma_f32 v[176:177], v[102:103], 0.5, v[230:231] op_sel_hi:[1,0,1]
	v_pk_fma_f32 v[174:175], v[100:101], 0.5, v[228:229] op_sel_hi:[1,0,1]
	global_store_dwordx4 v[188:189], v[174:177], off
	s_nop 1
	v_pk_fma_f32 v[176:177], v[98:99], 0.5, v[234:235] op_sel_hi:[1,0,1]
	v_pk_fma_f32 v[174:175], v[96:97], 0.5, v[232:233] op_sel_hi:[1,0,1]
	global_store_dwordx4 v[188:189], v[174:177], off offset:64
	s_nop 1
	v_pk_fma_f32 v[176:177], v[78:79], 0.5, v[238:239] op_sel_hi:[1,0,1]
	v_pk_fma_f32 v[174:175], v[76:77], 0.5, v[236:237] op_sel_hi:[1,0,1]
	global_store_dwordx4 v[188:189], v[174:177], off offset:512
	s_nop 1
	v_pk_fma_f32 v[176:177], v[74:75], 0.5, v[242:243] op_sel_hi:[1,0,1]
	v_pk_fma_f32 v[174:175], v[72:73], 0.5, v[240:241] op_sel_hi:[1,0,1]
	global_store_dwordx4 v[188:189], v[174:177], off offset:576
	s_nop 1
	v_pk_fma_f32 v[176:177], v[86:87], 0.5, v[246:247] op_sel_hi:[1,0,1]
	v_pk_fma_f32 v[174:175], v[84:85], 0.5, v[244:245] op_sel_hi:[1,0,1]
	global_store_dwordx4 v[168:169], v[174:177], off
	v_lshl_add_u64 v[168:169], v[166:167], 0, s[16:17]
	v_lshl_add_u64 v[128:129], v[164:165], 0, v[168:169]
	global_load_dwordx4 v[174:177], v[128:129], off
	global_load_dwordx4 v[200:203], v[128:129], off offset:64
	global_load_dwordx4 v[204:207], v[128:129], off offset:512
	global_load_dwordx4 v[208:211], v[128:129], off offset:576
	s_mov_b64 s[16:17], 0x120000
	v_lshl_add_u64 v[188:189], v[166:167], 0, s[16:17]
	v_lshl_add_u64 v[128:129], v[164:165], 0, v[188:189]
	global_load_dwordx4 v[212:215], v[128:129], off
	global_load_dwordx4 v[216:219], v[128:129], off offset:64
	global_load_dwordx4 v[220:223], v[128:129], off offset:512
	global_load_dwordx4 v[224:227], v[128:129], off offset:576
	s_mov_b64 s[16:17], 0x140000
	v_lshl_add_u64 v[190:191], v[166:167], 0, s[16:17]
	v_lshl_add_u64 v[128:129], v[164:165], 0, v[190:191]
	s_mov_b64 s[16:17], 0x160000
	global_load_dwordx4 v[228:231], v[128:129], off
	global_load_dwordx4 v[232:235], v[128:129], off offset:64
	global_load_dwordx4 v[236:239], v[128:129], off offset:512
	global_load_dwordx4 v[240:243], v[128:129], off offset:576
	v_lshl_add_u64 v[166:167], v[166:167], 0, s[16:17]
	v_lshl_add_u64 v[128:129], v[164:165], 0, v[166:167]
	global_load_dwordx4 v[244:247], v[128:129], off
	global_load_dwordx4 v[136:139], v[128:129], off offset:64
	global_load_dwordx4 v[132:135], v[128:129], off offset:512
	s_nop 0
	global_load_dwordx4 v[128:131], v[128:129], off offset:576
	v_lshl_add_u64 v[164:165], s[60:61], 0, v[168:169]
	v_lshl_add_u64 v[164:165], v[164:165], 0, v[162:163]
	s_mov_b64 s[16:17], 0
	s_waitcnt vmcnt(0)
;     __device__ __forceinline__ void operator()(const f32x4 (&acc)[2][2][4][2], const Unit& u, int wr, int wc, int fr, int fq) const {
;     ...
; #pragma unroll
;             for (int m = 0; m < 4; ++m) { const size_t off = (size_t)(row0 + ai * HALF + m * 16) * DM + col0;
; #pragma unroll
;                 for (int bj = 0; bj < 2; ++bj)
; #pragma unroll
;                     for (int n = 0; n < 2; ++n) *(f32x4*)(out + off + bj * HALF + n * 16) = bs[m][bj][n] + scale * acc[ai][bj][m][n]; }
;             asm volatile("" ::: "memory");
	v_pk_fma_f32 v[176:177], v[62:63], 0.5, v[176:177] op_sel_hi:[1,0,1]
	v_pk_fma_f32 v[174:175], v[60:61], 0.5, v[174:175] op_sel_hi:[1,0,1]
	global_store_dwordx4 v[164:165], v[174:177], off
	v_pk_fma_f32 v[138:139], v[18:19], 0.5, v[138:139] op_sel_hi:[1,0,1]
	s_nop 0
	v_pk_fma_f32 v[176:177], v[58:59], 0.5, v[202:203] op_sel_hi:[1,0,1]
	v_pk_fma_f32 v[174:175], v[56:57], 0.5, v[200:201] op_sel_hi:[1,0,1]
	global_store_dwordx4 v[164:165], v[174:177], off offset:64
	v_pk_fma_f32 v[136:137], v[16:17], 0.5, v[136:137] op_sel_hi:[1,0,1]
	v_pk_fma_f32 v[134:135], v[6:7], 0.5, v[134:135] op_sel_hi:[1,0,1]
	v_pk_fma_f32 v[176:177], v[46:47], 0.5, v[206:207] op_sel_hi:[1,0,1]
	v_pk_fma_f32 v[174:175], v[44:45], 0.5, v[204:205] op_sel_hi:[1,0,1]
	global_store_dwordx4 v[164:165], v[174:177], off offset:512
	v_pk_fma_f32 v[132:133], v[4:5], 0.5, v[132:133] op_sel_hi:[1,0,1]
	v_pk_fma_f32 v[130:131], v[2:3], 0.5, v[130:131] op_sel_hi:[1,0,1]
	v_pk_fma_f32 v[176:177], v[42:43], 0.5, v[210:211] op_sel_hi:[1,0,1]
	v_pk_fma_f32 v[174:175], v[40:41], 0.5, v[208:209] op_sel_hi:[1,0,1]
	global_store_dwordx4 v[164:165], v[174:177], off offset:576
	v_lshl_add_u64 v[164:165], s[60:61], 0, v[188:189]
	v_lshl_add_u64 v[164:165], v[164:165], 0, v[162:163]
	v_pk_fma_f32 v[176:177], v[54:55], 0.5, v[214:215] op_sel_hi:[1,0,1]
	v_pk_fma_f32 v[174:175], v[52:53], 0.5, v[212:213] op_sel_hi:[1,0,1]
	global_store_dwordx4 v[164:165], v[174:177], off
	v_pk_fma_f32 v[128:129], v[0:1], 0.5, v[128:129] op_sel_hi:[1,0,1]
	s_nop 0
	v_pk_fma_f32 v[176:177], v[50:51], 0.5, v[218:219] op_sel_hi:[1,0,1]
	v_pk_fma_f32 v[174:175], v[48:49], 0.5, v[216:217] op_sel_hi:[1,0,1]
	global_store_dwordx4 v[164:165], v[174:177], off offset:64
	s_nop 1
	v_pk_fma_f32 v[176:177], v[30:31], 0.5, v[222:223] op_sel_hi:[1,0,1]
	v_pk_fma_f32 v[174:175], v[28:29], 0.5, v[220:221] op_sel_hi:[1,0,1]
	global_store_dwordx4 v[164:165], v[174:177], off offset:512
	s_nop 1
	v_pk_fma_f32 v[176:177], v[26:27], 0.5, v[226:227] op_sel_hi:[1,0,1]
	v_pk_fma_f32 v[174:175], v[24:25], 0.5, v[224:225] op_sel_hi:[1,0,1]
	global_store_dwordx4 v[164:165], v[174:177], off offset:576
	v_lshl_add_u64 v[164:165], s[60:61], 0, v[190:191]
	v_lshl_add_u64 v[164:165], v[164:165], 0, v[162:163]
	v_pk_fma_f32 v[176:177], v[38:39], 0.5, v[230:231] op_sel_hi:[1,0,1]
	v_pk_fma_f32 v[174:175], v[36:37], 0.5, v[228:229] op_sel_hi:[1,0,1]
	global_store_dwordx4 v[164:165], v[174:177], off
	s_nop 1
	v_pk_fma_f32 v[176:177], v[34:35], 0.5, v[234:235] op_sel_hi:[1,0,1]
	v_pk_fma_f32 v[174:175], v[32:33], 0.5, v[232:233] op_sel_hi:[1,0,1]
	global_store_dwordx4 v[164:165], v[174:177], off offset:64
	s_nop 1
	v_pk_fma_f32 v[176:177], v[14:15], 0.5, v[238:239] op_sel_hi:[1,0,1]
	v_pk_fma_f32 v[174:175], v[12:13], 0.5, v[236:237] op_sel_hi:[1,0,1]
	global_store_dwordx4 v[164:165], v[174:177], off offset:512
	s_nop 1
	v_pk_fma_f32 v[176:177], v[10:11], 0.5, v[242:243] op_sel_hi:[1,0,1]
	v_pk_fma_f32 v[174:175], v[8:9], 0.5, v[240:241] op_sel_hi:[1,0,1]
	global_store_dwordx4 v[164:165], v[174:177], off offset:576
	v_lshl_add_u64 v[164:165], s[60:61], 0, v[166:167]
	v_lshl_add_u64 v[162:163], v[164:165], 0, v[162:163]
	v_pk_fma_f32 v[176:177], v[22:23], 0.5, v[246:247] op_sel_hi:[1,0,1]
	v_pk_fma_f32 v[174:175], v[20:21], 0.5, v[244:245] op_sel_hi:[1,0,1]
	global_store_dwordx4 v[162:163], v[174:177], off
	global_store_dwordx4 v[162:163], v[136:139], off offset:64
	global_store_dwordx4 v[162:163], v[132:135], off offset:512
	global_store_dwordx4 v[162:163], v[128:131], off offset:576

; #define PG8_STAGE(bufoff, gbase, voff) do { _Pragma("unroll") for (int _i = 0; _i < 2; ++_i) \
;         __builtin_amdgcn_global_load_lds((const unsigned*)((const char*)(gbase) + (voff)[_i]), (LAS unsigned*)(lds + (bufoff) + ldsw + _i * 8192), 16, 0, 0); } while (0)
; #define PG8_WAIT_V(n) asm volatile("s_waitcnt vmcnt(" #n ")" ::: "memory")
; #define PG8_BAR __builtin_amdgcn_s_barrier()
; template <class Epi, class Sched>
; __device__ __forceinline__ void gemm_phase(LAS unsigned char* lds, const Gemm g, const Sched& S, const Epi& E) {
;     ...
;     const int wid = __builtin_amdgcn_readfirstlane(tid >> 6), lane = tid & 63, wr = wid >> 2, wc = wid & 3, fr = lane & 15, fq = lane >> 4;
;     const int K = g.K;
;     unsigned voffA[2], voffB[2];
; #pragma unroll
;     for (int i = 0; i < 2; ++i) { int R, C; stage_rc(tid * 16 + i * 8192, R, C); const int Rb = Epi::PERM ? ((R & ~31) + perm32(R & 31)) : R;
;         voffA[i] = (unsigned)(R * K + C) * 2u; voffB[i] = (unsigned)(Rb * K + C) * 2u; }
;     const size_t kstep = (size_t)(BK * 2);
;     const size_t hstep = (size_t)HALF * K * 2;
;     const size_t tstep = 2 * hstep;
;     const unsigned ldsw = (unsigned)wid * 1024u;
;     const int aoff = lds_byte(wr * 64 + fr, fq * 8), boff = lds_byte(wc * 32 + fr, fq * 8);
;     ...
;     Unit cur, nxt; int ui = 0;
;     if (!S.next(0, cur)) return;
;     f32x4 acc[2][2][4][2];
; #pragma unroll
;     for (int a = 0; a < 2; ++a)
; #pragma unroll
;         for (int b = 0; b < 2; ++b)
; #pragma unroll
;             for (int m = 0; m < 4; ++m)
; #pragma unroll
;                 for (int n = 0; n < 2; ++n) acc[a][b][m][n] = (f32x4){0.f, 0.f, 0.f, 0.f};
;     bf16x8 At[4][2], B0[2][2], B1[2][2];
;     const char* cA = (const char*)g.A + (size_t)cur.pm * tstep + (size_t)cur.kt0 * kstep; const char* cB = (const char*)g.Bt + (size_t)cur.pn * tstep + (size_t)cur.kt0 * kstep;
;     PG8_STAGE(PG8_SB(0, 0), cB, voffB); PG8_STAGE(PG8_SA(0, 0), cA, voffA); PG8_STAGE(PG8_SB(0, 1), cB + hstep, voffB); PG8_STAGE(PG8_SA(0, 1), cA + hstep, voffA);
;     if (wr == 1) PG8_BAR;
;     PG8_WAIT_V(4); PG8_BAR;
;     PG8_STAGE(PG8_SB(1, 0), cB + kstep, voffB); PG8_STAGE(PG8_SA(1, 0), cA + kstep, voffA); PG8_STAGE(PG8_SB(1, 1), cB + hstep + kstep, voffB);
;     PG8_WAIT_V(6); PG8_BAR;
.LBB0_205:
	s_nop 0
	v_readlane_b32 s4, v253, 23
	v_readlane_b32 s5, v253, 24
	s_andn2_b64 vcc, exec, s[4:5]
	s_cbranch_vccnz .LBB0_248
	v_readlane_b32 s0, v251, 20
	v_mov_b32_e32 v8, v178
	v_readlane_b32 s1, v251, 21
	s_andn2_b64 vcc, exec, s[0:1]
	v_readfirstlane_b32 s24, v8
	s_cbranch_vccnz .LBB0_218
	v_lshlrev_b32_e32 v0, 4, v8
	v_add_u32_e32 v1, 0x2000, v0
	v_ashrrev_i32_e32 v2, 31, v1
	v_lshrrev_b32_e32 v2, 22, v2
	v_add_u32_e32 v2, v1, v2
	v_ashrrev_i32_e32 v9, 10, v2
	v_mul_i32_i24_e32 v2, 0x400, v9
	v_sub_u32_e32 v1, v1, v2
	v_lshrrev_b32_e32 v2, 4, v1
	v_bitop3_b32 v1, v2, v1, 32 bitop3:0x6c
	v_ashrrev_i32_e32 v2, 31, v1
	v_lshrrev_b32_e32 v2, 26, v2
	v_add_u32_e32 v2, v1, v2
	v_lshlrev_b32_e32 v3, 3, v9
	v_ashrrev_i32_e32 v10, 6, v2
	v_and_b32_e32 v3, -16, v3
	v_add_u32_e32 v3, v10, v3
	v_and_b32_e32 v4, 3, v10
	s_mov_b32 s4, 0xfffe0
	v_lshrrev_b32_e32 v5, 2, v3
	v_lshlrev_b32_e32 v6, 1, v3
	v_and_b32_e32 v2, 0xc0, v2
	v_and_or_b32 v4, v3, s4, v4
	v_and_b32_e32 v5, 4, v5
	v_and_b32_e32 v6, 24, v6
	v_sub_u32_e32 v1, v1, v2
	v_or3_b32 v4, v4, v5, v6
	v_lshlrev_b32_e32 v5, 5, v9
	v_ashrrev_i16_sdwa v1, v183, sext(v1) dst_sel:DWORD dst_unused:UNUSED_PAD src0_sel:DWORD src1_sel:BYTE_0
	v_and_b32_e32 v5, 32, v5
	v_bfe_i32 v11, v1, 0, 16
	v_add_lshl_u32 v1, v5, v11, 1
	v_lshl_add_u32 v128, v4, 12, v1
	v_lshl_add_u32 v130, v3, 12, v1
	v_bfe_i32 v1, v8, 27, 1
	v_lshrrev_b32_e32 v1, 22, v1
	v_add_u32_e32 v1, v0, v1
	v_and_b32_e32 v1, 0xfffffc00, v1
	v_sub_u32_e32 v0, v0, v1
	v_lshrrev_b32_e32 v1, 4, v0
	v_ashrrev_i32_e32 v2, 31, v8
	v_bitop3_b32 v0, v1, v0, 32 bitop3:0x6c
	v_lshrrev_b32_e32 v2, 26, v2
	v_ashrrev_i32_e32 v1, 31, v0
	v_add_u32_e32 v2, v8, v2
	v_lshrrev_b32_e32 v1, 26, v1
	v_ashrrev_i32_e32 v13, 6, v2
	v_readlane_b32 s0, v253, 27
	v_add_u32_e32 v1, v0, v1
	v_lshlrev_b32_e32 v2, 3, v13
	s_cmp_eq_u32 s0, 9
	v_ashrrev_i32_e32 v12, 6, v1
	v_and_b32_e32 v2, -16, v2
	s_cselect_b32 s0, 0x2c00000, 0
	v_add_u32_e32 v2, v12, v2
	s_add_u32 s25, s62, s0
	v_and_b32_e32 v3, 3, v12
	v_lshrrev_b32_e32 v4, 2, v2
	v_lshlrev_b32_e32 v5, 1, v2
	v_and_b32_e32 v1, 0xc0, v1
	s_addc_u32 s27, s63, 0
	s_ashr_i32 s1, s24, 6
	v_and_or_b32 v3, v2, s4, v3
	v_and_b32_e32 v4, 4, v4
	v_and_b32_e32 v5, 24, v5
	v_sub_u32_e32 v0, v0, v1
	s_ashr_i32 s0, s24, 8
	s_lshl_b32 s29, s1, 10
	v_or3_b32 v3, v3, v4, v5
	v_lshlrev_b32_e32 v4, 5, v13
	v_ashrrev_i16_sdwa v0, v183, sext(v0) dst_sel:DWORD dst_unused:UNUSED_PAD src0_sel:DWORD src1_sel:BYTE_0
	v_readlane_b32 s4, v252, 47
	v_and_b32_e32 v4, 32, v4
	v_bfe_i32 v14, v0, 0, 16
	v_readlane_b32 s5, v252, 48
	s_add_u32 s20, s25, s4
	v_add_lshl_u32 v0, v4, v14, 1
	s_addc_u32 s21, s27, s5
	s_add_i32 s30, s29, 0
	v_lshl_add_u32 v148, v3, 12, v0
	s_add_i32 m0, s30, 0x10000
	v_readlane_b32 s4, v252, 58
	global_load_lds_dwordx4 v148, s[20:21]
	s_add_i32 m0, s30, 0x12000
	v_readlane_b32 s6, v253, 15
	v_readlane_b32 s5, v252, 59
	s_add_u32 s16, s6, s4
	v_readlane_b32 s4, v253, 16
	v_lshl_add_u32 v132, v2, 12, v0
	global_load_lds_dwordx4 v128, s[20:21]
	s_addc_u32 s17, s4, s5
	s_mov_b32 m0, s30
	s_add_i32 s31, s30, 0x2000
	global_load_lds_dwordx4 v132, s[16:17]
	s_mov_b32 m0, s31
	s_add_u32 s4, s20, 0x80000
	global_load_lds_dwordx4 v130, s[16:17]
	s_addc_u32 s5, s21, 0
	s_add_i32 m0, s30, 0x14000
	v_mov_b32_e32 v129, v149
	global_load_lds_dwordx4 v148, s[4:5]
	s_add_i32 m0, s30, 0x16000
	v_mov_b32_e32 v133, v149
	global_load_lds_dwordx4 v128, s[4:5]
	s_add_u32 s4, s16, 0x80000
	s_addc_u32 s5, s17, 0
	s_add_i32 s33, s30, 0x4000
	s_mov_b32 m0, s33
	s_add_i32 s34, s30, 0x6000
	global_load_lds_dwordx4 v132, s[4:5]
	s_mov_b32 m0, s34
	v_mov_b32_e32 v131, v149
	global_load_lds_dwordx4 v130, s[4:5]
	v_lshl_add_u64 v[6:7], s[20:21], 0, v[148:149]
	v_lshl_add_u64 v[4:5], s[20:21], 0, v[128:129]
	v_lshl_add_u64 v[2:3], s[16:17], 0, v[132:133]
	s_cmp_lg_u32 s0, 1
	v_lshl_add_u64 v[0:1], s[16:17], 0, v[130:131]
	s_cbranch_scc1 .LBB0_209
	s_barrier
	s_setprio 1

; #define PG8_STAGE(bufoff, gbase, voff) do { _Pragma("unroll") for (int _i = 0; _i < 2; ++_i) \
;         __builtin_amdgcn_global_load_lds((const unsigned*)((const char*)(gbase) + (voff)[_i]), (LAS unsigned*)(lds + (bufoff) + ldsw + _i * 8192), 16, 0, 0); } while (0)
; #define PG8_LDA(dst, b, h) do { _Pragma("unroll") for (int m = 0; m < 4; ++m) _Pragma("unroll") for (int k = 0; k < 2; ++k) dst[m][k] = *(const LAS bf16x8*)(lds + PG8_SA(b, h) + aoff + m * 2048 + k * 1024); } while (0)
; #define PG8_LDB(dst, b, h) do { _Pragma("unroll") for (int n = 0; n < 2; ++n) _Pragma("unroll") for (int k = 0; k < 2; ++k) dst[n][k] = *(const LAS bf16x8*)(lds + PG8_SB(b, h) + boff + n * 2048 + k * 1024); } while (0)
; #define PG8_MMA(ai, bj, At, Bt) do { __builtin_amdgcn_s_setprio(1); _Pragma("unroll") for (int m = 0; m < 4; ++m) _Pragma("unroll") for (int n = 0; n < 2; ++n) _Pragma("unroll") for (int k = 0; k < 2; ++k) \
;         acc[ai][bj][m][n] = __builtin_amdgcn_mfma_f32_16x16x32_bf16(Bt[n][k], At[m][k], acc[ai][bj][m][n], 0, 0, 0); __builtin_amdgcn_s_setprio(0); } while (0)
; #define PG8_WAIT_L(n) asm volatile("s_waitcnt lgkmcnt(" #n ")" ::: "memory")
; #define PG8_BAR __builtin_amdgcn_s_barrier()
; #define PG8_SCHED __builtin_amdgcn_sched_barrier(0)
; template <class Epi, class Sched>
; __device__ __forceinline__ void gemm_phase(LAS unsigned char* lds, const Gemm g, const Sched& S, const Epi& E) {
;     ...
;             PG8_LDB(B0, 0, 0); PG8_SCHED; PG8_LDA(At, 0, 0); PG8_STAGE(PG8_SA(1, 1), a1 + hstep, voffA);
;             PG8_WAIT_L(8); PG8_BAR; PG8_WAIT_L(0); PG8_MMA(0, 0, At, B0); PG8_BAR; PG8_SCHED;
;             PG8_LDB(B1, 0, 1); PG8_STAGE(PG8_SB(0, 0), b2, voffB);
;             PG8_BAR; PG8_WAIT_L(0); PG8_MMA(0, 1, At, B1); PG8_BAR;
;             PG8_LDA(At, 0, 1); PG8_STAGE(PG8_SA(0, 0), a2, voffA);
;             PG8_BAR; PG8_WAIT_L(0); PG8_MMA(1, 0, At, B0); PG8_BAR; PG8_SCHED;
.LBB0_213:
	s_add_u32 s20, s16, 0xfff80080
	s_addc_u32 s21, s17, -1
	s_add_i32 s45, 0, 0x10000
	v_add_u32_e32 v138, s45, v141
	ds_read_b128 v[144:147], v138
	ds_read_b128 v[160:163], v138 offset:1024
	ds_read_b128 v[164:167], v138 offset:2048
	ds_read_b128 v[168:171], v138 offset:3072
	s_cmp_eq_u32 s44, 28
	s_cselect_b32 s23, s11, s21
	s_cselect_b32 s22, s40, s20
	s_cselect_b32 s21, s7, s43
	s_cselect_b32 s20, s41, s42
	v_lshl_add_u64 v[138:139], s[16:17], 0, v[134:135]
	s_add_i32 m0, s30, 0xc000
	ds_read_b128 v[172:175], v143
	ds_read_b128 v[200:203], v143 offset:1024
	ds_read_b128 v[204:207], v143 offset:2048
	ds_read_b128 v[208:211], v143 offset:3072
	ds_read_b128 v[212:215], v143 offset:4096
	ds_read_b128 v[216:219], v143 offset:5120
	ds_read_b128 v[220:223], v143 offset:6144
	ds_read_b128 v[224:227], v143 offset:7168
	global_load_lds_dwordx4 v[138:139], off
	v_lshl_add_u64 v[138:139], s[16:17], 0, v[136:137]
	s_add_i32 m0, s30, 0xe000
	s_nop 0
	global_load_lds_dwordx4 v[138:139], off
	s_waitcnt lgkmcnt(8)
	s_barrier
	s_waitcnt lgkmcnt(0)
	s_waitcnt lgkmcnt(0)
	v_mfma_f32_16x16x32_bf16 v[124:127], v[144:147], v[172:175], v[124:127]
	v_mfma_f32_16x16x32_bf16 v[116:119], v[164:167], v[172:175], v[116:119]
	v_mfma_f32_16x16x32_bf16 v[108:111], v[144:147], v[204:207], v[108:111]
	v_mfma_f32_16x16x32_bf16 v[100:103], v[164:167], v[204:207], v[100:103]
	v_mfma_f32_16x16x32_bf16 v[92:95], v[144:147], v[212:215], v[92:95]
	v_mfma_f32_16x16x32_bf16 v[84:87], v[164:167], v[212:215], v[84:87]
	v_mfma_f32_16x16x32_bf16 v[76:79], v[144:147], v[220:223], v[76:79]
	v_mfma_f32_16x16x32_bf16 v[68:71], v[164:167], v[220:223], v[68:71]
	v_mfma_f32_16x16x32_bf16 v[124:127], v[160:163], v[200:203], v[124:127]
	v_mfma_f32_16x16x32_bf16 v[116:119], v[168:171], v[200:203], v[116:119]
	v_mfma_f32_16x16x32_bf16 v[108:111], v[160:163], v[208:211], v[108:111]
	v_mfma_f32_16x16x32_bf16 v[100:103], v[168:171], v[208:211], v[100:103]
	v_mfma_f32_16x16x32_bf16 v[92:95], v[160:163], v[216:219], v[92:95]
	v_mfma_f32_16x16x32_bf16 v[84:87], v[168:171], v[216:219], v[84:87]
	v_mfma_f32_16x16x32_bf16 v[76:79], v[160:163], v[224:227], v[76:79]
	v_mfma_f32_16x16x32_bf16 v[68:71], v[168:171], v[224:227], v[68:71]
	s_barrier
	s_add_i32 s48, 0, 0x14000
	v_add_u32_e32 v138, s48, v141
	s_add_i32 s45, s45, s29
	ds_read_b128 v[228:231], v138
	ds_read_b128 v[232:235], v138 offset:1024
	ds_read_b128 v[236:239], v138 offset:2048
	ds_read_b128 v[240:243], v138 offset:3072
	v_lshl_add_u64 v[138:139], s[20:21], 0, v[148:149]
	s_mov_b32 m0, s45
	v_lshl_add_u64 v[176:177], s[20:21], 0, v[128:129]
	global_load_lds_dwordx4 v[138:139], off
	s_add_i32 m0, s45, 0x2000
	s_nop 0
	global_load_lds_dwordx4 v[176:177], off
	s_barrier
	s_waitcnt lgkmcnt(0)
	s_waitcnt lgkmcnt(0)
	v_mfma_f32_16x16x32_bf16 v[120:123], v[228:231], v[172:175], v[120:123]
	v_mfma_f32_16x16x32_bf16 v[112:115], v[236:239], v[172:175], v[112:115]
	v_mfma_f32_16x16x32_bf16 v[104:107], v[228:231], v[204:207], v[104:107]
	v_mfma_f32_16x16x32_bf16 v[96:99], v[236:239], v[204:207], v[96:99]
	v_mfma_f32_16x16x32_bf16 v[88:91], v[228:231], v[212:215], v[88:91]
	v_mfma_f32_16x16x32_bf16 v[80:83], v[236:239], v[212:215], v[80:83]
	v_mfma_f32_16x16x32_bf16 v[72:75], v[228:231], v[220:223], v[72:75]
	v_mfma_f32_16x16x32_bf16 v[64:67], v[236:239], v[220:223], v[64:67]
	v_mfma_f32_16x16x32_bf16 v[120:123], v[232:235], v[200:203], v[120:123]
	v_mfma_f32_16x16x32_bf16 v[112:115], v[240:243], v[200:203], v[112:115]
	v_mfma_f32_16x16x32_bf16 v[104:107], v[232:235], v[208:211], v[104:107]
	v_mfma_f32_16x16x32_bf16 v[96:99], v[240:243], v[208:211], v[96:99]
	v_mfma_f32_16x16x32_bf16 v[88:91], v[232:235], v[216:219], v[88:91]
	v_mfma_f32_16x16x32_bf16 v[80:83], v[240:243], v[216:219], v[80:83]
	v_mfma_f32_16x16x32_bf16 v[72:75], v[232:235], v[224:227], v[72:75]
	v_mfma_f32_16x16x32_bf16 v[64:67], v[240:243], v[224:227], v[64:67]
	s_mov_b32 m0, s30
	v_lshl_add_u64 v[244:245], s[22:23], 0, v[132:133]
	s_barrier
	ds_read_b128 v[172:175], v143 offset:16384
	ds_read_b128 v[200:203], v143 offset:17408
	ds_read_b128 v[204:207], v143 offset:18432
	ds_read_b128 v[208:211], v143 offset:19456
	ds_read_b128 v[212:215], v143 offset:20480
	ds_read_b128 v[216:219], v143 offset:21504
	ds_read_b128 v[220:223], v143 offset:22528
	ds_read_b128 v[224:227], v143 offset:23552
	global_load_lds_dwordx4 v[244:245], off
	v_lshl_add_u64 v[246:247], s[22:23], 0, v[130:131]
	s_mov_b32 m0, s31
	s_nop 0
	global_load_lds_dwordx4 v[246:247], off
	s_barrier
	s_waitcnt lgkmcnt(0)
	s_waitcnt lgkmcnt(0)
	v_mfma_f32_16x16x32_bf16 v[60:63], v[144:147], v[172:175], v[60:63]
	v_mfma_f32_16x16x32_bf16 v[52:55], v[164:167], v[172:175], v[52:55]
	v_mfma_f32_16x16x32_bf16 v[44:47], v[144:147], v[204:207], v[44:47]
	v_mfma_f32_16x16x32_bf16 v[36:39], v[164:167], v[204:207], v[36:39]
	v_mfma_f32_16x16x32_bf16 v[28:31], v[144:147], v[212:215], v[28:31]
	v_mfma_f32_16x16x32_bf16 v[20:23], v[164:167], v[212:215], v[20:23]
	v_mfma_f32_16x16x32_bf16 v[12:15], v[144:147], v[220:223], v[12:15]
	v_mfma_f32_16x16x32_bf16 v[4:7], v[164:167], v[220:223], v[4:7]
	v_mfma_f32_16x16x32_bf16 v[60:63], v[160:163], v[200:203], v[60:63]
	v_mfma_f32_16x16x32_bf16 v[52:55], v[168:171], v[200:203], v[52:55]
	v_mfma_f32_16x16x32_bf16 v[44:47], v[160:163], v[208:211], v[44:47]
	v_mfma_f32_16x16x32_bf16 v[36:39], v[168:171], v[208:211], v[36:39]
	v_mfma_f32_16x16x32_bf16 v[28:31], v[160:163], v[216:219], v[28:31]
	v_mfma_f32_16x16x32_bf16 v[20:23], v[168:171], v[216:219], v[20:23]
	v_mfma_f32_16x16x32_bf16 v[12:15], v[160:163], v[224:227], v[12:15]
	v_mfma_f32_16x16x32_bf16 v[4:7], v[168:171], v[224:227], v[4:7]
	s_barrier
; #define PG8_STAGE(bufoff, gbase, voff) do { _Pragma("unroll") for (int _i = 0; _i < 2; ++_i) \
;         __builtin_amdgcn_global_load_lds((const unsigned*)((const char*)(gbase) + (voff)[_i]), (LAS unsigned*)(lds + (bufoff) + ldsw + _i * 8192), 16, 0, 0); } while (0)
; #define PG8_LDA(dst, b, h) do { _Pragma("unroll") for (int m = 0; m < 4; ++m) _Pragma("unroll") for (int k = 0; k < 2; ++k) dst[m][k] = *(const LAS bf16x8*)(lds + PG8_SA(b, h) + aoff + m * 2048 + k * 1024); } while (0)
; #define PG8_LDB(dst, b, h) do { _Pragma("unroll") for (int n = 0; n < 2; ++n) _Pragma("unroll") for (int k = 0; k < 2; ++k) dst[n][k] = *(const LAS bf16x8*)(lds + PG8_SB(b, h) + boff + n * 2048 + k * 1024); } while (0)
; #define PG8_MMA(ai, bj, At, Bt) do { __builtin_amdgcn_s_setprio(1); _Pragma("unroll") for (int m = 0; m < 4; ++m) _Pragma("unroll") for (int n = 0; n < 2; ++n) _Pragma("unroll") for (int k = 0; k < 2; ++k) \
;         acc[ai][bj][m][n] = __builtin_amdgcn_mfma_f32_16x16x32_bf16(Bt[n][k], At[m][k], acc[ai][bj][m][n], 0, 0, 0); __builtin_amdgcn_s_setprio(0); } while (0)
; #define PG8_WAIT_V(n) asm volatile("s_waitcnt vmcnt(" #n ")" ::: "memory")
; #define PG8_WAIT_L(n) asm volatile("s_waitcnt lgkmcnt(" #n ")" ::: "memory")
; #define PG8_BAR __builtin_amdgcn_s_barrier()
; #define PG8_SCHED __builtin_amdgcn_sched_barrier(0)
; template <class Epi, class Sched>
; __device__ __forceinline__ void gemm_phase(LAS unsigned char* lds, const Gemm g, const Sched& S, const Epi& E) {
;     ...
;             PG8_BAR; PG8_WAIT_L(0); PG8_MMA(1, 0, At, B0); PG8_BAR; PG8_SCHED;
;             PG8_STAGE(PG8_SB(0, 1), b2 + hstep, voffB);
;             PG8_WAIT_V(6); PG8_BAR; PG8_MMA(1, 1, At, B1); PG8_BAR;
;             PG8_LDB(B0, 1, 0); PG8_SCHED; PG8_LDA(At, 1, 0); PG8_STAGE(PG8_SA(0, 1), a2 + hstep, voffA);
;             PG8_WAIT_L(8); PG8_BAR; PG8_WAIT_L(0); PG8_MMA(0, 0, At, B0); PG8_BAR; PG8_SCHED;
;             PG8_LDB(B1, 1, 1); PG8_STAGE(PG8_SB(1, 0), b3, voffB);
;             PG8_BAR; PG8_WAIT_L(0); PG8_MMA(0, 1, At, B1); PG8_BAR;
;             PG8_LDA(At, 1, 1); PG8_STAGE(PG8_SA(1, 0), a3, voffA);
	s_add_u32 s46, s20, 0x80000
	s_addc_u32 s47, s21, 0
	s_add_i32 s45, s48, s29
	v_lshl_add_u64 v[144:145], s[46:47], 0, v[148:149]
	s_mov_b32 m0, s45
	s_nop 0
	global_load_lds_dwordx4 v[144:145], off
	v_lshl_add_u64 v[144:145], s[46:47], 0, v[128:129]
	s_add_i32 m0, s45, 0x2000
	s_nop 0
	global_load_lds_dwordx4 v[144:145], off
	s_waitcnt vmcnt(6)
	s_barrier
	v_mfma_f32_16x16x32_bf16 v[56:59], v[228:231], v[172:175], v[56:59]
	v_mfma_f32_16x16x32_bf16 v[48:51], v[236:239], v[172:175], v[48:51]
	v_mfma_f32_16x16x32_bf16 v[40:43], v[228:231], v[204:207], v[40:43]
	v_mfma_f32_16x16x32_bf16 v[32:35], v[236:239], v[204:207], v[32:35]
	v_mfma_f32_16x16x32_bf16 v[24:27], v[228:231], v[212:215], v[24:27]
	v_mfma_f32_16x16x32_bf16 v[16:19], v[236:239], v[212:215], v[16:19]
	v_mfma_f32_16x16x32_bf16 v[8:11], v[228:231], v[220:223], v[8:11]
	v_mfma_f32_16x16x32_bf16 v[0:3], v[236:239], v[220:223], v[0:3]
	v_mfma_f32_16x16x32_bf16 v[56:59], v[232:235], v[200:203], v[56:59]
	v_mfma_f32_16x16x32_bf16 v[48:51], v[240:243], v[200:203], v[48:51]
	v_mfma_f32_16x16x32_bf16 v[40:43], v[232:235], v[208:211], v[40:43]
	v_mfma_f32_16x16x32_bf16 v[32:35], v[240:243], v[208:211], v[32:35]
	v_mfma_f32_16x16x32_bf16 v[24:27], v[232:235], v[216:219], v[24:27]
	v_mfma_f32_16x16x32_bf16 v[16:19], v[240:243], v[216:219], v[16:19]
	v_mfma_f32_16x16x32_bf16 v[8:11], v[232:235], v[224:227], v[8:11]
	v_mfma_f32_16x16x32_bf16 v[0:3], v[240:243], v[224:227], v[0:3]
	s_add_i32 s45, 0, 0x18000
	v_add_u32_e32 v168, s45, v141
	s_barrier
	ds_read_b128 v[144:147], v168
	ds_read_b128 v[160:163], v168 offset:1024
	ds_read_b128 v[164:167], v168 offset:2048
	ds_read_b128 v[168:171], v168 offset:3072
	s_add_u32 s22, s22, 0x80000
	s_addc_u32 s23, s23, 0
	s_mov_b32 m0, s33
	v_lshl_add_u64 v[228:229], s[22:23], 0, v[132:133]
	ds_read_b128 v[172:175], v143 offset:32768
	ds_read_b128 v[200:203], v143 offset:33792
	ds_read_b128 v[204:207], v143 offset:34816
	ds_read_b128 v[208:211], v143 offset:35840
	ds_read_b128 v[212:215], v143 offset:36864
	ds_read_b128 v[216:219], v143 offset:37888
	ds_read_b128 v[220:223], v143 offset:38912
	ds_read_b128 v[224:227], v143 offset:39936
	global_load_lds_dwordx4 v[228:229], off
	v_lshl_add_u64 v[228:229], s[22:23], 0, v[130:131]
	s_mov_b32 m0, s34
	s_nop 0
	global_load_lds_dwordx4 v[228:229], off
	s_waitcnt lgkmcnt(8)
	s_barrier
	s_waitcnt lgkmcnt(0)
	s_waitcnt lgkmcnt(0)
	v_mfma_f32_16x16x32_bf16 v[124:127], v[144:147], v[172:175], v[124:127]
	v_mfma_f32_16x16x32_bf16 v[116:119], v[164:167], v[172:175], v[116:119]
	v_mfma_f32_16x16x32_bf16 v[108:111], v[144:147], v[204:207], v[108:111]
	v_mfma_f32_16x16x32_bf16 v[100:103], v[164:167], v[204:207], v[100:103]
	v_mfma_f32_16x16x32_bf16 v[92:95], v[144:147], v[212:215], v[92:95]
	v_mfma_f32_16x16x32_bf16 v[84:87], v[164:167], v[212:215], v[84:87]
	v_mfma_f32_16x16x32_bf16 v[76:79], v[144:147], v[220:223], v[76:79]
	v_mfma_f32_16x16x32_bf16 v[68:71], v[164:167], v[220:223], v[68:71]
	v_mfma_f32_16x16x32_bf16 v[124:127], v[160:163], v[200:203], v[124:127]
	v_mfma_f32_16x16x32_bf16 v[116:119], v[168:171], v[200:203], v[116:119]
	v_mfma_f32_16x16x32_bf16 v[108:111], v[160:163], v[208:211], v[108:111]
	v_mfma_f32_16x16x32_bf16 v[100:103], v[168:171], v[208:211], v[100:103]
	v_mfma_f32_16x16x32_bf16 v[92:95], v[160:163], v[216:219], v[92:95]
	v_mfma_f32_16x16x32_bf16 v[84:87], v[168:171], v[216:219], v[84:87]
	v_mfma_f32_16x16x32_bf16 v[76:79], v[160:163], v[224:227], v[76:79]
	v_mfma_f32_16x16x32_bf16 v[68:71], v[168:171], v[224:227], v[68:71]
	s_barrier
	s_add_i32 s22, 0, 0x1c000
	s_add_i32 s23, s45, s29
	v_add_u32_e32 v188, s22, v141
	v_lshl_add_u64 v[138:139], v[138:139], 0, s[18:19]
	s_mov_b32 m0, s23
	ds_read_b128 v[228:231], v188
	ds_read_b128 v[232:235], v188 offset:1024
	ds_read_b128 v[236:239], v188 offset:2048
	ds_read_b128 v[240:243], v188 offset:3072
	global_load_lds_dwordx4 v[138:139], off
	v_lshl_add_u64 v[138:139], v[176:177], 0, s[18:19]
	s_add_i32 m0, s23, 0x2000
	s_nop 0
	global_load_lds_dwordx4 v[138:139], off
	s_barrier
	s_waitcnt lgkmcnt(0)
	s_waitcnt lgkmcnt(0)
	v_mfma_f32_16x16x32_bf16 v[120:123], v[228:231], v[172:175], v[120:123]
	v_mfma_f32_16x16x32_bf16 v[112:115], v[236:239], v[172:175], v[112:115]
	v_mfma_f32_16x16x32_bf16 v[104:107], v[228:231], v[204:207], v[104:107]
	v_mfma_f32_16x16x32_bf16 v[96:99], v[236:239], v[204:207], v[96:99]
	v_mfma_f32_16x16x32_bf16 v[88:91], v[228:231], v[212:215], v[88:91]
	v_mfma_f32_16x16x32_bf16 v[80:83], v[236:239], v[212:215], v[80:83]
	v_mfma_f32_16x16x32_bf16 v[72:75], v[228:231], v[220:223], v[72:75]
	v_mfma_f32_16x16x32_bf16 v[64:67], v[236:239], v[220:223], v[64:67]
	v_mfma_f32_16x16x32_bf16 v[120:123], v[232:235], v[200:203], v[120:123]
	v_mfma_f32_16x16x32_bf16 v[112:115], v[240:243], v[200:203], v[112:115]
	v_mfma_f32_16x16x32_bf16 v[104:107], v[232:235], v[208:211], v[104:107]
	v_mfma_f32_16x16x32_bf16 v[96:99], v[240:243], v[208:211], v[96:99]
	v_mfma_f32_16x16x32_bf16 v[88:91], v[232:235], v[216:219], v[88:91]
	v_mfma_f32_16x16x32_bf16 v[80:83], v[240:243], v[216:219], v[80:83]
	v_mfma_f32_16x16x32_bf16 v[72:75], v[232:235], v[224:227], v[72:75]
	v_mfma_f32_16x16x32_bf16 v[64:67], v[240:243], v[224:227], v[64:67]
	s_mov_b32 m0, s35
	v_lshl_add_u64 v[138:139], v[244:245], 0, s[18:19]
	s_barrier
	ds_read_b128 v[172:175], v143 offset:49152
	ds_read_b128 v[200:203], v143 offset:50176
	ds_read_b128 v[204:207], v143 offset:51200
	ds_read_b128 v[208:211], v143 offset:52224
	ds_read_b128 v[212:215], v143 offset:53248
	ds_read_b128 v[216:219], v143 offset:54272
	ds_read_b128 v[220:223], v143 offset:55296
	ds_read_b128 v[224:227], v143 offset:56320
	global_load_lds_dwordx4 v[138:139], off
	v_lshl_add_u64 v[138:139], v[246:247], 0, s[18:19]
	s_mov_b32 m0, s36
	s_nop 0
	global_load_lds_dwordx4 v[138:139], off
	s_barrier
; __device__ __forceinline__ unsigned cvt_pk_bf16(float lo, float hi) { unsigned r; asm("v_cvt_pk_bf16_f32 %0, %1, %2" : "=v"(r) : "v"(lo), "v"(hi)); return r; }
; #define PG8_STAGE(bufoff, gbase, voff) do { _Pragma("unroll") for (int _i = 0; _i < 2; ++_i) \
;         __builtin_amdgcn_global_load_lds((const unsigned*)((const char*)(gbase) + (voff)[_i]), (LAS unsigned*)(lds + (bufoff) + ldsw + _i * 8192), 16, 0, 0); } while (0)
; #define PG8_LDA(dst, b, h) do { _Pragma("unroll") for (int m = 0; m < 4; ++m) _Pragma("unroll") for (int k = 0; k < 2; ++k) dst[m][k] = *(const LAS bf16x8*)(lds + PG8_SA(b, h) + aoff + m * 2048 + k * 1024); } while (0)
; #define PG8_WAIT_V(n) asm volatile("s_waitcnt vmcnt(" #n ")" ::: "memory")
; #define PG8_WAIT_L(n) asm volatile("s_waitcnt lgkmcnt(" #n ")" ::: "memory")
; #define PG8_BAR __builtin_amdgcn_s_barrier()
; #define PG8_SCHED __builtin_amdgcn_sched_barrier(0)
;     __device__ __forceinline__ void operator()(const f32x4 (&acc)[2][2][4][2], const Unit& u, int wr, int wc, int fr, int fq) const {
;         const int row0 = u.pm * BM + wr * 64 + fr, col0 = u.pn * HALF + wc * 32 + 8 * fq;
; #pragma unroll
;         for (int ai = 0; ai < 2; ++ai)
; #pragma unroll
;             for (int m = 0; m < 4; ++m) { bf16_t* rowp = O + (size_t)(row0 + ai * HALF + m * 16) * ldc + col0;
;                 float h[8];
; #pragma unroll
;                 for (int n = 0; n < 2; ++n)
; #pragma unroll
;                     for (int j = 0; j < 4; ++j) { const float g = acc[ai][0][m][n][j], up = acc[ai][1][m][n][j];
;                         const float e = __builtin_amdgcn_exp2f(-1.4426950408889634f * g);
;                         h[n * 4 + j] = g * __builtin_amdgcn_rcpf(1.0f + e) * up; }
;                 u32x4 w; w.x = cvt_pk_bf16(h[0], h[1]); w.y = cvt_pk_bf16(h[2], h[3]); w.z = cvt_pk_bf16(h[4], h[5]); w.w = cvt_pk_bf16(h[6], h[7]);
;                 *(u32x4*)rowp = w; }
; template <class Epi, class Sched>
; __device__ __forceinline__ void gemm_phase(LAS unsigned char* lds, const Gemm g, const Sched& S, const Epi& E) {
;     ...
;             PG8_LDA(At, 1, 1); PG8_STAGE(PG8_SA(1, 0), a3, voffA);
;             PG8_BAR; PG8_WAIT_L(0); PG8_MMA(1, 0, At, B0); PG8_BAR; PG8_SCHED;
;             PG8_STAGE(PG8_SB(1, 1), b3 + hstep, voffB);
;             PG8_WAIT_V(6); PG8_BAR; PG8_MMA(1, 1, At, B1); PG8_BAR;
;         }
	s_waitcnt lgkmcnt(0)
	s_waitcnt lgkmcnt(0)
	v_mfma_f32_16x16x32_bf16 v[60:63], v[144:147], v[172:175], v[60:63]
	v_mfma_f32_16x16x32_bf16 v[52:55], v[164:167], v[172:175], v[52:55]
	v_mfma_f32_16x16x32_bf16 v[44:47], v[144:147], v[204:207], v[44:47]
	v_mfma_f32_16x16x32_bf16 v[36:39], v[164:167], v[204:207], v[36:39]
	v_mfma_f32_16x16x32_bf16 v[28:31], v[144:147], v[212:215], v[28:31]
	v_mfma_f32_16x16x32_bf16 v[20:23], v[164:167], v[212:215], v[20:23]
	v_mfma_f32_16x16x32_bf16 v[12:15], v[144:147], v[220:223], v[12:15]
	v_mfma_f32_16x16x32_bf16 v[4:7], v[164:167], v[220:223], v[4:7]
	v_mfma_f32_16x16x32_bf16 v[60:63], v[160:163], v[200:203], v[60:63]
	v_mfma_f32_16x16x32_bf16 v[52:55], v[168:171], v[200:203], v[52:55]
	v_mfma_f32_16x16x32_bf16 v[44:47], v[160:163], v[208:211], v[44:47]
	v_mfma_f32_16x16x32_bf16 v[36:39], v[168:171], v[208:211], v[36:39]
	v_mfma_f32_16x16x32_bf16 v[28:31], v[160:163], v[216:219], v[28:31]
	v_mfma_f32_16x16x32_bf16 v[20:23], v[168:171], v[216:219], v[20:23]
	v_mfma_f32_16x16x32_bf16 v[12:15], v[160:163], v[224:227], v[12:15]
	v_mfma_f32_16x16x32_bf16 v[4:7], v[168:171], v[224:227], v[4:7]
	s_barrier
	s_add_u32 s20, s20, 0x80080
	s_addc_u32 s21, s21, 0
	s_add_i32 s22, s22, s29
	v_lshl_add_u64 v[138:139], s[20:21], 0, v[148:149]
	s_mov_b32 m0, s22
	s_nop 0
	global_load_lds_dwordx4 v[138:139], off
	v_lshl_add_u64 v[138:139], s[20:21], 0, v[128:129]
	s_add_i32 m0, s22, 0x2000
	s_nop 0
	global_load_lds_dwordx4 v[138:139], off
	s_waitcnt vmcnt(6)
	s_barrier
	v_mfma_f32_16x16x32_bf16 v[56:59], v[228:231], v[172:175], v[56:59]
	v_mfma_f32_16x16x32_bf16 v[48:51], v[236:239], v[172:175], v[48:51]
	v_mfma_f32_16x16x32_bf16 v[40:43], v[228:231], v[204:207], v[40:43]
	v_mfma_f32_16x16x32_bf16 v[32:35], v[236:239], v[204:207], v[32:35]
	v_mfma_f32_16x16x32_bf16 v[24:27], v[228:231], v[212:215], v[24:27]
	v_mfma_f32_16x16x32_bf16 v[16:19], v[236:239], v[212:215], v[16:19]
	v_mfma_f32_16x16x32_bf16 v[8:11], v[228:231], v[220:223], v[8:11]
	v_mfma_f32_16x16x32_bf16 v[0:3], v[236:239], v[220:223], v[0:3]
	v_mfma_f32_16x16x32_bf16 v[56:59], v[232:235], v[200:203], v[56:59]
	v_mfma_f32_16x16x32_bf16 v[48:51], v[240:243], v[200:203], v[48:51]
	v_mfma_f32_16x16x32_bf16 v[40:43], v[232:235], v[208:211], v[40:43]
	v_mfma_f32_16x16x32_bf16 v[32:35], v[240:243], v[208:211], v[32:35]
	v_mfma_f32_16x16x32_bf16 v[24:27], v[232:235], v[216:219], v[24:27]
	v_mfma_f32_16x16x32_bf16 v[16:19], v[240:243], v[216:219], v[16:19]
	v_mfma_f32_16x16x32_bf16 v[8:11], v[232:235], v[224:227], v[8:11]
	v_mfma_f32_16x16x32_bf16 v[0:3], v[240:243], v[224:227], v[0:3]
	s_add_i32 s44, s44, 2
	s_add_u32 s16, s16, 0x100
	s_addc_u32 s17, s17, 0
	s_add_u32 s42, s42, 0x100
	s_addc_u32 s43, s43, 0
	s_cmp_gt_u32 s44, 29
	s_barrier
	s_cbranch_scc0 .LBB0_213
	v_mul_f32_e32 v145, 0xbfb8aa3b, v124
	v_exp_f32_e32 v145, v145
	v_lshl_or_b32 v146, s38, 7, v142
	v_lshl_add_u32 v144, s39, 8, v140
	v_ashrrev_i32_e32 v147, 31, v146
	v_add_f32_e32 v145, 1.0, v145
	v_rcp_f32_e32 v145, v145
	v_mov_b64_e32 v[138:139], s[4:5]
	s_movk_i32 s7, 0x2c00
	v_mad_i64_i32 v[160:161], s[16:17], v144, s7, v[138:139]
	v_mul_f32_e32 v124, v124, v145
	v_mul_f32_e32 v120, v120, v124
	v_mul_f32_e32 v124, 0xbfb8aa3b, v125
	v_exp_f32_e32 v124, v124
	s_and_b64 vcc, exec, s[0:1]
	s_mov_b32 s38, s6
	s_mov_b32 s39, s10
	v_add_f32_e32 v124, 1.0, v124
	v_rcp_f32_e32 v124, v124
	s_mov_b64 s[20:21], s[14:15]
	v_mul_f32_e32 v124, v125, v124
	v_mul_f32_e32 v121, v121, v124
	v_mul_f32_e32 v124, 0xbfb8aa3b, v126
	v_exp_f32_e32 v124, v124
	s_nop 0
	v_add_f32_e32 v124, 1.0, v124
	v_rcp_f32_e32 v124, v124
	s_nop 0
	v_mul_f32_e32 v124, v126, v124
	v_mul_f32_e32 v122, v122, v124
	v_mul_f32_e32 v124, 0xbfb8aa3b, v127
	v_exp_f32_e32 v124, v124
	s_nop 0
	v_add_f32_e32 v124, 1.0, v124
	v_rcp_f32_e32 v124, v124
	s_nop 0
	v_mul_f32_e32 v124, v127, v124
	v_mul_f32_e32 v123, v123, v124
	v_mul_f32_e32 v124, 0xbfb8aa3b, v116
	v_exp_f32_e32 v124, v124
	s_nop 0
	v_add_f32_e32 v124, 1.0, v124
	v_rcp_f32_e32 v124, v124
	s_nop 0
	v_mul_f32_e32 v116, v116, v124
	v_mul_f32_e32 v116, v112, v116
	v_mul_f32_e32 v112, 0xbfb8aa3b, v117
	v_exp_f32_e32 v112, v112
	s_nop 0
	v_add_f32_e32 v112, 1.0, v112
	v_rcp_f32_e32 v112, v112
	s_nop 0
	v_mul_f32_e32 v112, v117, v112
	v_mul_f32_e32 v117, v113, v112
	v_mul_f32_e32 v112, 0xbfb8aa3b, v118
	v_exp_f32_e32 v112, v112
	v_cvt_pk_bf16_f32 v116, v116, v117
	s_nop 0
	v_add_f32_e32 v112, 1.0, v112
	v_rcp_f32_e32 v112, v112
	s_nop 0
	v_mul_f32_e32 v112, v118, v112
	v_mul_f32_e32 v124, v114, v112
	v_mul_f32_e32 v112, 0xbfb8aa3b, v119
	v_exp_f32_e32 v112, v112
	v_cvt_pk_bf16_f32 v114, v120, v121
	s_nop 0
	v_add_f32_e32 v112, 1.0, v112
	v_rcp_f32_e32 v112, v112
	s_nop 0
	v_mul_f32_e32 v112, v119, v112
	v_mul_f32_e32 v125, v115, v112
	v_lshlrev_b64 v[112:113], 1, v[146:147]
	v_lshl_add_u64 v[118:119], v[160:161], 0, v[112:113]
	v_cvt_pk_bf16_f32 v115, v122, v123
	v_cvt_pk_bf16_f32 v117, v124, v125
	global_store_dwordx4 v[118:119], v[114:117], off
	s_nop 1
	v_mul_f32_e32 v116, 0xbfb8aa3b, v108
	v_exp_f32_e32 v116, v116
	v_or_b32_e32 v114, 16, v144
	v_mad_i64_i32 v[114:115], s[16:17], v114, s7, v[138:139]
	v_add_f32_e32 v116, 1.0, v116
	v_rcp_f32_e32 v116, v116
	s_nop 0
	v_mul_f32_e32 v108, v108, v116
	v_mul_f32_e32 v104, v104, v108
	v_mul_f32_e32 v108, 0xbfb8aa3b, v109
	v_exp_f32_e32 v108, v108
	s_nop 0
	v_add_f32_e32 v108, 1.0, v108
	v_rcp_f32_e32 v108, v108
	s_nop 0
	v_mul_f32_e32 v108, v109, v108
	v_mul_f32_e32 v105, v105, v108
	v_mul_f32_e32 v108, 0xbfb8aa3b, v110
	v_exp_f32_e32 v108, v108
	s_nop 0
	v_add_f32_e32 v108, 1.0, v108
	v_rcp_f32_e32 v108, v108
	s_nop 0
	v_mul_f32_e32 v108, v110, v108
; __device__ __forceinline__ unsigned cvt_pk_bf16(float lo, float hi) { unsigned r; asm("v_cvt_pk_bf16_f32 %0, %1, %2" : "=v"(r) : "v"(lo), "v"(hi)); return r; }
;     __device__ __forceinline__ void operator()(const f32x4 (&acc)[2][2][4][2], const Unit& u, int wr, int wc, int fr, int fq) const {
;         const int row0 = u.pm * BM + wr * 64 + fr, col0 = u.pn * HALF + wc * 32 + 8 * fq;
; #pragma unroll
;         for (int ai = 0; ai < 2; ++ai)
; #pragma unroll
;             for (int m = 0; m < 4; ++m) { bf16_t* rowp = O + (size_t)(row0 + ai * HALF + m * 16) * ldc + col0;
;                 float h[8];
; #pragma unroll
;                 for (int n = 0; n < 2; ++n)
; #pragma unroll
;                     for (int j = 0; j < 4; ++j) { const float g = acc[ai][0][m][n][j], up = acc[ai][1][m][n][j];
;                         const float e = __builtin_amdgcn_exp2f(-1.4426950408889634f * g);
;                         h[n * 4 + j] = g * __builtin_amdgcn_rcpf(1.0f + e) * up; }
;                 u32x4 w; w.x = cvt_pk_bf16(h[0], h[1]); w.y = cvt_pk_bf16(h[2], h[3]); w.z = cvt_pk_bf16(h[4], h[5]); w.w = cvt_pk_bf16(h[6], h[7]);
;                 *(u32x4*)rowp = w; }
	v_mul_f32_e32 v106, v106, v108
	v_mul_f32_e32 v108, 0xbfb8aa3b, v111
	v_exp_f32_e32 v108, v108
	s_nop 0
	v_add_f32_e32 v108, 1.0, v108
	v_rcp_f32_e32 v108, v108
	s_nop 0
	v_mul_f32_e32 v108, v111, v108
	v_mul_f32_e32 v107, v107, v108
	v_mul_f32_e32 v108, 0xbfb8aa3b, v100
	v_exp_f32_e32 v108, v108
	s_nop 0
	v_add_f32_e32 v108, 1.0, v108
	v_rcp_f32_e32 v108, v108
	s_nop 0
	v_mul_f32_e32 v100, v100, v108
	v_mul_f32_e32 v108, v96, v100
	v_mul_f32_e32 v96, 0xbfb8aa3b, v101
	v_exp_f32_e32 v96, v96
	s_nop 0
	v_add_f32_e32 v96, 1.0, v96
	v_rcp_f32_e32 v96, v96
	s_nop 0
	v_mul_f32_e32 v96, v101, v96
	v_mul_f32_e32 v109, v97, v96
	v_mul_f32_e32 v96, 0xbfb8aa3b, v102
	v_exp_f32_e32 v96, v96
	v_lshl_add_u64 v[100:101], v[114:115], 0, v[112:113]
	v_cvt_pk_bf16_f32 v97, v106, v107
	v_add_f32_e32 v96, 1.0, v96
	v_rcp_f32_e32 v96, v96
	s_nop 0
	v_mul_f32_e32 v96, v102, v96
	v_mul_f32_e32 v102, v98, v96
	v_mul_f32_e32 v96, 0xbfb8aa3b, v103
	v_exp_f32_e32 v96, v96
	v_cvt_pk_bf16_f32 v98, v108, v109
	s_nop 0
	v_add_f32_e32 v96, 1.0, v96
	v_rcp_f32_e32 v96, v96
	s_nop 0
	v_mul_f32_e32 v96, v103, v96
	v_mul_f32_e32 v99, v99, v96
	v_cvt_pk_bf16_f32 v96, v104, v105
	v_cvt_pk_bf16_f32 v99, v102, v99
	global_store_dwordx4 v[100:101], v[96:99], off
	s_nop 1
	v_mul_f32_e32 v98, 0xbfb8aa3b, v92
	v_exp_f32_e32 v98, v98
	v_or_b32_e32 v96, 32, v144
	v_mad_i64_i32 v[96:97], s[16:17], v96, s7, v[138:139]
	v_add_f32_e32 v98, 1.0, v98
	v_rcp_f32_e32 v98, v98
	s_nop 0
	v_mul_f32_e32 v92, v92, v98
	v_mul_f32_e32 v88, v88, v92
	v_mul_f32_e32 v92, 0xbfb8aa3b, v93
	v_exp_f32_e32 v92, v92
	s_nop 0
	v_add_f32_e32 v92, 1.0, v92
	v_rcp_f32_e32 v92, v92
	s_nop 0
	v_mul_f32_e32 v92, v93, v92
	v_mul_f32_e32 v89, v89, v92
	v_mul_f32_e32 v92, 0xbfb8aa3b, v94
	v_exp_f32_e32 v92, v92
	s_nop 0
	v_add_f32_e32 v92, 1.0, v92
	v_rcp_f32_e32 v92, v92
	s_nop 0
	v_mul_f32_e32 v92, v94, v92
	v_mul_f32_e32 v90, v90, v92
	v_mul_f32_e32 v92, 0xbfb8aa3b, v95
	v_exp_f32_e32 v92, v92
	s_nop 0
	v_add_f32_e32 v92, 1.0, v92
	v_rcp_f32_e32 v92, v92
	s_nop 0
	v_mul_f32_e32 v92, v95, v92
	v_mul_f32_e32 v91, v91, v92
	v_mul_f32_e32 v92, 0xbfb8aa3b, v84
	v_exp_f32_e32 v92, v92
	s_nop 0
	v_add_f32_e32 v92, 1.0, v92
	v_rcp_f32_e32 v92, v92
	s_nop 0
	v_mul_f32_e32 v84, v84, v92
	v_mul_f32_e32 v92, v80, v84
	v_mul_f32_e32 v80, 0xbfb8aa3b, v85
	v_exp_f32_e32 v80, v80
	s_nop 0
	v_add_f32_e32 v80, 1.0, v80
	v_rcp_f32_e32 v80, v80
	s_nop 0
	v_mul_f32_e32 v80, v85, v80
	v_mul_f32_e32 v93, v81, v80
	v_mul_f32_e32 v80, 0xbfb8aa3b, v86
	v_exp_f32_e32 v80, v80
	v_lshl_add_u64 v[84:85], v[96:97], 0, v[112:113]
	v_cvt_pk_bf16_f32 v81, v90, v91
	v_add_f32_e32 v80, 1.0, v80
	v_rcp_f32_e32 v80, v80
	s_nop 0
	v_mul_f32_e32 v80, v86, v80
	v_mul_f32_e32 v86, v82, v80
	v_mul_f32_e32 v80, 0xbfb8aa3b, v87
	v_exp_f32_e32 v80, v80
	v_cvt_pk_bf16_f32 v82, v92, v93
	s_nop 0
	v_add_f32_e32 v80, 1.0, v80
	v_rcp_f32_e32 v80, v80
	s_nop 0
	v_mul_f32_e32 v80, v87, v80
	v_mul_f32_e32 v83, v83, v80
	v_cvt_pk_bf16_f32 v80, v88, v89
	v_cvt_pk_bf16_f32 v83, v86, v83
	global_store_dwordx4 v[84:85], v[80:83], off
	s_nop 1
	v_mul_f32_e32 v82, 0xbfb8aa3b, v76
	v_exp_f32_e32 v82, v82
	v_or_b32_e32 v80, 48, v144
	v_mad_i64_i32 v[80:81], s[16:17], v80, s7, v[138:139]
	v_add_f32_e32 v82, 1.0, v82
	v_rcp_f32_e32 v82, v82
	s_nop 0
	v_mul_f32_e32 v76, v76, v82
	v_mul_f32_e32 v72, v72, v76
	v_mul_f32_e32 v76, 0xbfb8aa3b, v77
	v_exp_f32_e32 v76, v76
	s_nop 0
	v_add_f32_e32 v76, 1.0, v76
	v_rcp_f32_e32 v76, v76
	s_nop 0
	v_mul_f32_e32 v76, v77, v76
	v_mul_f32_e32 v73, v73, v76
	v_mul_f32_e32 v76, 0xbfb8aa3b, v78
	v_exp_f32_e32 v76, v76
	s_nop 0
	v_add_f32_e32 v76, 1.0, v76
	v_rcp_f32_e32 v76, v76
	s_nop 0
	v_mul_f32_e32 v76, v78, v76
	v_mul_f32_e32 v74, v74, v76
	v_mul_f32_e32 v76, 0xbfb8aa3b, v79
	v_exp_f32_e32 v76, v76
	s_nop 0
	v_add_f32_e32 v76, 1.0, v76
	v_rcp_f32_e32 v76, v76
	s_nop 0
	v_mul_f32_e32 v76, v79, v76
	v_mul_f32_e32 v75, v75, v76
	v_mul_f32_e32 v76, 0xbfb8aa3b, v68
	v_exp_f32_e32 v76, v76
	s_nop 0
	v_add_f32_e32 v76, 1.0, v76
	v_rcp_f32_e32 v76, v76
	s_nop 0
	v_mul_f32_e32 v68, v68, v76
	v_mul_f32_e32 v76, v64, v68
	v_mul_f32_e32 v64, 0xbfb8aa3b, v69
	v_exp_f32_e32 v64, v64
	s_nop 0
	v_add_f32_e32 v64, 1.0, v64
	v_rcp_f32_e32 v64, v64
	s_nop 0
	v_mul_f32_e32 v64, v69, v64
	v_mul_f32_e32 v77, v65, v64
	v_mul_f32_e32 v64, 0xbfb8aa3b, v70
	v_exp_f32_e32 v64, v64
	v_lshl_add_u64 v[68:69], v[80:81], 0, v[112:113]
	v_cvt_pk_bf16_f32 v65, v74, v75
	v_add_f32_e32 v64, 1.0, v64
	v_rcp_f32_e32 v64, v64
	s_nop 0
	v_mul_f32_e32 v64, v70, v64
	v_mul_f32_e32 v70, v66, v64
	v_mul_f32_e32 v64, 0xbfb8aa3b, v71
	v_exp_f32_e32 v64, v64
	v_cvt_pk_bf16_f32 v66, v76, v77
	s_nop 0
	v_add_f32_e32 v64, 1.0, v64
	v_rcp_f32_e32 v64, v64
	s_nop 0
	v_mul_f32_e32 v64, v71, v64
	v_mul_f32_e32 v67, v67, v64
	v_cvt_pk_bf16_f32 v64, v72, v73
	v_cvt_pk_bf16_f32 v67, v70, v67
	global_store_dwordx4 v[68:69], v[64:67], off
	s_nop 1
	v_mul_f32_e32 v66, 0xbfb8aa3b, v60
	v_exp_f32_e32 v66, v66
	v_add_u32_e32 v64, 0x80, v144
	v_mad_i64_i32 v[64:65], s[16:17], v64, s7, v[138:139]
	v_add_f32_e32 v66, 1.0, v66
	v_rcp_f32_e32 v66, v66
	s_nop 0
	v_mul_f32_e32 v60, v60, v66
	v_mul_f32_e32 v56, v56, v60
	v_mul_f32_e32 v60, 0xbfb8aa3b, v61
	v_exp_f32_e32 v60, v60
	s_nop 0
	v_add_f32_e32 v60, 1.0, v60
	v_rcp_f32_e32 v60, v60
	s_nop 0
	v_mul_f32_e32 v60, v61, v60
	v_mul_f32_e32 v57, v57, v60
	v_mul_f32_e32 v60, 0xbfb8aa3b, v62
	v_exp_f32_e32 v60, v60
	s_nop 0
	v_add_f32_e32 v60, 1.0, v60
	v_rcp_f32_e32 v60, v60
	s_nop 0
	v_mul_f32_e32 v60, v62, v60
	v_mul_f32_e32 v58, v58, v60
	v_mul_f32_e32 v60, 0xbfb8aa3b, v63
	v_exp_f32_e32 v60, v60
	s_nop 0
	v_add_f32_e32 v60, 1.0, v60
	v_rcp_f32_e32 v60, v60
; __device__ __forceinline__ unsigned cvt_pk_bf16(float lo, float hi) { unsigned r; asm("v_cvt_pk_bf16_f32 %0, %1, %2" : "=v"(r) : "v"(lo), "v"(hi)); return r; }
; #define PG8_WAIT_V(n) asm volatile("s_waitcnt vmcnt(" #n ")" ::: "memory")
; #define PG8_BAR __builtin_amdgcn_s_barrier()
;     __device__ __forceinline__ void operator()(const f32x4 (&acc)[2][2][4][2], const Unit& u, int wr, int wc, int fr, int fq) const {
;         const int row0 = u.pm * BM + wr * 64 + fr, col0 = u.pn * HALF + wc * 32 + 8 * fq;
; #pragma unroll
;         for (int ai = 0; ai < 2; ++ai)
; #pragma unroll
;             for (int m = 0; m < 4; ++m) { bf16_t* rowp = O + (size_t)(row0 + ai * HALF + m * 16) * ldc + col0;
;                 float h[8];
; #pragma unroll
;                 for (int n = 0; n < 2; ++n)
; #pragma unroll
;                     for (int j = 0; j < 4; ++j) { const float g = acc[ai][0][m][n][j], up = acc[ai][1][m][n][j];
;                         const float e = __builtin_amdgcn_exp2f(-1.4426950408889634f * g);
;                         h[n * 4 + j] = g * __builtin_amdgcn_rcpf(1.0f + e) * up; }
;                 u32x4 w; w.x = cvt_pk_bf16(h[0], h[1]); w.y = cvt_pk_bf16(h[2], h[3]); w.z = cvt_pk_bf16(h[4], h[5]); w.w = cvt_pk_bf16(h[6], h[7]);
;                 *(u32x4*)rowp = w; }
; template <class Epi, class Sched>
; __device__ __forceinline__ void gemm_phase(LAS unsigned char* lds, const Gemm g, const Sched& S, const Epi& E) {
;     ...
;         E(acc, cur, wr, wc, fr, fq);
;         if (!has_next) break;
; #pragma unroll
;         for (int a = 0; a < 2; ++a)
; #pragma unroll
;             for (int b = 0; b < 2; ++b)
; #pragma unroll
;                 for (int m = 0; m < 4; ++m)
; #pragma unroll
;                     for (int n = 0; n < 2; ++n) acc[a][b][m][n] = (f32x4){0.f, 0.f, 0.f, 0.f};
;         cur = nxt; cA = nA; cB = nB; ++ui;
;     }
;     PG8_WAIT_V(0);
;     if (wr == 0) PG8_BAR;
	s_nop 0
	v_mul_f32_e32 v60, v63, v60
	v_mul_f32_e32 v59, v59, v60
	v_mul_f32_e32 v60, 0xbfb8aa3b, v52
	v_exp_f32_e32 v60, v60
	s_nop 0
	v_add_f32_e32 v60, 1.0, v60
	v_rcp_f32_e32 v60, v60
	s_nop 0
	v_mul_f32_e32 v52, v52, v60
	v_mul_f32_e32 v60, v48, v52
	v_mul_f32_e32 v48, 0xbfb8aa3b, v53
	v_exp_f32_e32 v48, v48
	s_nop 0
	v_add_f32_e32 v48, 1.0, v48
	v_rcp_f32_e32 v48, v48
	s_nop 0
	v_mul_f32_e32 v48, v53, v48
	v_mul_f32_e32 v61, v49, v48
	v_mul_f32_e32 v48, 0xbfb8aa3b, v54
	v_exp_f32_e32 v48, v48
	v_lshl_add_u64 v[52:53], v[64:65], 0, v[112:113]
	v_cvt_pk_bf16_f32 v49, v58, v59
	v_add_f32_e32 v48, 1.0, v48
	v_rcp_f32_e32 v48, v48
	s_nop 0
	v_mul_f32_e32 v48, v54, v48
	v_mul_f32_e32 v54, v50, v48
	v_mul_f32_e32 v48, 0xbfb8aa3b, v55
	v_exp_f32_e32 v48, v48
	v_cvt_pk_bf16_f32 v50, v60, v61
	s_nop 0
	v_add_f32_e32 v48, 1.0, v48
	v_rcp_f32_e32 v48, v48
	s_nop 0
	v_mul_f32_e32 v48, v55, v48
	v_mul_f32_e32 v51, v51, v48
	v_cvt_pk_bf16_f32 v48, v56, v57
	v_cvt_pk_bf16_f32 v51, v54, v51
	global_store_dwordx4 v[52:53], v[48:51], off
	s_nop 1
	v_mul_f32_e32 v50, 0xbfb8aa3b, v44
	v_exp_f32_e32 v50, v50
	v_add_u32_e32 v48, 0x90, v144
	v_mad_i64_i32 v[48:49], s[16:17], v48, s7, v[138:139]
	v_add_f32_e32 v50, 1.0, v50
	v_rcp_f32_e32 v50, v50
	s_nop 0
	v_mul_f32_e32 v44, v44, v50
	v_mul_f32_e32 v40, v40, v44
	v_mul_f32_e32 v44, 0xbfb8aa3b, v45
	v_exp_f32_e32 v44, v44
	s_nop 0
	v_add_f32_e32 v44, 1.0, v44
	v_rcp_f32_e32 v44, v44
	s_nop 0
	v_mul_f32_e32 v44, v45, v44
	v_mul_f32_e32 v41, v41, v44
	v_mul_f32_e32 v44, 0xbfb8aa3b, v46
	v_exp_f32_e32 v44, v44
	s_nop 0
	v_add_f32_e32 v44, 1.0, v44
	v_rcp_f32_e32 v44, v44
	s_nop 0
	v_mul_f32_e32 v44, v46, v44
	v_mul_f32_e32 v42, v42, v44
	v_mul_f32_e32 v44, 0xbfb8aa3b, v47
	v_exp_f32_e32 v44, v44
	s_nop 0
	v_add_f32_e32 v44, 1.0, v44
	v_rcp_f32_e32 v44, v44
	s_nop 0
	v_mul_f32_e32 v44, v47, v44
	v_mul_f32_e32 v43, v43, v44
	v_mul_f32_e32 v44, 0xbfb8aa3b, v36
	v_exp_f32_e32 v44, v44
	s_nop 0
	v_add_f32_e32 v44, 1.0, v44
	v_rcp_f32_e32 v44, v44
	s_nop 0
	v_mul_f32_e32 v36, v36, v44
	v_mul_f32_e32 v44, v32, v36
	v_mul_f32_e32 v32, 0xbfb8aa3b, v37
	v_exp_f32_e32 v32, v32
	s_nop 0
	v_add_f32_e32 v32, 1.0, v32
	v_rcp_f32_e32 v32, v32
	s_nop 0
	v_mul_f32_e32 v32, v37, v32
	v_mul_f32_e32 v45, v33, v32
	v_mul_f32_e32 v32, 0xbfb8aa3b, v38
	v_exp_f32_e32 v32, v32
	v_lshl_add_u64 v[36:37], v[48:49], 0, v[112:113]
	v_cvt_pk_bf16_f32 v33, v42, v43
	v_add_f32_e32 v32, 1.0, v32
	v_rcp_f32_e32 v32, v32
	s_nop 0
	v_mul_f32_e32 v32, v38, v32
	v_mul_f32_e32 v38, v34, v32
	v_mul_f32_e32 v32, 0xbfb8aa3b, v39
	v_exp_f32_e32 v32, v32
	v_cvt_pk_bf16_f32 v34, v44, v45
	s_nop 0
	v_add_f32_e32 v32, 1.0, v32
	v_rcp_f32_e32 v32, v32
	s_nop 0
	v_mul_f32_e32 v32, v39, v32
	v_mul_f32_e32 v35, v35, v32
	v_cvt_pk_bf16_f32 v32, v40, v41
	v_cvt_pk_bf16_f32 v35, v38, v35
	global_store_dwordx4 v[36:37], v[32:35], off
	s_nop 1
	v_mul_f32_e32 v34, 0xbfb8aa3b, v28
	v_exp_f32_e32 v34, v34
	v_add_u32_e32 v32, 0xa0, v144
	v_mad_i64_i32 v[32:33], s[16:17], v32, s7, v[138:139]
	v_add_f32_e32 v34, 1.0, v34
	v_rcp_f32_e32 v34, v34
	s_nop 0
	v_mul_f32_e32 v28, v28, v34
	v_mul_f32_e32 v24, v24, v28
	v_mul_f32_e32 v28, 0xbfb8aa3b, v29
	v_exp_f32_e32 v28, v28
	s_nop 0
	v_add_f32_e32 v28, 1.0, v28
	v_rcp_f32_e32 v28, v28
	s_nop 0
	v_mul_f32_e32 v28, v29, v28
	v_mul_f32_e32 v25, v25, v28
	v_mul_f32_e32 v28, 0xbfb8aa3b, v30
	v_exp_f32_e32 v28, v28
	s_nop 0
	v_add_f32_e32 v28, 1.0, v28
	v_rcp_f32_e32 v28, v28
	s_nop 0
	v_mul_f32_e32 v28, v30, v28
	v_mul_f32_e32 v26, v26, v28
	v_mul_f32_e32 v28, 0xbfb8aa3b, v31
	v_exp_f32_e32 v28, v28
	s_nop 0
	v_add_f32_e32 v28, 1.0, v28
	v_rcp_f32_e32 v28, v28
	s_nop 0
	v_mul_f32_e32 v28, v31, v28
	v_mul_f32_e32 v27, v27, v28
	v_mul_f32_e32 v28, 0xbfb8aa3b, v20
	v_exp_f32_e32 v28, v28
	s_nop 0
	v_add_f32_e32 v28, 1.0, v28
	v_rcp_f32_e32 v28, v28
	s_nop 0
	v_mul_f32_e32 v20, v20, v28
	v_mul_f32_e32 v28, v16, v20
	v_mul_f32_e32 v16, 0xbfb8aa3b, v21
	v_exp_f32_e32 v16, v16
	s_nop 0
	v_add_f32_e32 v16, 1.0, v16
	v_rcp_f32_e32 v16, v16
	s_nop 0
	v_mul_f32_e32 v16, v21, v16
	v_mul_f32_e32 v29, v17, v16
	v_mul_f32_e32 v16, 0xbfb8aa3b, v22
	v_exp_f32_e32 v16, v16
	v_lshl_add_u64 v[20:21], v[32:33], 0, v[112:113]
	v_cvt_pk_bf16_f32 v17, v26, v27
	v_add_f32_e32 v16, 1.0, v16
	v_rcp_f32_e32 v16, v16
	s_nop 0
	v_mul_f32_e32 v16, v22, v16
	v_mul_f32_e32 v22, v18, v16
	v_mul_f32_e32 v16, 0xbfb8aa3b, v23
	v_exp_f32_e32 v16, v16
	v_cvt_pk_bf16_f32 v18, v28, v29
	s_nop 0
	v_add_f32_e32 v16, 1.0, v16
	v_rcp_f32_e32 v16, v16
	s_nop 0
	v_mul_f32_e32 v16, v23, v16
	v_mul_f32_e32 v19, v19, v16
	v_cvt_pk_bf16_f32 v16, v24, v25
	v_cvt_pk_bf16_f32 v19, v22, v19
	global_store_dwordx4 v[20:21], v[16:19], off
	s_nop 1
	v_mul_f32_e32 v18, 0xbfb8aa3b, v12
	v_exp_f32_e32 v18, v18
	v_add_u32_e32 v16, 0xb0, v144
	v_mad_i64_i32 v[16:17], s[16:17], v16, s7, v[138:139]
	v_add_f32_e32 v18, 1.0, v18
	v_rcp_f32_e32 v18, v18
	s_mov_b64 s[16:17], s[12:13]
	v_mul_f32_e32 v12, v12, v18
	v_mul_f32_e32 v8, v8, v12
	v_mul_f32_e32 v12, 0xbfb8aa3b, v13
	v_exp_f32_e32 v12, v12
	s_nop 0
	v_add_f32_e32 v12, 1.0, v12
	v_rcp_f32_e32 v12, v12
	s_nop 0
	v_mul_f32_e32 v12, v13, v12
	v_mul_f32_e32 v9, v9, v12
	v_mul_f32_e32 v12, 0xbfb8aa3b, v14
	v_exp_f32_e32 v12, v12
	s_nop 0
	v_add_f32_e32 v12, 1.0, v12
	v_rcp_f32_e32 v12, v12
	s_nop 0
	v_mul_f32_e32 v12, v14, v12
	v_mul_f32_e32 v10, v10, v12
	v_mul_f32_e32 v12, 0xbfb8aa3b, v15
	v_exp_f32_e32 v12, v12
	s_nop 0
	v_add_f32_e32 v12, 1.0, v12
	v_rcp_f32_e32 v12, v12
	s_nop 0
	v_mul_f32_e32 v12, v15, v12
	v_mul_f32_e32 v11, v11, v12
	v_mul_f32_e32 v12, 0xbfb8aa3b, v4
	v_exp_f32_e32 v12, v12
	s_nop 0
	v_add_f32_e32 v12, 1.0, v12
	v_rcp_f32_e32 v12, v12
	s_nop 0
	v_mul_f32_e32 v4, v4, v12
	v_mul_f32_e32 v12, v0, v4
	v_mul_f32_e32 v0, 0xbfb8aa3b, v5
	v_exp_f32_e32 v0, v0
	s_nop 0
	v_add_f32_e32 v0, 1.0, v0
	v_rcp_f32_e32 v0, v0
	s_nop 0
	v_mul_f32_e32 v0, v5, v0
	v_mul_f32_e32 v13, v1, v0
	v_mul_f32_e32 v0, 0xbfb8aa3b, v6
	v_exp_f32_e32 v0, v0
	v_lshl_add_u64 v[4:5], v[16:17], 0, v[112:113]
	v_cvt_pk_bf16_f32 v1, v10, v11
	v_add_f32_e32 v0, 1.0, v0
	v_rcp_f32_e32 v0, v0
	s_nop 0
	v_mul_f32_e32 v0, v6, v0
	v_mul_f32_e32 v6, v2, v0
	v_mul_f32_e32 v0, 0xbfb8aa3b, v7
	v_exp_f32_e32 v0, v0
	v_cvt_pk_bf16_f32 v2, v12, v13
	s_nop 0
	v_add_f32_e32 v0, 1.0, v0
	v_rcp_f32_e32 v0, v0
	s_nop 0
	v_mul_f32_e32 v0, v7, v0
	v_mul_f32_e32 v3, v3, v0
	v_cvt_pk_bf16_f32 v0, v8, v9
	v_cvt_pk_bf16_f32 v3, v6, v3
	global_store_dwordx4 v[4:5], v[0:3], off
	s_cbranch_vccz .LBB0_210
	s_waitcnt vmcnt(0)
	s_cmpk_gt_u32 s24, 0xff
	s_cbranch_scc1 .LBB0_217
	s_barrier

; #define PG8_STAGE(bufoff, gbase, voff) do { _Pragma("unroll") for (int _i = 0; _i < 2; ++_i) \
;         __builtin_amdgcn_global_load_lds((const unsigned*)((const char*)(gbase) + (voff)[_i]), (LAS unsigned*)(lds + (bufoff) + ldsw + _i * 8192), 16, 0, 0); } while (0)
; #define PG8_WAIT_V(n) asm volatile("s_waitcnt vmcnt(" #n ")" ::: "memory")
; #define PG8_BAR __builtin_amdgcn_s_barrier()
; template <class Epi, class Sched>
; __device__ __forceinline__ void gemm_phase(LAS unsigned char* lds, const Gemm g, const Sched& S, const Epi& E) {
;     ...
;     const int wid = __builtin_amdgcn_readfirstlane(tid >> 6), lane = tid & 63, wr = wid >> 2, wc = wid & 3, fr = lane & 15, fq = lane >> 4;
;     const int K = g.K;
;     unsigned voffA[2], voffB[2];
; #pragma unroll
;     for (int i = 0; i < 2; ++i) { int R, C; stage_rc(tid * 16 + i * 8192, R, C); const int Rb = Epi::PERM ? ((R & ~31) + perm32(R & 31)) : R;
;         voffA[i] = (unsigned)(R * K + C) * 2u; voffB[i] = (unsigned)(Rb * K + C) * 2u; }
;     const size_t kstep = (size_t)(BK * 2);
;     const size_t hstep = (size_t)HALF * K * 2;
;     const size_t tstep = 2 * hstep;
;     const unsigned ldsw = (unsigned)wid * 1024u;
;     const int aoff = lds_byte(wr * 64 + fr, fq * 8), boff = lds_byte(wc * 32 + fr, fq * 8);
;     ...
;     Unit cur, nxt; int ui = 0;
;     if (!S.next(0, cur)) return;
;     f32x4 acc[2][2][4][2];
; #pragma unroll
;     for (int a = 0; a < 2; ++a)
; #pragma unroll
;         for (int b = 0; b < 2; ++b)
; #pragma unroll
;             for (int m = 0; m < 4; ++m)
; #pragma unroll
;                 for (int n = 0; n < 2; ++n) acc[a][b][m][n] = (f32x4){0.f, 0.f, 0.f, 0.f};
;     bf16x8 At[4][2], B0[2][2], B1[2][2];
;     const char* cA = (const char*)g.A + (size_t)cur.pm * tstep + (size_t)cur.kt0 * kstep; const char* cB = (const char*)g.Bt + (size_t)cur.pn * tstep + (size_t)cur.kt0 * kstep;
;     PG8_STAGE(PG8_SB(0, 0), cB, voffB); PG8_STAGE(PG8_SA(0, 0), cA, voffA); PG8_STAGE(PG8_SB(0, 1), cB + hstep, voffB); PG8_STAGE(PG8_SA(0, 1), cA + hstep, voffA);
;     if (wr == 1) PG8_BAR;
;     PG8_WAIT_V(4); PG8_BAR;
.LBB0_250:
	s_nop 0
	v_readlane_b32 s0, v253, 21
	v_readlane_b32 s1, v253, 22
	s_andn2_b64 vcc, exec, s[0:1]
	s_cbranch_vccnz .LBB0_272
	v_readlane_b32 s0, v251, 15
	v_mov_b32_e32 v16, v178
	v_readlane_b32 s1, v251, 16
	s_andn2_b64 vcc, exec, s[0:1]
	v_readfirstlane_b32 s27, v16
	s_cbranch_vccnz .LBB0_276
	v_lshlrev_b32_e32 v0, 4, v16
	v_add_u32_e32 v1, 0x2000, v0
	v_ashrrev_i32_e32 v2, 31, v1
	v_lshrrev_b32_e32 v2, 22, v2
	v_add_u32_e32 v2, v1, v2
	v_ashrrev_i32_e32 v8, 10, v2
	v_mul_i32_i24_e32 v2, 0x400, v8
	v_sub_u32_e32 v1, v1, v2
	v_lshrrev_b32_e32 v2, 4, v1
	v_bitop3_b32 v1, v2, v1, 32 bitop3:0x6c
	v_ashrrev_i32_e32 v2, 31, v1
	v_lshrrev_b32_e32 v2, 26, v2
	v_add_u32_e32 v2, v1, v2
	v_ashrrev_i32_e32 v9, 6, v2
	v_and_b32_e32 v2, 0xc0, v2
	v_sub_u32_e32 v1, v1, v2
	v_ashrrev_i16_sdwa v1, v183, sext(v1) dst_sel:DWORD dst_unused:UNUSED_PAD src0_sel:DWORD src1_sel:BYTE_0
	v_bfe_i32 v11, v1, 0, 16
	v_bfe_i32 v1, v16, 27, 1
	v_lshrrev_b32_e32 v1, 22, v1
	v_add_u32_e32 v1, v0, v1
	v_and_b32_e32 v1, 0xfffffc00, v1
	v_sub_u32_e32 v0, v0, v1
	s_add_u32 s29, s62, 0x8e00000
	v_lshrrev_b32_e32 v1, 4, v0
	s_addc_u32 s30, s63, 0
	s_ashr_i32 s0, s27, 6
	v_bitop3_b32 v0, v1, v0, 32 bitop3:0x6c
	v_ashrrev_i32_e32 v2, 31, v16
	s_ashr_i32 s1, s27, 8
	s_lshl_b32 s31, s0, 10
	v_lshlrev_b32_e32 v3, 3, v8
	v_ashrrev_i32_e32 v1, 31, v0
	v_lshrrev_b32_e32 v2, 26, v2
	v_readlane_b32 s4, v252, 30
	v_readlane_b32 s6, v253, 15
	v_and_b32_e32 v3, 0xffff0, v3
	v_lshlrev_b32_e32 v4, 5, v8
	v_lshrrev_b32_e32 v1, 26, v1
	v_add_u32_e32 v2, v16, v2
	v_readlane_b32 s5, v252, 31
	s_add_u32 s4, s6, s4
	v_readlane_b32 s6, v253, 16
	v_add_u32_e32 v3, v9, v3
	v_and_b32_e32 v10, 32, v4
	v_add_u32_e32 v1, v0, v1
	v_ashrrev_i32_e32 v13, 6, v2
	s_addc_u32 s5, s6, s5
	v_readlane_b32 s6, v252, 34
	v_lshl_or_b32 v3, v3, 11, v10
	v_ashrrev_i32_e32 v12, 6, v1
	v_lshlrev_b32_e32 v2, 3, v13
	v_and_b32_e32 v1, 0xc0, v1
	v_readlane_b32 s7, v252, 35
	s_add_u32 s6, s29, s6
	v_add_lshl_u32 v160, v3, v11, 1
	v_and_b32_e32 v2, 0xffff0, v2
	v_lshlrev_b32_e32 v3, 5, v13
	v_sub_u32_e32 v0, v0, v1
	s_addc_u32 s7, s30, s7
	v_readlane_b32 s10, v251, 22
	v_add_u32_e32 v2, v12, v2
	v_and_b32_e32 v14, 32, v3
	v_ashrrev_i16_sdwa v0, v183, sext(v0) dst_sel:DWORD dst_unused:UNUSED_PAD src0_sel:DWORD src1_sel:BYTE_0
	v_readlane_b32 s11, v251, 23
	s_add_u32 s20, s6, s10
	v_lshl_or_b32 v2, v2, 11, v14
	v_bfe_i32 v15, v0, 0, 16
	s_addc_u32 s21, s7, s11
	s_add_i32 s33, s31, 0
	v_add_lshl_u32 v148, v2, v15, 1
	s_add_i32 m0, s33, 0x10000
	v_mov_b32_e32 v161, v149
	global_load_lds_dwordx4 v148, s[20:21]
	s_add_i32 m0, s33, 0x12000
	s_add_u32 s16, s4, s10
	global_load_lds_dwordx4 v160, s[20:21]
	s_addc_u32 s17, s5, s11
	s_mov_b32 m0, s33
	s_add_i32 s34, s33, 0x2000
	global_load_lds_dwordx4 v148, s[16:17]
	s_mov_b32 m0, s34
	s_add_u32 s4, s20, 0x80000
	global_load_lds_dwordx4 v160, s[16:17]
	s_addc_u32 s5, s21, 0
	s_add_i32 m0, s33, 0x14000
	v_lshl_add_u64 v[6:7], s[20:21], 0, v[148:149]
	global_load_lds_dwordx4 v148, s[4:5]
	s_add_i32 m0, s33, 0x16000
	v_lshl_add_u64 v[4:5], s[20:21], 0, v[160:161]
	global_load_lds_dwordx4 v160, s[4:5]
	s_add_u32 s4, s16, 0x80000
	s_addc_u32 s5, s17, 0
	s_add_i32 s35, s33, 0x4000
	s_mov_b32 m0, s35
	s_add_i32 s36, s33, 0x6000
	global_load_lds_dwordx4 v148, s[4:5]
	s_mov_b32 m0, s36
	v_lshl_add_u64 v[2:3], s[16:17], 0, v[148:149]
	global_load_lds_dwordx4 v160, s[4:5]
	s_cmp_lg_u32 s1, 1
	v_lshl_add_u64 v[0:1], s[16:17], 0, v[160:161]
	s_cbranch_scc1 .LBB0_254
	s_barrier
	s_setprio 1

; #define PG8_STAGE(bufoff, gbase, voff) do { _Pragma("unroll") for (int _i = 0; _i < 2; ++_i) \
;         __builtin_amdgcn_global_load_lds((const unsigned*)((const char*)(gbase) + (voff)[_i]), (LAS unsigned*)(lds + (bufoff) + ldsw + _i * 8192), 16, 0, 0); } while (0)
; #define PG8_LDA(dst, b, h) do { _Pragma("unroll") for (int m = 0; m < 4; ++m) _Pragma("unroll") for (int k = 0; k < 2; ++k) dst[m][k] = *(const LAS bf16x8*)(lds + PG8_SA(b, h) + aoff + m * 2048 + k * 1024); } while (0)
; #define PG8_LDB(dst, b, h) do { _Pragma("unroll") for (int n = 0; n < 2; ++n) _Pragma("unroll") for (int k = 0; k < 2; ++k) dst[n][k] = *(const LAS bf16x8*)(lds + PG8_SB(b, h) + boff + n * 2048 + k * 1024); } while (0)
; #define PG8_MMA(ai, bj, At, Bt) do { __builtin_amdgcn_s_setprio(1); _Pragma("unroll") for (int m = 0; m < 4; ++m) _Pragma("unroll") for (int n = 0; n < 2; ++n) _Pragma("unroll") for (int k = 0; k < 2; ++k) \
;         acc[ai][bj][m][n] = __builtin_amdgcn_mfma_f32_16x16x32_bf16(Bt[n][k], At[m][k], acc[ai][bj][m][n], 0, 0, 0); __builtin_amdgcn_s_setprio(0); } while (0)
; #define PG8_WAIT_L(n) asm volatile("s_waitcnt lgkmcnt(" #n ")" ::: "memory")
; #define PG8_BAR __builtin_amdgcn_s_barrier()
; #define PG8_SCHED __builtin_amdgcn_sched_barrier(0)
; template <class Epi, class Sched>
; __device__ __forceinline__ void gemm_phase(LAS unsigned char* lds, const Gemm g, const Sched& S, const Epi& E) {
;     ...
;             PG8_LDB(B0, 0, 0); PG8_SCHED; PG8_LDA(At, 0, 0); PG8_STAGE(PG8_SA(1, 1), a1 + hstep, voffA);
;             PG8_WAIT_L(8); PG8_BAR; PG8_WAIT_L(0); PG8_MMA(0, 0, At, B0); PG8_BAR; PG8_SCHED;
;             PG8_LDB(B1, 0, 1); PG8_STAGE(PG8_SB(0, 0), b2, voffB);
;             PG8_BAR; PG8_WAIT_L(0); PG8_MMA(0, 1, At, B1); PG8_BAR;
;             PG8_LDA(At, 0, 1); PG8_STAGE(PG8_SA(0, 0), a2, voffA);
;             PG8_BAR; PG8_WAIT_L(0); PG8_MMA(1, 0, At, B0); PG8_BAR; PG8_SCHED;
.LBB0_267:
	s_add_i32 s47, s22, 2
	s_add_u32 s20, s16, 0x100
	s_addc_u32 s21, s17, 0
	s_add_i32 s48, 0, 0x10000
	v_add_u32_e32 v140, s48, v201
	ds_read_b128 v[128:131], v140
	ds_read_b128 v[132:135], v140 offset:1024
	ds_read_b128 v[136:139], v140 offset:2048
	ds_read_b128 v[140:143], v140 offset:3072
	s_cmp_eq_u32 s11, s22
	s_cselect_b32 s22, s4, s13
	s_cselect_b32 s25, s7, s21
	s_cselect_b32 s24, s6, s20
	s_cselect_b32 s23, s5, s15
	v_lshl_add_u64 v[188:189], s[16:17], 0, v[162:163]
	s_add_i32 m0, s33, 0xc000
	ds_read_b128 v[144:147], v203
	ds_read_b128 v[166:169], v203 offset:1024
	ds_read_b128 v[170:173], v203 offset:2048
	ds_read_b128 v[174:177], v203 offset:3072
	ds_read_b128 v[204:207], v203 offset:4096
	ds_read_b128 v[208:211], v203 offset:5120
	ds_read_b128 v[212:215], v203 offset:6144
	ds_read_b128 v[216:219], v203 offset:7168
	global_load_lds_dwordx4 v[188:189], off
	v_lshl_add_u64 v[188:189], s[16:17], 0, v[164:165]
	s_add_i32 m0, s33, 0xe000
	s_nop 0
	global_load_lds_dwordx4 v[188:189], off
	s_waitcnt lgkmcnt(8)
	s_barrier
	s_waitcnt lgkmcnt(0)
	s_waitcnt lgkmcnt(0)
	v_mfma_f32_16x16x32_bf16 v[124:127], v[128:131], v[144:147], v[124:127]
	v_mfma_f32_16x16x32_bf16 v[120:123], v[136:139], v[144:147], v[120:123]
	v_mfma_f32_16x16x32_bf16 v[116:119], v[128:131], v[170:173], v[116:119]
	v_mfma_f32_16x16x32_bf16 v[112:115], v[136:139], v[170:173], v[112:115]
	v_mfma_f32_16x16x32_bf16 v[100:103], v[128:131], v[204:207], v[100:103]
	v_mfma_f32_16x16x32_bf16 v[96:99], v[136:139], v[204:207], v[96:99]
	v_mfma_f32_16x16x32_bf16 v[84:87], v[128:131], v[212:215], v[84:87]
	v_mfma_f32_16x16x32_bf16 v[80:83], v[136:139], v[212:215], v[80:83]
	v_mfma_f32_16x16x32_bf16 v[124:127], v[132:135], v[166:169], v[124:127]
	v_mfma_f32_16x16x32_bf16 v[120:123], v[140:143], v[166:169], v[120:123]
	v_mfma_f32_16x16x32_bf16 v[116:119], v[132:135], v[174:177], v[116:119]
	v_mfma_f32_16x16x32_bf16 v[112:115], v[140:143], v[174:177], v[112:115]
	v_mfma_f32_16x16x32_bf16 v[100:103], v[132:135], v[208:211], v[100:103]
	v_mfma_f32_16x16x32_bf16 v[96:99], v[140:143], v[208:211], v[96:99]
	v_mfma_f32_16x16x32_bf16 v[84:87], v[132:135], v[216:219], v[84:87]
	v_mfma_f32_16x16x32_bf16 v[80:83], v[140:143], v[216:219], v[80:83]
	s_barrier
	s_add_i32 s49, 0, 0x14000
	v_add_u32_e32 v188, s49, v201
	s_add_i32 s16, s48, s31
	ds_read_b128 v[220:223], v188
	ds_read_b128 v[224:227], v188 offset:1024
	ds_read_b128 v[228:231], v188 offset:2048
	ds_read_b128 v[232:235], v188 offset:3072
	v_lshl_add_u64 v[188:189], s[22:23], 0, v[148:149]
	s_mov_b32 m0, s16
	v_lshl_add_u64 v[190:191], s[22:23], 0, v[160:161]
	global_load_lds_dwordx4 v[188:189], off
	s_add_i32 m0, s16, 0x2000
	s_nop 0
	global_load_lds_dwordx4 v[190:191], off
	s_barrier
	s_waitcnt lgkmcnt(0)
	s_waitcnt lgkmcnt(0)
	v_mfma_f32_16x16x32_bf16 v[108:111], v[220:223], v[144:147], v[108:111]
	v_mfma_f32_16x16x32_bf16 v[104:107], v[228:231], v[144:147], v[104:107]
	v_mfma_f32_16x16x32_bf16 v[92:95], v[220:223], v[170:173], v[92:95]
	v_mfma_f32_16x16x32_bf16 v[88:91], v[228:231], v[170:173], v[88:91]
	v_mfma_f32_16x16x32_bf16 v[76:79], v[220:223], v[204:207], v[76:79]
	v_mfma_f32_16x16x32_bf16 v[72:75], v[228:231], v[204:207], v[72:75]
	v_mfma_f32_16x16x32_bf16 v[68:71], v[220:223], v[212:215], v[68:71]
	v_mfma_f32_16x16x32_bf16 v[64:67], v[228:231], v[212:215], v[64:67]
	v_mfma_f32_16x16x32_bf16 v[108:111], v[224:227], v[166:169], v[108:111]
	v_mfma_f32_16x16x32_bf16 v[104:107], v[232:235], v[166:169], v[104:107]
	v_mfma_f32_16x16x32_bf16 v[92:95], v[224:227], v[174:177], v[92:95]
	v_mfma_f32_16x16x32_bf16 v[88:91], v[232:235], v[174:177], v[88:91]
	v_mfma_f32_16x16x32_bf16 v[76:79], v[224:227], v[208:211], v[76:79]
	v_mfma_f32_16x16x32_bf16 v[72:75], v[232:235], v[208:211], v[72:75]
	v_mfma_f32_16x16x32_bf16 v[68:71], v[224:227], v[216:219], v[68:71]
	v_mfma_f32_16x16x32_bf16 v[64:67], v[232:235], v[216:219], v[64:67]
	s_mov_b32 m0, s33
	v_lshl_add_u64 v[236:237], s[24:25], 0, v[148:149]
	s_barrier
	ds_read_b128 v[144:147], v203 offset:16384
	ds_read_b128 v[166:169], v203 offset:17408
	ds_read_b128 v[170:173], v203 offset:18432
	ds_read_b128 v[174:177], v203 offset:19456
	ds_read_b128 v[204:207], v203 offset:20480
	ds_read_b128 v[208:211], v203 offset:21504
	ds_read_b128 v[212:215], v203 offset:22528
	ds_read_b128 v[216:219], v203 offset:23552
	global_load_lds_dwordx4 v[236:237], off
	v_lshl_add_u64 v[238:239], s[24:25], 0, v[160:161]
	s_mov_b32 m0, s34
	s_nop 0
	global_load_lds_dwordx4 v[238:239], off
	s_barrier
	s_waitcnt lgkmcnt(0)
	s_waitcnt lgkmcnt(0)
	v_mfma_f32_16x16x32_bf16 v[60:63], v[128:131], v[144:147], v[60:63]
	v_mfma_f32_16x16x32_bf16 v[56:59], v[136:139], v[144:147], v[56:59]
	v_mfma_f32_16x16x32_bf16 v[52:55], v[128:131], v[170:173], v[52:55]
	v_mfma_f32_16x16x32_bf16 v[48:51], v[136:139], v[170:173], v[48:51]
	v_mfma_f32_16x16x32_bf16 v[36:39], v[128:131], v[204:207], v[36:39]
	v_mfma_f32_16x16x32_bf16 v[32:35], v[136:139], v[204:207], v[32:35]
	v_mfma_f32_16x16x32_bf16 v[20:23], v[128:131], v[212:215], v[20:23]
	v_mfma_f32_16x16x32_bf16 v[16:19], v[136:139], v[212:215], v[16:19]
	v_mfma_f32_16x16x32_bf16 v[60:63], v[132:135], v[166:169], v[60:63]
	v_mfma_f32_16x16x32_bf16 v[56:59], v[140:143], v[166:169], v[56:59]
	v_mfma_f32_16x16x32_bf16 v[52:55], v[132:135], v[174:177], v[52:55]
	v_mfma_f32_16x16x32_bf16 v[48:51], v[140:143], v[174:177], v[48:51]
	v_mfma_f32_16x16x32_bf16 v[36:39], v[132:135], v[208:211], v[36:39]
	v_mfma_f32_16x16x32_bf16 v[32:35], v[140:143], v[208:211], v[32:35]
	v_mfma_f32_16x16x32_bf16 v[20:23], v[132:135], v[216:219], v[20:23]
	v_mfma_f32_16x16x32_bf16 v[16:19], v[140:143], v[216:219], v[16:19]
	s_barrier
; #define PG8_STAGE(bufoff, gbase, voff) do { _Pragma("unroll") for (int _i = 0; _i < 2; ++_i) \
;         __builtin_amdgcn_global_load_lds((const unsigned*)((const char*)(gbase) + (voff)[_i]), (LAS unsigned*)(lds + (bufoff) + ldsw + _i * 8192), 16, 0, 0); } while (0)
; #define PG8_LDA(dst, b, h) do { _Pragma("unroll") for (int m = 0; m < 4; ++m) _Pragma("unroll") for (int k = 0; k < 2; ++k) dst[m][k] = *(const LAS bf16x8*)(lds + PG8_SA(b, h) + aoff + m * 2048 + k * 1024); } while (0)
; #define PG8_LDB(dst, b, h) do { _Pragma("unroll") for (int n = 0; n < 2; ++n) _Pragma("unroll") for (int k = 0; k < 2; ++k) dst[n][k] = *(const LAS bf16x8*)(lds + PG8_SB(b, h) + boff + n * 2048 + k * 1024); } while (0)
; #define PG8_MMA(ai, bj, At, Bt) do { __builtin_amdgcn_s_setprio(1); _Pragma("unroll") for (int m = 0; m < 4; ++m) _Pragma("unroll") for (int n = 0; n < 2; ++n) _Pragma("unroll") for (int k = 0; k < 2; ++k) \
;         acc[ai][bj][m][n] = __builtin_amdgcn_mfma_f32_16x16x32_bf16(Bt[n][k], At[m][k], acc[ai][bj][m][n], 0, 0, 0); __builtin_amdgcn_s_setprio(0); } while (0)
; #define PG8_WAIT_V(n) asm volatile("s_waitcnt vmcnt(" #n ")" ::: "memory")
; #define PG8_WAIT_L(n) asm volatile("s_waitcnt lgkmcnt(" #n ")" ::: "memory")
; #define PG8_BAR __builtin_amdgcn_s_barrier()
; #define PG8_SCHED __builtin_amdgcn_sched_barrier(0)
; template <class Epi, class Sched>
; __device__ __forceinline__ void gemm_phase(LAS unsigned char* lds, const Gemm g, const Sched& S, const Epi& E) {
;     ...
;             PG8_STAGE(PG8_SB(0, 1), b2 + hstep, voffB);
;             PG8_WAIT_V(6); PG8_BAR; PG8_MMA(1, 1, At, B1); PG8_BAR;
;             PG8_LDB(B0, 1, 0); PG8_SCHED; PG8_LDA(At, 1, 0); PG8_STAGE(PG8_SA(0, 1), a2 + hstep, voffA);
;             PG8_WAIT_L(8); PG8_BAR; PG8_WAIT_L(0); PG8_MMA(0, 0, At, B0); PG8_BAR; PG8_SCHED;
;             PG8_LDB(B1, 1, 1); PG8_STAGE(PG8_SB(1, 0), b3, voffB);
;             PG8_BAR; PG8_WAIT_L(0); PG8_MMA(0, 1, At, B1); PG8_BAR;
;             PG8_LDA(At, 1, 1); PG8_STAGE(PG8_SA(1, 0), a3, voffA);
;             PG8_BAR; PG8_WAIT_L(0); PG8_MMA(1, 0, At, B0); PG8_BAR; PG8_SCHED;
	s_add_u32 s16, s22, 0x80000
	s_addc_u32 s17, s23, 0
	s_add_i32 s48, s49, s31
	v_lshl_add_u64 v[128:129], s[16:17], 0, v[148:149]
	s_mov_b32 m0, s48
	s_nop 0
	global_load_lds_dwordx4 v[128:129], off
	v_lshl_add_u64 v[128:129], s[16:17], 0, v[160:161]
	s_add_i32 m0, s48, 0x2000
	s_nop 0
	global_load_lds_dwordx4 v[128:129], off
	s_waitcnt vmcnt(6)
	s_barrier
	v_mfma_f32_16x16x32_bf16 v[44:47], v[220:223], v[144:147], v[44:47]
	v_mfma_f32_16x16x32_bf16 v[40:43], v[228:231], v[144:147], v[40:43]
	v_mfma_f32_16x16x32_bf16 v[28:31], v[220:223], v[170:173], v[28:31]
	v_mfma_f32_16x16x32_bf16 v[24:27], v[228:231], v[170:173], v[24:27]
	v_mfma_f32_16x16x32_bf16 v[12:15], v[220:223], v[204:207], v[12:15]
	v_mfma_f32_16x16x32_bf16 v[8:11], v[228:231], v[204:207], v[8:11]
	v_mfma_f32_16x16x32_bf16 v[4:7], v[220:223], v[212:215], v[4:7]
	v_mfma_f32_16x16x32_bf16 v[0:3], v[228:231], v[212:215], v[0:3]
	v_mfma_f32_16x16x32_bf16 v[44:47], v[224:227], v[166:169], v[44:47]
	v_mfma_f32_16x16x32_bf16 v[40:43], v[232:235], v[166:169], v[40:43]
	v_mfma_f32_16x16x32_bf16 v[28:31], v[224:227], v[174:177], v[28:31]
	v_mfma_f32_16x16x32_bf16 v[24:27], v[232:235], v[174:177], v[24:27]
	v_mfma_f32_16x16x32_bf16 v[12:15], v[224:227], v[208:211], v[12:15]
	v_mfma_f32_16x16x32_bf16 v[8:11], v[232:235], v[208:211], v[8:11]
	v_mfma_f32_16x16x32_bf16 v[4:7], v[224:227], v[216:219], v[4:7]
	v_mfma_f32_16x16x32_bf16 v[0:3], v[232:235], v[216:219], v[0:3]
	s_add_i32 s48, 0, 0x18000
	v_add_u32_e32 v140, s48, v201
	s_barrier
	ds_read_b128 v[128:131], v140
	ds_read_b128 v[132:135], v140 offset:1024
	ds_read_b128 v[136:139], v140 offset:2048
	ds_read_b128 v[140:143], v140 offset:3072
	s_add_u32 s16, s24, 0x80000
	s_addc_u32 s17, s25, 0
	s_mov_b32 m0, s35
	v_lshl_add_u64 v[220:221], s[16:17], 0, v[148:149]
	ds_read_b128 v[144:147], v203 offset:32768
	ds_read_b128 v[166:169], v203 offset:33792
	ds_read_b128 v[170:173], v203 offset:34816
	ds_read_b128 v[174:177], v203 offset:35840
	ds_read_b128 v[204:207], v203 offset:36864
	ds_read_b128 v[208:211], v203 offset:37888
	ds_read_b128 v[212:215], v203 offset:38912
	ds_read_b128 v[216:219], v203 offset:39936
	global_load_lds_dwordx4 v[220:221], off
	v_lshl_add_u64 v[220:221], s[16:17], 0, v[160:161]
	s_mov_b32 m0, s36
	s_nop 0
	global_load_lds_dwordx4 v[220:221], off
	s_waitcnt lgkmcnt(8)
	s_barrier
	s_waitcnt lgkmcnt(0)
	s_waitcnt lgkmcnt(0)
	v_mfma_f32_16x16x32_bf16 v[124:127], v[128:131], v[144:147], v[124:127]
	v_mfma_f32_16x16x32_bf16 v[120:123], v[136:139], v[144:147], v[120:123]
	v_mfma_f32_16x16x32_bf16 v[116:119], v[128:131], v[170:173], v[116:119]
	v_mfma_f32_16x16x32_bf16 v[112:115], v[136:139], v[170:173], v[112:115]
	v_mfma_f32_16x16x32_bf16 v[100:103], v[128:131], v[204:207], v[100:103]
	v_mfma_f32_16x16x32_bf16 v[96:99], v[136:139], v[204:207], v[96:99]
	v_mfma_f32_16x16x32_bf16 v[84:87], v[128:131], v[212:215], v[84:87]
	v_mfma_f32_16x16x32_bf16 v[80:83], v[136:139], v[212:215], v[80:83]
	v_mfma_f32_16x16x32_bf16 v[124:127], v[132:135], v[166:169], v[124:127]
	v_mfma_f32_16x16x32_bf16 v[120:123], v[140:143], v[166:169], v[120:123]
	v_mfma_f32_16x16x32_bf16 v[116:119], v[132:135], v[174:177], v[116:119]
	v_mfma_f32_16x16x32_bf16 v[112:115], v[140:143], v[174:177], v[112:115]
	v_mfma_f32_16x16x32_bf16 v[100:103], v[132:135], v[208:211], v[100:103]
	v_mfma_f32_16x16x32_bf16 v[96:99], v[140:143], v[208:211], v[96:99]
	v_mfma_f32_16x16x32_bf16 v[84:87], v[132:135], v[216:219], v[84:87]
	v_mfma_f32_16x16x32_bf16 v[80:83], v[140:143], v[216:219], v[80:83]
	s_barrier
	s_add_i32 s24, 0, 0x1c000
	s_add_i32 s16, s48, s31
	v_add_u32_e32 v232, s24, v201
	v_lshl_add_u64 v[188:189], v[188:189], 0, s[18:19]
	s_mov_b32 m0, s16
	ds_read_b128 v[220:223], v232
	ds_read_b128 v[224:227], v232 offset:1024
	ds_read_b128 v[228:231], v232 offset:2048
	ds_read_b128 v[232:235], v232 offset:3072
	global_load_lds_dwordx4 v[188:189], off
	v_lshl_add_u64 v[188:189], v[190:191], 0, s[18:19]
	s_add_i32 m0, s16, 0x2000
	s_nop 0
	global_load_lds_dwordx4 v[188:189], off
	s_barrier
	s_waitcnt lgkmcnt(0)
	s_waitcnt lgkmcnt(0)
	v_mfma_f32_16x16x32_bf16 v[108:111], v[220:223], v[144:147], v[108:111]
	v_mfma_f32_16x16x32_bf16 v[104:107], v[228:231], v[144:147], v[104:107]
	v_mfma_f32_16x16x32_bf16 v[92:95], v[220:223], v[170:173], v[92:95]
	v_mfma_f32_16x16x32_bf16 v[88:91], v[228:231], v[170:173], v[88:91]
	v_mfma_f32_16x16x32_bf16 v[76:79], v[220:223], v[204:207], v[76:79]
	v_mfma_f32_16x16x32_bf16 v[72:75], v[228:231], v[204:207], v[72:75]
	v_mfma_f32_16x16x32_bf16 v[68:71], v[220:223], v[212:215], v[68:71]
	v_mfma_f32_16x16x32_bf16 v[64:67], v[228:231], v[212:215], v[64:67]
	v_mfma_f32_16x16x32_bf16 v[108:111], v[224:227], v[166:169], v[108:111]
	v_mfma_f32_16x16x32_bf16 v[104:107], v[232:235], v[166:169], v[104:107]
	v_mfma_f32_16x16x32_bf16 v[92:95], v[224:227], v[174:177], v[92:95]
	v_mfma_f32_16x16x32_bf16 v[88:91], v[232:235], v[174:177], v[88:91]
	v_mfma_f32_16x16x32_bf16 v[76:79], v[224:227], v[208:211], v[76:79]
	v_mfma_f32_16x16x32_bf16 v[72:75], v[232:235], v[208:211], v[72:75]
	v_mfma_f32_16x16x32_bf16 v[68:71], v[224:227], v[216:219], v[68:71]
	v_mfma_f32_16x16x32_bf16 v[64:67], v[232:235], v[216:219], v[64:67]
	s_mov_b32 m0, s39
	v_lshl_add_u64 v[188:189], v[236:237], 0, s[18:19]
	s_barrier
	ds_read_b128 v[144:147], v203 offset:49152
	ds_read_b128 v[166:169], v203 offset:50176
	ds_read_b128 v[170:173], v203 offset:51200
	ds_read_b128 v[174:177], v203 offset:52224
	ds_read_b128 v[204:207], v203 offset:53248
	ds_read_b128 v[208:211], v203 offset:54272
	ds_read_b128 v[212:215], v203 offset:55296
	ds_read_b128 v[216:219], v203 offset:56320
	global_load_lds_dwordx4 v[188:189], off
	v_lshl_add_u64 v[188:189], v[238:239], 0, s[18:19]
	s_mov_b32 m0, s40
	s_nop 0
	global_load_lds_dwordx4 v[188:189], off
	s_barrier
; #define PG8_STAGE(bufoff, gbase, voff) do { _Pragma("unroll") for (int _i = 0; _i < 2; ++_i) \
;         __builtin_amdgcn_global_load_lds((const unsigned*)((const char*)(gbase) + (voff)[_i]), (LAS unsigned*)(lds + (bufoff) + ldsw + _i * 8192), 16, 0, 0); } while (0)
; #define PG8_MMA(ai, bj, At, Bt) do { __builtin_amdgcn_s_setprio(1); _Pragma("unroll") for (int m = 0; m < 4; ++m) _Pragma("unroll") for (int n = 0; n < 2; ++n) _Pragma("unroll") for (int k = 0; k < 2; ++k) \
;         acc[ai][bj][m][n] = __builtin_amdgcn_mfma_f32_16x16x32_bf16(Bt[n][k], At[m][k], acc[ai][bj][m][n], 0, 0, 0); __builtin_amdgcn_s_setprio(0); } while (0)
; #define PG8_WAIT_V(n) asm volatile("s_waitcnt vmcnt(" #n ")" ::: "memory")
; #define PG8_BAR __builtin_amdgcn_s_barrier()
;     __device__ __forceinline__ void operator()(const f32x4 (&acc)[2][2][4][2], const Unit& u, int wr, int wc, int fr, int fq) const {
;     ...
;         const float* base = (u.pm < 32) ? base_lo : base_hi;
; #pragma unroll
;         for (int ai = 0; ai < 2; ++ai) {
;             f32x4 bs[4][2][2];
; #pragma unroll
;             for (int m = 0; m < 4; ++m) { const size_t off = (size_t)(row0 + ai * HALF + m * 16) * DM + col0;
; #pragma unroll
;                 for (int bj = 0; bj < 2; ++bj)
; #pragma unroll
;                     for (int n = 0; n < 2; ++n) bs[m][bj][n] = *(const f32x4*)(base + off + bj * HALF + n * 16); }
; template <class Epi, class Sched>
; __device__ __forceinline__ void gemm_phase(LAS unsigned char* lds, const Gemm g, const Sched& S, const Epi& E) {
;     ...
;             PG8_STAGE(PG8_SB(1, 1), b3 + hstep, voffB);
;             PG8_WAIT_V(6); PG8_BAR; PG8_MMA(1, 1, At, B1); PG8_BAR;
;         }
;         E(acc, cur, wr, wc, fr, fq);
;         if (!has_next) break;
	s_waitcnt lgkmcnt(0)
	s_waitcnt lgkmcnt(0)
	v_mfma_f32_16x16x32_bf16 v[60:63], v[128:131], v[144:147], v[60:63]
	v_mfma_f32_16x16x32_bf16 v[56:59], v[136:139], v[144:147], v[56:59]
	v_mfma_f32_16x16x32_bf16 v[52:55], v[128:131], v[170:173], v[52:55]
	v_mfma_f32_16x16x32_bf16 v[48:51], v[136:139], v[170:173], v[48:51]
	v_mfma_f32_16x16x32_bf16 v[36:39], v[128:131], v[204:207], v[36:39]
	v_mfma_f32_16x16x32_bf16 v[32:35], v[136:139], v[204:207], v[32:35]
	v_mfma_f32_16x16x32_bf16 v[20:23], v[128:131], v[212:215], v[20:23]
	v_mfma_f32_16x16x32_bf16 v[16:19], v[136:139], v[212:215], v[16:19]
	v_mfma_f32_16x16x32_bf16 v[60:63], v[132:135], v[166:169], v[60:63]
	v_mfma_f32_16x16x32_bf16 v[56:59], v[140:143], v[166:169], v[56:59]
	v_mfma_f32_16x16x32_bf16 v[52:55], v[132:135], v[174:177], v[52:55]
	v_mfma_f32_16x16x32_bf16 v[48:51], v[140:143], v[174:177], v[48:51]
	v_mfma_f32_16x16x32_bf16 v[36:39], v[132:135], v[208:211], v[36:39]
	v_mfma_f32_16x16x32_bf16 v[32:35], v[140:143], v[208:211], v[32:35]
	v_mfma_f32_16x16x32_bf16 v[20:23], v[132:135], v[216:219], v[20:23]
	v_mfma_f32_16x16x32_bf16 v[16:19], v[140:143], v[216:219], v[16:19]
	s_barrier
	s_add_u32 s16, s22, 0x80080
	s_addc_u32 s17, s23, 0
	s_add_i32 s22, s24, s31
	v_lshl_add_u64 v[128:129], s[16:17], 0, v[148:149]
	s_mov_b32 m0, s22
	s_nop 0
	global_load_lds_dwordx4 v[128:129], off
	v_lshl_add_u64 v[128:129], s[16:17], 0, v[160:161]
	s_add_i32 m0, s22, 0x2000
	s_nop 0
	global_load_lds_dwordx4 v[128:129], off
	s_waitcnt vmcnt(6)
	s_barrier
	v_mfma_f32_16x16x32_bf16 v[44:47], v[220:223], v[144:147], v[44:47]
	v_mfma_f32_16x16x32_bf16 v[40:43], v[228:231], v[144:147], v[40:43]
	v_mfma_f32_16x16x32_bf16 v[28:31], v[220:223], v[170:173], v[28:31]
	v_mfma_f32_16x16x32_bf16 v[24:27], v[228:231], v[170:173], v[24:27]
	v_mfma_f32_16x16x32_bf16 v[12:15], v[220:223], v[204:207], v[12:15]
	v_mfma_f32_16x16x32_bf16 v[8:11], v[228:231], v[204:207], v[8:11]
	v_mfma_f32_16x16x32_bf16 v[4:7], v[220:223], v[212:215], v[4:7]
	v_mfma_f32_16x16x32_bf16 v[0:3], v[228:231], v[212:215], v[0:3]
	v_mfma_f32_16x16x32_bf16 v[44:47], v[224:227], v[166:169], v[44:47]
	v_mfma_f32_16x16x32_bf16 v[40:43], v[232:235], v[166:169], v[40:43]
	v_mfma_f32_16x16x32_bf16 v[28:31], v[224:227], v[174:177], v[28:31]
	v_mfma_f32_16x16x32_bf16 v[24:27], v[232:235], v[174:177], v[24:27]
	v_mfma_f32_16x16x32_bf16 v[12:15], v[224:227], v[208:211], v[12:15]
	v_mfma_f32_16x16x32_bf16 v[8:11], v[232:235], v[208:211], v[8:11]
	v_mfma_f32_16x16x32_bf16 v[4:7], v[224:227], v[216:219], v[4:7]
	v_mfma_f32_16x16x32_bf16 v[0:3], v[232:235], v[216:219], v[0:3]
	s_add_u32 s13, s13, 0x100
	s_addc_u32 s15, s15, 0
	s_cmp_ge_i32 s47, s45
	s_mov_b64 s[16:17], s[20:21]
	s_mov_b32 s22, s47
	s_barrier
	s_cbranch_scc0 .LBB0_267
	v_lshl_add_u32 v166, s46, 8, v200
	v_lshl_or_b32 v168, s44, 8, v202
	s_mov_b64 s[16:17], -1
	s_cmp_lt_i32 s82, 0
	v_ashrrev_i32_e32 v169, 31, v168
	v_ashrrev_i32_e32 v167, 31, v166
	s_cbranch_scc0 .LBB0_270
	v_lshlrev_b64 v[170:171], 2, v[168:169]
	v_lshl_add_u64 v[172:173], s[60:61], 0, v[170:171]
	v_lshlrev_b64 v[174:175], 13, v[166:167]
	v_lshl_add_u64 v[128:129], v[172:173], 0, v[174:175]
	global_load_dwordx4 v[204:207], v[128:129], off
	global_load_dwordx4 v[208:211], v[128:129], off offset:64
	global_load_dwordx4 v[212:215], v[128:129], off offset:512
	global_load_dwordx4 v[216:219], v[128:129], off offset:576
	v_or_b32_e32 v128, 16, v166
	v_ashrrev_i32_e32 v129, 31, v128
	v_lshlrev_b64 v[188:189], 13, v[128:129]
	v_lshl_add_u64 v[128:129], v[172:173], 0, v[188:189]
	global_load_dwordx4 v[220:223], v[128:129], off
	global_load_dwordx4 v[224:227], v[128:129], off offset:64
	global_load_dwordx4 v[228:231], v[128:129], off offset:512
	global_load_dwordx4 v[232:235], v[128:129], off offset:576
	v_or_b32_e32 v128, 32, v166
	v_ashrrev_i32_e32 v129, 31, v128
	v_lshlrev_b64 v[190:191], 13, v[128:129]
	v_lshl_add_u64 v[128:129], v[172:173], 0, v[190:191]
	global_load_dwordx4 v[236:239], v[128:129], off
	global_load_dwordx4 v[240:243], v[128:129], off offset:64
	global_load_dwordx4 v[144:147], v[128:129], off offset:512
	global_load_dwordx4 v[140:143], v[128:129], off offset:576
	v_or_b32_e32 v128, 48, v166
	v_ashrrev_i32_e32 v129, 31, v128
	v_lshlrev_b64 v[176:177], 13, v[128:129]
	v_lshl_add_u64 v[128:129], v[172:173], 0, v[176:177]
	global_load_dwordx4 v[244:247], v[128:129], off
	global_load_dwordx4 v[136:139], v[128:129], off offset:64
	global_load_dwordx4 v[132:135], v[128:129], off offset:512
	s_nop 0
	global_load_dwordx4 v[128:131], v[128:129], off offset:576
	v_lshl_add_u64 v[248:249], s[60:61], 0, v[174:175]
	v_lshl_add_u64 v[248:249], v[248:249], 0, v[170:171]
	v_lshl_add_u64 v[188:189], s[60:61], 0, v[188:189]
	v_lshl_add_u64 v[188:189], v[188:189], 0, v[170:171]
	s_mov_b64 s[16:17], 0x100000
	s_waitcnt vmcnt(0)
;     __device__ __forceinline__ void operator()(const f32x4 (&acc)[2][2][4][2], const Unit& u, int wr, int wc, int fr, int fq) const {
;     ...
;             for (int m = 0; m < 4; ++m) { const size_t off = (size_t)(row0 + ai * HALF + m * 16) * DM + col0;
; #pragma unroll
;                 for (int bj = 0; bj < 2; ++bj)
; #pragma unroll
;                     for (int n = 0; n < 2; ++n) bs[m][bj][n] = *(const f32x4*)(base + off + bj * HALF + n * 16); }
; #pragma unroll
;             for (int m = 0; m < 4; ++m) { const size_t off = (size_t)(row0 + ai * HALF + m * 16) * DM + col0;
; #pragma unroll
;                 for (int bj = 0; bj < 2; ++bj)
; #pragma unroll
;                     for (int n = 0; n < 2; ++n) *(f32x4*)(out + off + bj * HALF + n * 16) = bs[m][bj][n] + scale * acc[ai][bj][m][n]; }
;             asm volatile("" ::: "memory");
	v_pk_add_f32 v[206:207], v[206:207], v[126:127]
	v_pk_add_f32 v[204:205], v[204:205], v[124:125]
	global_store_dwordx4 v[248:249], v[204:207], off
	v_pk_add_f32 v[146:147], v[146:147], v[78:79]
	s_nop 0
	v_pk_add_f32 v[206:207], v[210:211], v[122:123]
	v_pk_add_f32 v[204:205], v[208:209], v[120:121]
	global_store_dwordx4 v[248:249], v[204:207], off offset:64
	v_pk_add_f32 v[144:145], v[144:145], v[76:77]
	v_pk_add_f32 v[142:143], v[142:143], v[74:75]
	v_pk_add_f32 v[206:207], v[214:215], v[110:111]
	v_pk_add_f32 v[204:205], v[212:213], v[108:109]
	global_store_dwordx4 v[248:249], v[204:207], off offset:512
	v_pk_add_f32 v[140:141], v[140:141], v[72:73]
	v_pk_add_f32 v[138:139], v[138:139], v[82:83]
	v_pk_add_f32 v[206:207], v[218:219], v[106:107]
	v_pk_add_f32 v[204:205], v[216:217], v[104:105]
	global_store_dwordx4 v[248:249], v[204:207], off offset:576
	v_pk_add_f32 v[136:137], v[136:137], v[80:81]
	v_pk_add_f32 v[134:135], v[134:135], v[70:71]
	v_pk_add_f32 v[206:207], v[222:223], v[118:119]
	v_pk_add_f32 v[204:205], v[220:221], v[116:117]
	global_store_dwordx4 v[188:189], v[204:207], off
	v_pk_add_f32 v[132:133], v[132:133], v[68:69]
	v_pk_add_f32 v[130:131], v[130:131], v[66:67]
	v_pk_add_f32 v[206:207], v[226:227], v[114:115]
	v_pk_add_f32 v[204:205], v[224:225], v[112:113]
	global_store_dwordx4 v[188:189], v[204:207], off offset:64
	v_pk_add_f32 v[128:129], v[128:129], v[64:65]
	s_nop 0
	v_pk_add_f32 v[206:207], v[230:231], v[94:95]
	v_pk_add_f32 v[204:205], v[228:229], v[92:93]
	global_store_dwordx4 v[188:189], v[204:207], off offset:512
	s_nop 1
	v_pk_add_f32 v[206:207], v[234:235], v[90:91]
	v_pk_add_f32 v[204:205], v[232:233], v[88:89]
	global_store_dwordx4 v[188:189], v[204:207], off offset:576
	v_lshl_add_u64 v[188:189], s[60:61], 0, v[190:191]
	v_lshl_add_u64 v[188:189], v[188:189], 0, v[170:171]
	v_pk_add_f32 v[206:207], v[238:239], v[102:103]
	v_pk_add_f32 v[204:205], v[236:237], v[100:101]
	global_store_dwordx4 v[188:189], v[144:147], off offset:512
	global_store_dwordx4 v[188:189], v[204:207], off
	global_store_dwordx4 v[188:189], v[140:143], off offset:576
	v_lshl_add_u64 v[144:145], s[60:61], 0, v[176:177]
	v_pk_add_f32 v[206:207], v[242:243], v[98:99]
	v_pk_add_f32 v[204:205], v[240:241], v[96:97]
	v_pk_add_f32 v[142:143], v[246:247], v[86:87]
	v_pk_add_f32 v[140:141], v[244:245], v[84:85]
	v_lshl_add_u64 v[144:145], v[144:145], 0, v[170:171]
	global_store_dwordx4 v[188:189], v[204:207], off offset:64
	global_store_dwordx4 v[144:145], v[140:143], off
	global_store_dwordx4 v[144:145], v[136:139], off offset:64
	global_store_dwordx4 v[144:145], v[132:135], off offset:512
	global_store_dwordx4 v[144:145], v[128:131], off offset:576
	v_lshl_add_u64 v[146:147], v[174:175], 0, s[16:17]
	s_mov_b64 s[16:17], 0x120000
	v_lshl_add_u64 v[128:129], v[172:173], 0, v[146:147]
	global_load_dwordx4 v[142:145], v[128:129], off
	global_load_dwordx4 v[204:207], v[128:129], off offset:64
	global_load_dwordx4 v[208:211], v[128:129], off offset:512
	global_load_dwordx4 v[212:215], v[128:129], off offset:576
	v_lshl_add_u64 v[176:177], v[174:175], 0, s[16:17]
	v_lshl_add_u64 v[128:129], v[172:173], 0, v[176:177]
	global_load_dwordx4 v[216:219], v[128:129], off
	global_load_dwordx4 v[220:223], v[128:129], off offset:64
	global_load_dwordx4 v[224:227], v[128:129], off offset:512
	global_load_dwordx4 v[228:231], v[128:129], off offset:576
	s_mov_b64 s[16:17], 0x140000
	v_lshl_add_u64 v[188:189], v[174:175], 0, s[16:17]
	s_mov_b64 s[16:17], 0x160000
	v_lshl_add_u64 v[128:129], v[172:173], 0, v[188:189]
	v_lshl_add_u64 v[140:141], v[174:175], 0, s[16:17]
	global_load_dwordx4 v[232:235], v[128:129], off
	global_load_dwordx4 v[236:239], v[128:129], off offset:64
	global_load_dwordx4 v[240:243], v[128:129], off offset:512
	global_load_dwordx4 v[244:247], v[128:129], off offset:576
	v_lshl_add_u64 v[128:129], v[172:173], 0, v[140:141]
	global_load_dwordx4 v[172:175], v[128:129], off
	global_load_dwordx4 v[136:139], v[128:129], off offset:64
	global_load_dwordx4 v[132:135], v[128:129], off offset:512
	s_nop 0
	global_load_dwordx4 v[128:131], v[128:129], off offset:576
	v_lshl_add_u64 v[146:147], s[60:61], 0, v[146:147]
	v_lshl_add_u64 v[146:147], v[146:147], 0, v[170:171]
	v_lshl_add_u64 v[140:141], s[60:61], 0, v[140:141]
	v_lshl_add_u64 v[140:141], v[140:141], 0, v[170:171]
	s_mov_b64 s[16:17], 0
	s_waitcnt vmcnt(0)
;     __device__ __forceinline__ void operator()(const f32x4 (&acc)[2][2][4][2], const Unit& u, int wr, int wc, int fr, int fq) const {
;     ...
;             for (int m = 0; m < 4; ++m) { const size_t off = (size_t)(row0 + ai * HALF + m * 16) * DM + col0;
; #pragma unroll
;                 for (int bj = 0; bj < 2; ++bj)
; #pragma unroll
;                     for (int n = 0; n < 2; ++n) *(f32x4*)(out + off + bj * HALF + n * 16) = bs[m][bj][n] + scale * acc[ai][bj][m][n]; }
	v_pk_add_f32 v[144:145], v[62:63], v[144:145]
	v_pk_add_f32 v[142:143], v[60:61], v[142:143]
	global_store_dwordx4 v[146:147], v[142:145], off
	v_pk_add_f32 v[138:139], v[18:19], v[138:139]
	s_nop 0
	v_pk_add_f32 v[144:145], v[58:59], v[206:207]
	v_pk_add_f32 v[142:143], v[56:57], v[204:205]
	global_store_dwordx4 v[146:147], v[142:145], off offset:64
	v_pk_add_f32 v[136:137], v[16:17], v[136:137]
	v_pk_add_f32 v[134:135], v[6:7], v[134:135]
	v_pk_add_f32 v[144:145], v[46:47], v[210:211]
	v_pk_add_f32 v[142:143], v[44:45], v[208:209]
	global_store_dwordx4 v[146:147], v[142:145], off offset:512
	v_pk_add_f32 v[132:133], v[4:5], v[132:133]
	v_pk_add_f32 v[130:131], v[2:3], v[130:131]
	v_pk_add_f32 v[144:145], v[42:43], v[214:215]
	v_pk_add_f32 v[142:143], v[40:41], v[212:213]
	global_store_dwordx4 v[146:147], v[142:145], off offset:576
	v_lshl_add_u64 v[146:147], s[60:61], 0, v[176:177]
	v_lshl_add_u64 v[146:147], v[146:147], 0, v[170:171]
	v_pk_add_f32 v[144:145], v[54:55], v[218:219]
	v_pk_add_f32 v[142:143], v[52:53], v[216:217]
	global_store_dwordx4 v[146:147], v[142:145], off
	v_pk_add_f32 v[128:129], v[0:1], v[128:129]
	global_store_dwordx4 v[140:141], v[136:139], off offset:64
	v_pk_add_f32 v[144:145], v[50:51], v[222:223]
	v_pk_add_f32 v[142:143], v[48:49], v[220:221]
	global_store_dwordx4 v[146:147], v[142:145], off offset:64
	global_store_dwordx4 v[140:141], v[132:135], off offset:512
	global_store_dwordx4 v[140:141], v[128:131], off offset:576
	v_pk_add_f32 v[144:145], v[30:31], v[226:227]
	v_pk_add_f32 v[142:143], v[28:29], v[224:225]
	global_store_dwordx4 v[146:147], v[142:145], off offset:512
	s_nop 1
	v_pk_add_f32 v[144:145], v[26:27], v[230:231]
	v_pk_add_f32 v[142:143], v[24:25], v[228:229]
	global_store_dwordx4 v[146:147], v[142:145], off offset:576
	v_lshl_add_u64 v[146:147], s[60:61], 0, v[188:189]
	v_lshl_add_u64 v[146:147], v[146:147], 0, v[170:171]
	v_pk_add_f32 v[144:145], v[38:39], v[234:235]
	v_pk_add_f32 v[142:143], v[36:37], v[232:233]
	global_store_dwordx4 v[146:147], v[142:145], off
	s_nop 1
	v_pk_add_f32 v[144:145], v[34:35], v[238:239]
	v_pk_add_f32 v[142:143], v[32:33], v[236:237]
	global_store_dwordx4 v[146:147], v[142:145], off offset:64
	s_nop 1
	v_pk_add_f32 v[144:145], v[14:15], v[242:243]
	v_pk_add_f32 v[142:143], v[12:13], v[240:241]
	global_store_dwordx4 v[146:147], v[142:145], off offset:512
	s_nop 1
	v_pk_add_f32 v[144:145], v[10:11], v[246:247]
	v_pk_add_f32 v[142:143], v[8:9], v[244:245]
	global_store_dwordx4 v[146:147], v[142:145], off offset:576
	s_nop 1
	v_pk_add_f32 v[144:145], v[22:23], v[174:175]
	v_pk_add_f32 v[142:143], v[20:21], v[172:173]
	global_store_dwordx4 v[140:141], v[142:145], off
